# pass 2: skip-term FMA and GELU polynomial as packed f32 ops (same operation order); on top of v52
# baseline (speedup 1.0000x reference)
.LBB0_1063:
	v_lshl_add_u64 v[2:3], s[58:59], 0, v[2:3]
	v_lshl_add_u64 v[4:5], s[58:59], 0, v[4:5]
	global_load_dwordx4 v[94:97], v[2:3], off
	global_load_dwordx4 v[90:93], v[4:5], off
	v_lshl_add_u64 v[2:3], s[58:59], 0, v[6:7]
	v_lshl_add_u64 v[4:5], s[58:59], 0, v[8:9]
	global_load_dwordx4 v[86:89], v[2:3], off
	global_load_dwordx4 v[82:85], v[4:5], off
	s_lshl_b32 s0, s2, 4
	s_lshl_b32 s1, s0, 2
	v_readlane_b32 s4, v252, 48
	v_readlane_b32 s5, v252, 49
	v_lshrrev_b32_e32 v1, 4, v148
	s_add_u32 s4, s4, s1
	s_addc_u32 s5, s5, 0
	v_lshlrev_b32_e32 v178, 4, v1
	v_and_b32_e32 v176, 15, v148
	v_lshlrev_b32_e32 v176, 10, v176
	global_load_dwordx4 v[98:101], v178, s[4:5]
	v_lshl_or_b32 v176, v1, 3, v176
	v_add_u32_e32 v177, 0x4000, v176
	s_lshl_b64 s[8:9], s[56:57], 10
	s_add_u32 s6, s66, s8
	s_addc_u32 s7, s67, s9
	s_lshl_b32 s1, s0, 1
	s_add_u32 s10, s74, s1
	s_addc_u32 s11, s75, 0
	s_add_u32 s10, s10, s8
	s_addc_u32 s11, s11, s9
	v_and_b32_e32 v1, 31, v148
	v_mul_u32_u24_e32 v174, 0x1100, v149
	v_lshlrev_b32_e32 v1, 2, v1
	v_add3_u32 v174, s3, v174, v1
	v_and_b32_e32 v1, 15, v148
	v_mul_u32_u24_e32 v175, 0x110, v1
	v_add3_u32 v175, s3, v175, v178
	v_cmp_lt_u32_e32 vcc, 31, v148
	s_waitcnt vmcnt(12)
	v_mfma_f32_32x32x16_bf16 v[50:65], v[18:21], v[114:117], 0
	v_mfma_f32_32x32x16_bf16 v[2:17], v[18:21], v[110:113], 0
	v_mfma_f32_32x32x16_bf16 v[34:49], v[18:21], v[106:109], 0
	v_mfma_f32_32x32x16_bf16 v[18:33], v[18:21], v[102:105], 0
	global_load_dwordx2 v[160:161], v176, s[6:7]
	global_load_dwordx2 v[162:163], v177, s[6:7]
	v_mov_b32_e32 v1, v79
	v_mov_b32_e32 v79, v80
	v_mov_b32_e32 v80, v1
	v_mov_b32_e32 v1, v71
	v_mov_b32_e32 v71, v72
	v_mov_b32_e32 v72, v1
	v_mov_b32_e32 v1, v75
	v_mov_b32_e32 v75, v76
	v_mov_b32_e32 v76, v1
	v_mov_b32_e32 v1, v67
	v_mov_b32_e32 v67, v68
	v_mov_b32_e32 v68, v1
	v_mul_f32_e32 v156, v71, v71
	v_mul_f32_e32 v157, v71, v73
	v_fma_f32 v156, -v73, v73, v156
	v_add_f32_e32 v157, v157, v157
	v_mul_f32_e32 v152, v156, v156
	v_mul_f32_e32 v153, v156, v157
	v_fma_f32 v152, -v157, v157, v152
	v_add_f32_e32 v153, v153, v153
	v_mul_f32_e32 v156, v67, v67
	v_mul_f32_e32 v157, v67, v69
	v_fma_f32 v156, -v69, v69, v156
	v_add_f32_e32 v157, v157, v157
	v_mul_f32_e32 v154, v156, v156
	v_mul_f32_e32 v155, v156, v157
	v_fma_f32 v154, -v157, v157, v154
	v_add_f32_e32 v155, v155, v155
	v_fmac_f32_e32 v51, v78, v50
	v_fmac_f32_e32 v35, v74, v34
	v_fmac_f32_e32 v3, v80, v50
	v_fmac_f32_e32 v19, v76, v34
	v_fma_f32 v51, -v80, v2, v51
	v_fma_f32 v35, -v76, v18, v35
	v_fmac_f32_e32 v3, v78, v2
	v_fmac_f32_e32 v19, v74, v18
	v_fmac_f32_e32 v52, v78, v51
	v_fmac_f32_e32 v36, v74, v35
	v_fmac_f32_e32 v4, v80, v51
	v_fmac_f32_e32 v20, v76, v35
	v_fma_f32 v52, -v80, v3, v52
	v_fma_f32 v36, -v76, v19, v36
	v_fmac_f32_e32 v4, v78, v3
	v_fmac_f32_e32 v20, v74, v19
	v_fmac_f32_e32 v53, v78, v52
	v_fmac_f32_e32 v37, v74, v36
	v_fmac_f32_e32 v5, v80, v52
	v_fmac_f32_e32 v21, v76, v36
	v_fma_f32 v53, -v80, v4, v53
	v_fma_f32 v37, -v76, v20, v37
	v_fmac_f32_e32 v5, v78, v4
	v_fmac_f32_e32 v21, v74, v20
	v_fmac_f32_e32 v54, v78, v53
	v_fmac_f32_e32 v38, v74, v37
	v_fmac_f32_e32 v6, v80, v53
	v_fmac_f32_e32 v22, v76, v37
	v_fma_f32 v54, -v80, v5, v54
	v_fma_f32 v38, -v76, v21, v38
	v_fmac_f32_e32 v6, v78, v5
	v_fmac_f32_e32 v22, v74, v21
	v_fmac_f32_e32 v55, v78, v54
	v_fmac_f32_e32 v39, v74, v38
	v_fmac_f32_e32 v7, v80, v54
	v_fmac_f32_e32 v23, v76, v38
	v_fma_f32 v55, -v80, v6, v55
	v_fma_f32 v39, -v76, v22, v39
	v_fmac_f32_e32 v7, v78, v6
	v_fmac_f32_e32 v23, v74, v22
	v_fmac_f32_e32 v56, v78, v55
	v_fmac_f32_e32 v40, v74, v39
	v_fmac_f32_e32 v8, v80, v55
	v_fmac_f32_e32 v24, v76, v39
	v_fma_f32 v56, -v80, v7, v56
	v_fma_f32 v40, -v76, v23, v40
	v_fmac_f32_e32 v8, v78, v7
	v_fmac_f32_e32 v24, v74, v23
	v_fmac_f32_e32 v57, v78, v56
	v_fmac_f32_e32 v41, v74, v40
	v_fmac_f32_e32 v9, v80, v56
	v_fmac_f32_e32 v25, v76, v40
	v_fma_f32 v57, -v80, v8, v57
	v_fma_f32 v41, -v76, v24, v41
	v_fmac_f32_e32 v9, v78, v8
	v_fmac_f32_e32 v25, v74, v24
	v_fmac_f32_e32 v58, v78, v57
	v_fmac_f32_e32 v42, v74, v41
	v_fmac_f32_e32 v10, v80, v57
	v_fmac_f32_e32 v26, v76, v41
	v_fma_f32 v58, -v80, v9, v58
	v_fma_f32 v42, -v76, v25, v42
	v_fmac_f32_e32 v10, v78, v9
	v_fmac_f32_e32 v26, v74, v25
	v_fmac_f32_e32 v59, v78, v58
	v_fmac_f32_e32 v43, v74, v42
	v_fmac_f32_e32 v11, v80, v58
	v_fmac_f32_e32 v27, v76, v42
	v_fma_f32 v59, -v80, v10, v59
	v_fma_f32 v43, -v76, v26, v43
	v_fmac_f32_e32 v11, v78, v10
	v_fmac_f32_e32 v27, v74, v26
	v_fmac_f32_e32 v60, v78, v59
	v_fmac_f32_e32 v44, v74, v43
	v_fmac_f32_e32 v12, v80, v59
	v_fmac_f32_e32 v28, v76, v43
	v_fma_f32 v60, -v80, v11, v60
	v_fma_f32 v44, -v76, v27, v44
	v_fmac_f32_e32 v12, v78, v11
	v_fmac_f32_e32 v28, v74, v27
	v_fmac_f32_e32 v61, v78, v60
	v_fmac_f32_e32 v45, v74, v44
	v_fmac_f32_e32 v13, v80, v60
	v_fmac_f32_e32 v29, v76, v44
	v_fma_f32 v61, -v80, v12, v61
	v_fma_f32 v45, -v76, v28, v45
	v_fmac_f32_e32 v13, v78, v12
	v_fmac_f32_e32 v29, v74, v28
	v_fmac_f32_e32 v62, v78, v61
	v_fmac_f32_e32 v46, v74, v45
	v_fmac_f32_e32 v14, v80, v61
	v_fmac_f32_e32 v30, v76, v45
	v_fma_f32 v62, -v80, v13, v62
	v_fma_f32 v46, -v76, v29, v46
	v_fmac_f32_e32 v14, v78, v13
	v_fmac_f32_e32 v30, v74, v29
	v_fmac_f32_e32 v63, v78, v62
	v_fmac_f32_e32 v47, v74, v46
	v_fmac_f32_e32 v15, v80, v62
	v_fmac_f32_e32 v31, v76, v46
	v_fma_f32 v63, -v80, v14, v63
	v_fma_f32 v47, -v76, v30, v47
	v_fmac_f32_e32 v15, v78, v14
	v_fmac_f32_e32 v31, v74, v30
	v_fmac_f32_e32 v64, v78, v63
	v_fmac_f32_e32 v48, v74, v47
	v_fmac_f32_e32 v16, v80, v63
	v_fmac_f32_e32 v32, v76, v47
	v_fma_f32 v64, -v80, v15, v64
	v_fma_f32 v48, -v76, v31, v48
	v_fmac_f32_e32 v16, v78, v15
	v_fmac_f32_e32 v32, v74, v31
	v_fmac_f32_e32 v65, v78, v64
	v_fmac_f32_e32 v49, v74, v48
	v_fmac_f32_e32 v17, v80, v64
	v_fmac_f32_e32 v33, v76, v48
	v_fma_f32 v65, -v80, v16, v65
	v_fma_f32 v49, -v76, v32, v49
	v_fmac_f32_e32 v17, v78, v16
	v_fmac_f32_e32 v33, v74, v32
	v_mov_b32_e32 v156, v65
	v_mov_b32_e32 v157, v17
	v_mov_b32_e32 v158, v65
	v_mov_b32_e32 v159, v17
	s_nop 1
	v_permlane32_swap_b32_e32 v156, v158
	v_permlane32_swap_b32_e32 v157, v159
	v_pk_fma_f32 v[164:165], v[166:167], v[152:153], v[156:157] op_sel_hi:[1,0,1]
	v_pk_fma_f32 v[164:165], v[166:167], v[152:153], v[164:165] op_sel:[1,1,0] op_sel_hi:[0,1,1] neg_lo:[0,1,0]
	v_cndmask_b32_e32 v164, v166, v164, vcc
	v_cndmask_b32_e32 v165, v167, v165, vcc
	v_mov_b32_e32 v156, v49
	v_mov_b32_e32 v157, v33
	v_mov_b32_e32 v158, v49
	v_mov_b32_e32 v159, v33
	s_nop 1
	v_permlane32_swap_b32_e32 v156, v158
	v_permlane32_swap_b32_e32 v157, v159
	v_pk_fma_f32 v[170:171], v[150:151], v[154:155], v[156:157] op_sel_hi:[1,0,1]
	v_pk_fma_f32 v[170:171], v[150:151], v[154:155], v[170:171] op_sel:[1,1,0] op_sel_hi:[0,1,1] neg_lo:[0,1,0]
	v_cndmask_b32_e32 v170, v150, v170, vcc
	v_cndmask_b32_e32 v171, v151, v171, vcc
	v_pk_mul_f32 v[168:169], v[164:165], v[70:71] op_sel:[0,1] op_sel_hi:[1,1]
	v_pk_mul_f32 v[172:173], v[170:171], v[66:67] op_sel:[0,1] op_sel_hi:[1,1]
	v_pk_fma_f32 v[168:169], v[164:165], v[72:73], v[168:169] op_sel:[1,1,0] op_sel_hi:[0,1,1] neg_lo:[0,1,0]
	v_pk_fma_f32 v[172:173], v[170:171], v[68:69], v[172:173] op_sel:[1,1,0] op_sel_hi:[0,1,1] neg_lo:[0,1,0]
	v_pk_fma_f32 v[50:51], v[78:79], v[164:165], v[50:51] op_sel_hi:[1,0,1]
	v_pk_fma_f32 v[34:35], v[74:75], v[170:171], v[34:35] op_sel_hi:[1,0,1]
	v_pk_fma_f32 v[52:53], v[70:71], v[164:165], v[52:53] op_sel_hi:[1,0,1]
	v_pk_fma_f32 v[36:37], v[66:67], v[170:171], v[36:37] op_sel_hi:[1,0,1]
	v_pk_fma_f32 v[2:3], v[80:81], v[164:165], v[2:3] op_sel_hi:[1,0,1]
	v_pk_fma_f32 v[18:19], v[76:77], v[170:171], v[18:19] op_sel_hi:[1,0,1]
	v_pk_fma_f32 v[4:5], v[72:73], v[164:165], v[4:5] op_sel_hi:[1,0,1]
	v_pk_fma_f32 v[20:21], v[68:69], v[170:171], v[20:21] op_sel_hi:[1,0,1]
	v_pk_fma_f32 v[50:51], v[80:81], v[164:165], v[50:51] op_sel:[0,1,0] op_sel_hi:[1,1,1] neg_lo:[0,1,0] neg_hi:[0,1,0]
	v_pk_fma_f32 v[34:35], v[76:77], v[170:171], v[34:35] op_sel:[0,1,0] op_sel_hi:[1,1,1] neg_lo:[0,1,0] neg_hi:[0,1,0]
	v_pk_fma_f32 v[52:53], v[72:73], v[164:165], v[52:53] op_sel:[0,1,0] op_sel_hi:[1,1,1] neg_lo:[0,1,0] neg_hi:[0,1,0]
	v_pk_fma_f32 v[36:37], v[68:69], v[170:171], v[36:37] op_sel:[0,1,0] op_sel_hi:[1,1,1] neg_lo:[0,1,0] neg_hi:[0,1,0]
	v_pk_fma_f32 v[2:3], v[78:79], v[164:165], v[2:3] op_sel:[0,1,0] op_sel_hi:[1,1,1]
	v_pk_fma_f32 v[18:19], v[74:75], v[170:171], v[18:19] op_sel:[0,1,0] op_sel_hi:[1,1,1]
	v_pk_fma_f32 v[4:5], v[70:71], v[164:165], v[4:5] op_sel:[0,1,0] op_sel_hi:[1,1,1]
	v_pk_fma_f32 v[20:21], v[66:67], v[170:171], v[20:21] op_sel:[0,1,0] op_sel_hi:[1,1,1]
	v_pk_mul_f32 v[164:165], v[168:169], v[70:71] op_sel:[0,1] op_sel_hi:[1,1]
	v_pk_mul_f32 v[170:171], v[172:173], v[66:67] op_sel:[0,1] op_sel_hi:[1,1]
	v_pk_fma_f32 v[164:165], v[168:169], v[72:73], v[164:165] op_sel:[1,1,0] op_sel_hi:[0,1,1] neg_lo:[0,1,0]
	v_pk_fma_f32 v[170:171], v[172:173], v[68:69], v[170:171] op_sel:[1,1,0] op_sel_hi:[0,1,1] neg_lo:[0,1,0]
	v_pk_fma_f32 v[54:55], v[78:79], v[168:169], v[54:55] op_sel_hi:[1,0,1]
	v_pk_fma_f32 v[38:39], v[74:75], v[172:173], v[38:39] op_sel_hi:[1,0,1]
	v_pk_fma_f32 v[56:57], v[70:71], v[168:169], v[56:57] op_sel_hi:[1,0,1]
	v_pk_fma_f32 v[40:41], v[66:67], v[172:173], v[40:41] op_sel_hi:[1,0,1]
	v_pk_fma_f32 v[6:7], v[80:81], v[168:169], v[6:7] op_sel_hi:[1,0,1]
	v_pk_fma_f32 v[22:23], v[76:77], v[172:173], v[22:23] op_sel_hi:[1,0,1]
	v_pk_fma_f32 v[8:9], v[72:73], v[168:169], v[8:9] op_sel_hi:[1,0,1]
	v_pk_fma_f32 v[24:25], v[68:69], v[172:173], v[24:25] op_sel_hi:[1,0,1]
	v_pk_fma_f32 v[54:55], v[80:81], v[168:169], v[54:55] op_sel:[0,1,0] op_sel_hi:[1,1,1] neg_lo:[0,1,0] neg_hi:[0,1,0]
	v_pk_fma_f32 v[38:39], v[76:77], v[172:173], v[38:39] op_sel:[0,1,0] op_sel_hi:[1,1,1] neg_lo:[0,1,0] neg_hi:[0,1,0]
	v_pk_fma_f32 v[56:57], v[72:73], v[168:169], v[56:57] op_sel:[0,1,0] op_sel_hi:[1,1,1] neg_lo:[0,1,0] neg_hi:[0,1,0]
	v_pk_fma_f32 v[40:41], v[68:69], v[172:173], v[40:41] op_sel:[0,1,0] op_sel_hi:[1,1,1] neg_lo:[0,1,0] neg_hi:[0,1,0]
	v_pk_fma_f32 v[6:7], v[78:79], v[168:169], v[6:7] op_sel:[0,1,0] op_sel_hi:[1,1,1]
	v_pk_fma_f32 v[22:23], v[74:75], v[172:173], v[22:23] op_sel:[0,1,0] op_sel_hi:[1,1,1]
	v_pk_fma_f32 v[8:9], v[70:71], v[168:169], v[8:9] op_sel:[0,1,0] op_sel_hi:[1,1,1]
	v_pk_fma_f32 v[24:25], v[66:67], v[172:173], v[24:25] op_sel:[0,1,0] op_sel_hi:[1,1,1]
	v_pk_mul_f32 v[168:169], v[164:165], v[70:71] op_sel:[0,1] op_sel_hi:[1,1]
	v_pk_mul_f32 v[172:173], v[170:171], v[66:67] op_sel:[0,1] op_sel_hi:[1,1]
	v_pk_fma_f32 v[168:169], v[164:165], v[72:73], v[168:169] op_sel:[1,1,0] op_sel_hi:[0,1,1] neg_lo:[0,1,0]
	v_pk_fma_f32 v[172:173], v[170:171], v[68:69], v[172:173] op_sel:[1,1,0] op_sel_hi:[0,1,1] neg_lo:[0,1,0]
	v_pk_fma_f32 v[58:59], v[78:79], v[164:165], v[58:59] op_sel_hi:[1,0,1]
	v_pk_fma_f32 v[42:43], v[74:75], v[170:171], v[42:43] op_sel_hi:[1,0,1]
	v_pk_fma_f32 v[60:61], v[70:71], v[164:165], v[60:61] op_sel_hi:[1,0,1]
	v_pk_fma_f32 v[44:45], v[66:67], v[170:171], v[44:45] op_sel_hi:[1,0,1]
	v_pk_fma_f32 v[10:11], v[80:81], v[164:165], v[10:11] op_sel_hi:[1,0,1]
	v_pk_fma_f32 v[26:27], v[76:77], v[170:171], v[26:27] op_sel_hi:[1,0,1]
	v_pk_fma_f32 v[12:13], v[72:73], v[164:165], v[12:13] op_sel_hi:[1,0,1]
	v_pk_fma_f32 v[28:29], v[68:69], v[170:171], v[28:29] op_sel_hi:[1,0,1]
	v_pk_fma_f32 v[58:59], v[80:81], v[164:165], v[58:59] op_sel:[0,1,0] op_sel_hi:[1,1,1] neg_lo:[0,1,0] neg_hi:[0,1,0]
	v_pk_fma_f32 v[42:43], v[76:77], v[170:171], v[42:43] op_sel:[0,1,0] op_sel_hi:[1,1,1] neg_lo:[0,1,0] neg_hi:[0,1,0]
	v_pk_fma_f32 v[60:61], v[72:73], v[164:165], v[60:61] op_sel:[0,1,0] op_sel_hi:[1,1,1] neg_lo:[0,1,0] neg_hi:[0,1,0]
	v_pk_fma_f32 v[44:45], v[68:69], v[170:171], v[44:45] op_sel:[0,1,0] op_sel_hi:[1,1,1] neg_lo:[0,1,0] neg_hi:[0,1,0]
	v_pk_fma_f32 v[10:11], v[78:79], v[164:165], v[10:11] op_sel:[0,1,0] op_sel_hi:[1,1,1]
	v_pk_fma_f32 v[26:27], v[74:75], v[170:171], v[26:27] op_sel:[0,1,0] op_sel_hi:[1,1,1]
	v_pk_fma_f32 v[12:13], v[70:71], v[164:165], v[12:13] op_sel:[0,1,0] op_sel_hi:[1,1,1]
	v_pk_fma_f32 v[28:29], v[66:67], v[170:171], v[28:29] op_sel:[0,1,0] op_sel_hi:[1,1,1]
	v_pk_fma_f32 v[62:63], v[78:79], v[168:169], v[62:63] op_sel_hi:[1,0,1]
	v_pk_fma_f32 v[46:47], v[74:75], v[172:173], v[46:47] op_sel_hi:[1,0,1]
	v_pk_fma_f32 v[64:65], v[70:71], v[168:169], v[64:65] op_sel_hi:[1,0,1]
	v_pk_fma_f32 v[48:49], v[66:67], v[172:173], v[48:49] op_sel_hi:[1,0,1]
	v_pk_fma_f32 v[14:15], v[80:81], v[168:169], v[14:15] op_sel_hi:[1,0,1]
	v_pk_fma_f32 v[30:31], v[76:77], v[172:173], v[30:31] op_sel_hi:[1,0,1]
	v_pk_fma_f32 v[16:17], v[72:73], v[168:169], v[16:17] op_sel_hi:[1,0,1]
	v_pk_fma_f32 v[32:33], v[68:69], v[172:173], v[32:33] op_sel_hi:[1,0,1]
	v_pk_fma_f32 v[62:63], v[80:81], v[168:169], v[62:63] op_sel:[0,1,0] op_sel_hi:[1,1,1] neg_lo:[0,1,0] neg_hi:[0,1,0]
	v_pk_fma_f32 v[46:47], v[76:77], v[172:173], v[46:47] op_sel:[0,1,0] op_sel_hi:[1,1,1] neg_lo:[0,1,0] neg_hi:[0,1,0]
	v_pk_fma_f32 v[64:65], v[72:73], v[168:169], v[64:65] op_sel:[0,1,0] op_sel_hi:[1,1,1] neg_lo:[0,1,0] neg_hi:[0,1,0]
	v_pk_fma_f32 v[48:49], v[68:69], v[172:173], v[48:49] op_sel:[0,1,0] op_sel_hi:[1,1,1] neg_lo:[0,1,0] neg_hi:[0,1,0]
	v_pk_fma_f32 v[14:15], v[78:79], v[168:169], v[14:15] op_sel:[0,1,0] op_sel_hi:[1,1,1]
	v_pk_fma_f32 v[30:31], v[74:75], v[172:173], v[30:31] op_sel:[0,1,0] op_sel_hi:[1,1,1]
	v_pk_fma_f32 v[16:17], v[70:71], v[168:169], v[16:17] op_sel:[0,1,0] op_sel_hi:[1,1,1]
	v_pk_fma_f32 v[32:33], v[66:67], v[172:173], v[32:33] op_sel:[0,1,0] op_sel_hi:[1,1,1]
	v_mov_b32_e32 v156, v65
	v_mov_b32_e32 v157, v17
	v_mov_b32_e32 v166, v65
	v_mov_b32_e32 v167, v17
	s_nop 1
	v_permlane32_swap_b32_e32 v156, v166
	v_permlane32_swap_b32_e32 v157, v167
	v_mov_b32_e32 v156, v49
	v_mov_b32_e32 v157, v33
	v_mov_b32_e32 v150, v49
	v_mov_b32_e32 v151, v33
	s_nop 1
	v_permlane32_swap_b32_e32 v156, v150
	v_permlane32_swap_b32_e32 v157, v151
	v_cvt_pk_bf16_f32 v1, v50, v2
	ds_write_b32 v174, v1
	v_cvt_pk_bf16_f32 v146, v34, v18
	ds_write_b32 v174, v146 offset:128
	v_cvt_pk_bf16_f32 v178, v51, v3
	ds_write_b32 v174, v178 offset:272
	v_cvt_pk_bf16_f32 v1, v35, v19
	ds_write_b32 v174, v1 offset:400
	v_cvt_pk_bf16_f32 v146, v52, v4
	ds_write_b32 v174, v146 offset:544
	v_cvt_pk_bf16_f32 v178, v36, v20
	ds_write_b32 v174, v178 offset:672
	v_cvt_pk_bf16_f32 v1, v53, v5
	ds_write_b32 v174, v1 offset:816
	v_cvt_pk_bf16_f32 v146, v37, v21
	ds_write_b32 v174, v146 offset:944
	v_cvt_pk_bf16_f32 v178, v54, v6
	ds_write_b32 v174, v178 offset:1088
	v_cvt_pk_bf16_f32 v1, v38, v22
	ds_write_b32 v174, v1 offset:1216
	v_cvt_pk_bf16_f32 v146, v55, v7
	ds_write_b32 v174, v146 offset:1360
	v_cvt_pk_bf16_f32 v178, v39, v23
	ds_write_b32 v174, v178 offset:1488
	v_cvt_pk_bf16_f32 v1, v56, v8
	ds_write_b32 v174, v1 offset:1632
	v_cvt_pk_bf16_f32 v146, v40, v24
	ds_write_b32 v174, v146 offset:1760
	v_cvt_pk_bf16_f32 v178, v57, v9
	ds_write_b32 v174, v178 offset:1904
	v_cvt_pk_bf16_f32 v1, v41, v25
	ds_write_b32 v174, v1 offset:2032
	v_cvt_pk_bf16_f32 v146, v58, v10
	ds_write_b32 v174, v146 offset:2176
	v_cvt_pk_bf16_f32 v178, v42, v26
	ds_write_b32 v174, v178 offset:2304
	v_cvt_pk_bf16_f32 v1, v59, v11
	ds_write_b32 v174, v1 offset:2448
	v_cvt_pk_bf16_f32 v146, v43, v27
	ds_write_b32 v174, v146 offset:2576
	v_cvt_pk_bf16_f32 v178, v60, v12
	ds_write_b32 v174, v178 offset:2720
	v_cvt_pk_bf16_f32 v1, v44, v28
	ds_write_b32 v174, v1 offset:2848
	v_cvt_pk_bf16_f32 v146, v61, v13
	ds_write_b32 v174, v146 offset:2992
	v_cvt_pk_bf16_f32 v178, v45, v29
	ds_write_b32 v174, v178 offset:3120
	v_cvt_pk_bf16_f32 v1, v62, v14
	ds_write_b32 v174, v1 offset:3264
	v_cvt_pk_bf16_f32 v146, v46, v30
	ds_write_b32 v174, v146 offset:3392
	v_cvt_pk_bf16_f32 v178, v63, v15
	ds_write_b32 v174, v178 offset:3536
	v_cvt_pk_bf16_f32 v1, v47, v31
	ds_write_b32 v174, v1 offset:3664
	v_cvt_pk_bf16_f32 v146, v64, v16
	ds_write_b32 v174, v146 offset:3808
	v_cvt_pk_bf16_f32 v178, v48, v32
	ds_write_b32 v174, v178 offset:3936
	v_cvt_pk_bf16_f32 v1, v65, v17
	ds_write_b32 v174, v1 offset:4080
	v_cvt_pk_bf16_f32 v146, v49, v33
	ds_write_b32 v174, v146 offset:4208
	s_waitcnt lgkmcnt(0)
	ds_read_b128 v[2:5], v175
	ds_read_b128 v[6:9], v175 offset:64
	ds_read_b128 v[10:13], v175 offset:128
	ds_read_b128 v[14:17], v175 offset:192
	ds_read_b128 v[18:21], v175 offset:4352
	ds_read_b128 v[22:25], v175 offset:4416
	ds_read_b128 v[26:29], v175 offset:4480
	ds_read_b128 v[30:33], v175 offset:4544
	s_waitcnt vmcnt(0)
	s_waitcnt lgkmcnt(7)
	v_mfma_f32_16x16x32_bf16 v[34:37], v[94:97], v[2:5], 0
	s_waitcnt lgkmcnt(6)
	v_mfma_f32_16x16x32_bf16 v[34:37], v[90:93], v[6:9], v[34:37]
	s_waitcnt lgkmcnt(5)
	v_mfma_f32_16x16x32_bf16 v[34:37], v[86:89], v[10:13], v[34:37]
	s_waitcnt lgkmcnt(4)
	v_mfma_f32_16x16x32_bf16 v[34:37], v[82:85], v[14:17], v[34:37]
	s_waitcnt lgkmcnt(3)
	v_mfma_f32_16x16x32_bf16 v[38:41], v[94:97], v[18:21], 0
	s_waitcnt lgkmcnt(2)
	v_mfma_f32_16x16x32_bf16 v[38:41], v[90:93], v[22:25], v[38:41]
	s_waitcnt lgkmcnt(1)
	v_mfma_f32_16x16x32_bf16 v[38:41], v[86:89], v[26:29], v[38:41]
	s_waitcnt lgkmcnt(0)
	v_mfma_f32_16x16x32_bf16 v[38:41], v[82:85], v[30:33], v[38:41]
	s_add_u32 s6, s6, 0x8000
	s_addc_u32 s7, s7, 0
	v_lshlrev_b32_e32 v42, 16, v160
	v_and_b32_e32 v43, 0xffff0000, v160
	v_lshlrev_b32_e32 v44, 16, v161
	v_and_b32_e32 v45, 0xffff0000, v161
	v_lshlrev_b32_e32 v46, 16, v162
	v_and_b32_e32 v47, 0xffff0000, v162
	v_lshlrev_b32_e32 v48, 16, v163
	v_and_b32_e32 v49, 0xffff0000, v163
	s_nop 1
	v_mov_b32_e32 v156, 0x3d372713
	v_mov_b32_e32 v158, 0xbfcc422a
	v_mov_b32_e32 v164, 0x3fb8aa3b
	v_mov_b32_e32 v168, 1.0
	v_pk_fma_f32 v[50:51], v[98:99], v[42:43], v[34:35]
	v_pk_fma_f32 v[52:53], v[100:101], v[44:45], v[36:37]
	v_pk_fma_f32 v[54:55], v[98:99], v[46:47], v[38:39]
	v_pk_fma_f32 v[56:57], v[100:101], v[48:49], v[40:41]
	v_pk_mul_f32 v[2:3], v[50:51], v[156:157] op_sel_hi:[1,0]
	v_pk_mul_f32 v[4:5], v[52:53], v[156:157] op_sel_hi:[1,0]
	v_pk_mul_f32 v[6:7], v[54:55], v[156:157] op_sel_hi:[1,0]
	v_pk_mul_f32 v[8:9], v[56:57], v[156:157] op_sel_hi:[1,0]
	v_pk_mul_f32 v[2:3], v[50:51], v[2:3]
	v_pk_mul_f32 v[4:5], v[52:53], v[4:5]
	v_pk_mul_f32 v[6:7], v[54:55], v[6:7]
	v_pk_mul_f32 v[8:9], v[56:57], v[8:9]
	v_pk_fma_f32 v[2:3], v[50:51], v[2:3], v[50:51]
	v_pk_fma_f32 v[4:5], v[52:53], v[4:5], v[52:53]
	v_pk_fma_f32 v[6:7], v[54:55], v[6:7], v[54:55]
	v_pk_fma_f32 v[8:9], v[56:57], v[8:9], v[56:57]
	v_pk_mul_f32 v[2:3], v[2:3], v[158:159] op_sel_hi:[1,0]
	v_pk_mul_f32 v[4:5], v[4:5], v[158:159] op_sel_hi:[1,0]
	v_pk_mul_f32 v[6:7], v[6:7], v[158:159] op_sel_hi:[1,0]
	v_pk_mul_f32 v[8:9], v[8:9], v[158:159] op_sel_hi:[1,0]
	v_pk_mul_f32 v[2:3], v[2:3], v[164:165] op_sel_hi:[1,0]
	v_pk_mul_f32 v[4:5], v[4:5], v[164:165] op_sel_hi:[1,0]
	v_pk_mul_f32 v[6:7], v[6:7], v[164:165] op_sel_hi:[1,0]
	v_pk_mul_f32 v[8:9], v[8:9], v[164:165] op_sel_hi:[1,0]
	v_exp_f32_e32 v2, v2
	v_exp_f32_e32 v3, v3
	v_exp_f32_e32 v4, v4
	v_exp_f32_e32 v5, v5
	v_exp_f32_e32 v6, v6
	v_exp_f32_e32 v7, v7
	v_exp_f32_e32 v8, v8
	v_exp_f32_e32 v9, v9
	v_pk_add_f32 v[2:3], v[2:3], v[168:169] op_sel_hi:[1,0]
	v_pk_add_f32 v[4:5], v[4:5], v[168:169] op_sel_hi:[1,0]
	v_pk_add_f32 v[6:7], v[6:7], v[168:169] op_sel_hi:[1,0]
	v_pk_add_f32 v[8:9], v[8:9], v[168:169] op_sel_hi:[1,0]
	v_rcp_f32_e32 v2, v2
	v_rcp_f32_e32 v3, v3
	v_rcp_f32_e32 v4, v4
	v_rcp_f32_e32 v5, v5
	v_rcp_f32_e32 v6, v6
	v_rcp_f32_e32 v7, v7
	v_rcp_f32_e32 v8, v8
	v_rcp_f32_e32 v9, v9
	v_pk_mul_f32 v[50:51], v[50:51], v[2:3]
	v_pk_mul_f32 v[52:53], v[52:53], v[4:5]
	v_pk_mul_f32 v[54:55], v[54:55], v[6:7]
	v_pk_mul_f32 v[56:57], v[56:57], v[8:9]
	v_cvt_pk_bf16_f32 v10, v50, v51
	v_cvt_pk_bf16_f32 v11, v52, v53
	v_cvt_pk_bf16_f32 v12, v54, v55
	v_cvt_pk_bf16_f32 v13, v56, v57
	global_store_dwordx2 v176, v[10:11], s[10:11]
	global_store_dwordx2 v177, v[12:13], s[10:11]
	s_add_u32 s10, s10, 0x8000
	s_addc_u32 s11, s11, 0
	s_nop 0
	v_mfma_f32_32x32x16_bf16 v[50:65], v[142:145], v[114:117], 0
	v_mfma_f32_32x32x16_bf16 v[2:17], v[142:145], v[110:113], 0
	v_mfma_f32_32x32x16_bf16 v[34:49], v[142:145], v[106:109], 0
	v_mfma_f32_32x32x16_bf16 v[18:33], v[142:145], v[102:105], 0
	global_load_dwordx2 v[160:161], v176, s[6:7]
	global_load_dwordx2 v[162:163], v177, s[6:7]
	s_nop 9
	v_fmac_f32_e32 v51, v78, v50
	v_fmac_f32_e32 v35, v74, v34
	v_fmac_f32_e32 v3, v80, v50
	v_fmac_f32_e32 v19, v76, v34
	v_fma_f32 v51, -v80, v2, v51
	v_fma_f32 v35, -v76, v18, v35
	v_fmac_f32_e32 v3, v78, v2
	v_fmac_f32_e32 v19, v74, v18
	v_fmac_f32_e32 v52, v78, v51
	v_fmac_f32_e32 v36, v74, v35
	v_fmac_f32_e32 v4, v80, v51
	v_fmac_f32_e32 v20, v76, v35
	v_fma_f32 v52, -v80, v3, v52
	v_fma_f32 v36, -v76, v19, v36
	v_fmac_f32_e32 v4, v78, v3
	v_fmac_f32_e32 v20, v74, v19
	v_fmac_f32_e32 v53, v78, v52
	v_fmac_f32_e32 v37, v74, v36
	v_fmac_f32_e32 v5, v80, v52
	v_fmac_f32_e32 v21, v76, v36
	v_fma_f32 v53, -v80, v4, v53
	v_fma_f32 v37, -v76, v20, v37
	v_fmac_f32_e32 v5, v78, v4
	v_fmac_f32_e32 v21, v74, v20
	v_fmac_f32_e32 v54, v78, v53
	v_fmac_f32_e32 v38, v74, v37
	v_fmac_f32_e32 v6, v80, v53
	v_fmac_f32_e32 v22, v76, v37
	v_fma_f32 v54, -v80, v5, v54
	v_fma_f32 v38, -v76, v21, v38
	v_fmac_f32_e32 v6, v78, v5
	v_fmac_f32_e32 v22, v74, v21
	v_fmac_f32_e32 v55, v78, v54
	v_fmac_f32_e32 v39, v74, v38
	v_fmac_f32_e32 v7, v80, v54
	v_fmac_f32_e32 v23, v76, v38
	v_fma_f32 v55, -v80, v6, v55
	v_fma_f32 v39, -v76, v22, v39
	v_fmac_f32_e32 v7, v78, v6
	v_fmac_f32_e32 v23, v74, v22
	v_fmac_f32_e32 v56, v78, v55
	v_fmac_f32_e32 v40, v74, v39
	v_fmac_f32_e32 v8, v80, v55
	v_fmac_f32_e32 v24, v76, v39
	v_fma_f32 v56, -v80, v7, v56
	v_fma_f32 v40, -v76, v23, v40
	v_fmac_f32_e32 v8, v78, v7
	v_fmac_f32_e32 v24, v74, v23
	v_fmac_f32_e32 v57, v78, v56
	v_fmac_f32_e32 v41, v74, v40
	v_fmac_f32_e32 v9, v80, v56
	v_fmac_f32_e32 v25, v76, v40
	v_fma_f32 v57, -v80, v8, v57
	v_fma_f32 v41, -v76, v24, v41
	v_fmac_f32_e32 v9, v78, v8
	v_fmac_f32_e32 v25, v74, v24
	v_fmac_f32_e32 v58, v78, v57
	v_fmac_f32_e32 v42, v74, v41
	v_fmac_f32_e32 v10, v80, v57
	v_fmac_f32_e32 v26, v76, v41
	v_fma_f32 v58, -v80, v9, v58
	v_fma_f32 v42, -v76, v25, v42
	v_fmac_f32_e32 v10, v78, v9
	v_fmac_f32_e32 v26, v74, v25
	v_fmac_f32_e32 v59, v78, v58
	v_fmac_f32_e32 v43, v74, v42
	v_fmac_f32_e32 v11, v80, v58
	v_fmac_f32_e32 v27, v76, v42
	v_fma_f32 v59, -v80, v10, v59
	v_fma_f32 v43, -v76, v26, v43
	v_fmac_f32_e32 v11, v78, v10
	v_fmac_f32_e32 v27, v74, v26
	v_fmac_f32_e32 v60, v78, v59
	v_fmac_f32_e32 v44, v74, v43
	v_fmac_f32_e32 v12, v80, v59
	v_fmac_f32_e32 v28, v76, v43
	v_fma_f32 v60, -v80, v11, v60
	v_fma_f32 v44, -v76, v27, v44
	v_fmac_f32_e32 v12, v78, v11
	v_fmac_f32_e32 v28, v74, v27
	v_fmac_f32_e32 v61, v78, v60
	v_fmac_f32_e32 v45, v74, v44
	v_fmac_f32_e32 v13, v80, v60
	v_fmac_f32_e32 v29, v76, v44
	v_fma_f32 v61, -v80, v12, v61
	v_fma_f32 v45, -v76, v28, v45
	v_fmac_f32_e32 v13, v78, v12
	v_fmac_f32_e32 v29, v74, v28
	v_fmac_f32_e32 v62, v78, v61
	v_fmac_f32_e32 v46, v74, v45
	v_fmac_f32_e32 v14, v80, v61
	v_fmac_f32_e32 v30, v76, v45
	v_fma_f32 v62, -v80, v13, v62
	v_fma_f32 v46, -v76, v29, v46
	v_fmac_f32_e32 v14, v78, v13
	v_fmac_f32_e32 v30, v74, v29
	v_fmac_f32_e32 v63, v78, v62
	v_fmac_f32_e32 v47, v74, v46
	v_fmac_f32_e32 v15, v80, v62
	v_fmac_f32_e32 v31, v76, v46
	v_fma_f32 v63, -v80, v14, v63
	v_fma_f32 v47, -v76, v30, v47
	v_fmac_f32_e32 v15, v78, v14
	v_fmac_f32_e32 v31, v74, v30
	v_fmac_f32_e32 v64, v78, v63
	v_fmac_f32_e32 v48, v74, v47
	v_fmac_f32_e32 v16, v80, v63
	v_fmac_f32_e32 v32, v76, v47
	v_fma_f32 v64, -v80, v15, v64
	v_fma_f32 v48, -v76, v31, v48
	v_fmac_f32_e32 v16, v78, v15
	v_fmac_f32_e32 v32, v74, v31
	v_fmac_f32_e32 v65, v78, v64
	v_fmac_f32_e32 v49, v74, v48
	v_fmac_f32_e32 v17, v80, v64
	v_fmac_f32_e32 v33, v76, v48
	v_fma_f32 v65, -v80, v16, v65
	v_fma_f32 v49, -v76, v32, v49
	v_fmac_f32_e32 v17, v78, v16
	v_fmac_f32_e32 v33, v74, v32
	v_mov_b32_e32 v156, v65
	v_mov_b32_e32 v157, v17
	v_mov_b32_e32 v158, v65
	v_mov_b32_e32 v159, v17
	s_nop 1
	v_permlane32_swap_b32_e32 v156, v158
	v_permlane32_swap_b32_e32 v157, v159
	v_pk_fma_f32 v[164:165], v[166:167], v[152:153], v[156:157] op_sel_hi:[1,0,1]
	v_pk_fma_f32 v[164:165], v[166:167], v[152:153], v[164:165] op_sel:[1,1,0] op_sel_hi:[0,1,1] neg_lo:[0,1,0]
	v_cndmask_b32_e32 v164, v166, v164, vcc
	v_cndmask_b32_e32 v165, v167, v165, vcc
	v_mov_b32_e32 v156, v49
	v_mov_b32_e32 v157, v33
	v_mov_b32_e32 v158, v49
	v_mov_b32_e32 v159, v33
	s_nop 1
	v_permlane32_swap_b32_e32 v156, v158
	v_permlane32_swap_b32_e32 v157, v159
	v_pk_fma_f32 v[170:171], v[150:151], v[154:155], v[156:157] op_sel_hi:[1,0,1]
	v_pk_fma_f32 v[170:171], v[150:151], v[154:155], v[170:171] op_sel:[1,1,0] op_sel_hi:[0,1,1] neg_lo:[0,1,0]
	v_cndmask_b32_e32 v170, v150, v170, vcc
	v_cndmask_b32_e32 v171, v151, v171, vcc
	v_pk_mul_f32 v[168:169], v[164:165], v[70:71] op_sel:[0,1] op_sel_hi:[1,1]
	v_pk_mul_f32 v[172:173], v[170:171], v[66:67] op_sel:[0,1] op_sel_hi:[1,1]
	v_pk_fma_f32 v[168:169], v[164:165], v[72:73], v[168:169] op_sel:[1,1,0] op_sel_hi:[0,1,1] neg_lo:[0,1,0]
	v_pk_fma_f32 v[172:173], v[170:171], v[68:69], v[172:173] op_sel:[1,1,0] op_sel_hi:[0,1,1] neg_lo:[0,1,0]
	v_pk_fma_f32 v[50:51], v[78:79], v[164:165], v[50:51] op_sel_hi:[1,0,1]
	v_pk_fma_f32 v[34:35], v[74:75], v[170:171], v[34:35] op_sel_hi:[1,0,1]
	v_pk_fma_f32 v[52:53], v[70:71], v[164:165], v[52:53] op_sel_hi:[1,0,1]
	v_pk_fma_f32 v[36:37], v[66:67], v[170:171], v[36:37] op_sel_hi:[1,0,1]
	v_pk_fma_f32 v[2:3], v[80:81], v[164:165], v[2:3] op_sel_hi:[1,0,1]
	v_pk_fma_f32 v[18:19], v[76:77], v[170:171], v[18:19] op_sel_hi:[1,0,1]
	v_pk_fma_f32 v[4:5], v[72:73], v[164:165], v[4:5] op_sel_hi:[1,0,1]
	v_pk_fma_f32 v[20:21], v[68:69], v[170:171], v[20:21] op_sel_hi:[1,0,1]
	v_pk_fma_f32 v[50:51], v[80:81], v[164:165], v[50:51] op_sel:[0,1,0] op_sel_hi:[1,1,1] neg_lo:[0,1,0] neg_hi:[0,1,0]
	v_pk_fma_f32 v[34:35], v[76:77], v[170:171], v[34:35] op_sel:[0,1,0] op_sel_hi:[1,1,1] neg_lo:[0,1,0] neg_hi:[0,1,0]
	v_pk_fma_f32 v[52:53], v[72:73], v[164:165], v[52:53] op_sel:[0,1,0] op_sel_hi:[1,1,1] neg_lo:[0,1,0] neg_hi:[0,1,0]
	v_pk_fma_f32 v[36:37], v[68:69], v[170:171], v[36:37] op_sel:[0,1,0] op_sel_hi:[1,1,1] neg_lo:[0,1,0] neg_hi:[0,1,0]
	v_pk_fma_f32 v[2:3], v[78:79], v[164:165], v[2:3] op_sel:[0,1,0] op_sel_hi:[1,1,1]
	v_pk_fma_f32 v[18:19], v[74:75], v[170:171], v[18:19] op_sel:[0,1,0] op_sel_hi:[1,1,1]
	v_pk_fma_f32 v[4:5], v[70:71], v[164:165], v[4:5] op_sel:[0,1,0] op_sel_hi:[1,1,1]
	v_pk_fma_f32 v[20:21], v[66:67], v[170:171], v[20:21] op_sel:[0,1,0] op_sel_hi:[1,1,1]
	v_pk_mul_f32 v[164:165], v[168:169], v[70:71] op_sel:[0,1] op_sel_hi:[1,1]
	v_pk_mul_f32 v[170:171], v[172:173], v[66:67] op_sel:[0,1] op_sel_hi:[1,1]
	v_pk_fma_f32 v[164:165], v[168:169], v[72:73], v[164:165] op_sel:[1,1,0] op_sel_hi:[0,1,1] neg_lo:[0,1,0]
	v_pk_fma_f32 v[170:171], v[172:173], v[68:69], v[170:171] op_sel:[1,1,0] op_sel_hi:[0,1,1] neg_lo:[0,1,0]
	v_pk_fma_f32 v[54:55], v[78:79], v[168:169], v[54:55] op_sel_hi:[1,0,1]
	v_pk_fma_f32 v[38:39], v[74:75], v[172:173], v[38:39] op_sel_hi:[1,0,1]
	v_pk_fma_f32 v[56:57], v[70:71], v[168:169], v[56:57] op_sel_hi:[1,0,1]
	v_pk_fma_f32 v[40:41], v[66:67], v[172:173], v[40:41] op_sel_hi:[1,0,1]
	v_pk_fma_f32 v[6:7], v[80:81], v[168:169], v[6:7] op_sel_hi:[1,0,1]
	v_pk_fma_f32 v[22:23], v[76:77], v[172:173], v[22:23] op_sel_hi:[1,0,1]
	v_pk_fma_f32 v[8:9], v[72:73], v[168:169], v[8:9] op_sel_hi:[1,0,1]
	v_pk_fma_f32 v[24:25], v[68:69], v[172:173], v[24:25] op_sel_hi:[1,0,1]
	v_pk_fma_f32 v[54:55], v[80:81], v[168:169], v[54:55] op_sel:[0,1,0] op_sel_hi:[1,1,1] neg_lo:[0,1,0] neg_hi:[0,1,0]
	v_pk_fma_f32 v[38:39], v[76:77], v[172:173], v[38:39] op_sel:[0,1,0] op_sel_hi:[1,1,1] neg_lo:[0,1,0] neg_hi:[0,1,0]
	v_pk_fma_f32 v[56:57], v[72:73], v[168:169], v[56:57] op_sel:[0,1,0] op_sel_hi:[1,1,1] neg_lo:[0,1,0] neg_hi:[0,1,0]
	v_pk_fma_f32 v[40:41], v[68:69], v[172:173], v[40:41] op_sel:[0,1,0] op_sel_hi:[1,1,1] neg_lo:[0,1,0] neg_hi:[0,1,0]
	v_pk_fma_f32 v[6:7], v[78:79], v[168:169], v[6:7] op_sel:[0,1,0] op_sel_hi:[1,1,1]
	v_pk_fma_f32 v[22:23], v[74:75], v[172:173], v[22:23] op_sel:[0,1,0] op_sel_hi:[1,1,1]
	v_pk_fma_f32 v[8:9], v[70:71], v[168:169], v[8:9] op_sel:[0,1,0] op_sel_hi:[1,1,1]
	v_pk_fma_f32 v[24:25], v[66:67], v[172:173], v[24:25] op_sel:[0,1,0] op_sel_hi:[1,1,1]
	v_pk_mul_f32 v[168:169], v[164:165], v[70:71] op_sel:[0,1] op_sel_hi:[1,1]
	v_pk_mul_f32 v[172:173], v[170:171], v[66:67] op_sel:[0,1] op_sel_hi:[1,1]
	v_pk_fma_f32 v[168:169], v[164:165], v[72:73], v[168:169] op_sel:[1,1,0] op_sel_hi:[0,1,1] neg_lo:[0,1,0]
	v_pk_fma_f32 v[172:173], v[170:171], v[68:69], v[172:173] op_sel:[1,1,0] op_sel_hi:[0,1,1] neg_lo:[0,1,0]
	v_pk_fma_f32 v[58:59], v[78:79], v[164:165], v[58:59] op_sel_hi:[1,0,1]
	v_pk_fma_f32 v[42:43], v[74:75], v[170:171], v[42:43] op_sel_hi:[1,0,1]
	v_pk_fma_f32 v[60:61], v[70:71], v[164:165], v[60:61] op_sel_hi:[1,0,1]
	v_pk_fma_f32 v[44:45], v[66:67], v[170:171], v[44:45] op_sel_hi:[1,0,1]
	v_pk_fma_f32 v[10:11], v[80:81], v[164:165], v[10:11] op_sel_hi:[1,0,1]
	v_pk_fma_f32 v[26:27], v[76:77], v[170:171], v[26:27] op_sel_hi:[1,0,1]
	v_pk_fma_f32 v[12:13], v[72:73], v[164:165], v[12:13] op_sel_hi:[1,0,1]
	v_pk_fma_f32 v[28:29], v[68:69], v[170:171], v[28:29] op_sel_hi:[1,0,1]
	v_pk_fma_f32 v[58:59], v[80:81], v[164:165], v[58:59] op_sel:[0,1,0] op_sel_hi:[1,1,1] neg_lo:[0,1,0] neg_hi:[0,1,0]
	v_pk_fma_f32 v[42:43], v[76:77], v[170:171], v[42:43] op_sel:[0,1,0] op_sel_hi:[1,1,1] neg_lo:[0,1,0] neg_hi:[0,1,0]
	v_pk_fma_f32 v[60:61], v[72:73], v[164:165], v[60:61] op_sel:[0,1,0] op_sel_hi:[1,1,1] neg_lo:[0,1,0] neg_hi:[0,1,0]
	v_pk_fma_f32 v[44:45], v[68:69], v[170:171], v[44:45] op_sel:[0,1,0] op_sel_hi:[1,1,1] neg_lo:[0,1,0] neg_hi:[0,1,0]
	v_pk_fma_f32 v[10:11], v[78:79], v[164:165], v[10:11] op_sel:[0,1,0] op_sel_hi:[1,1,1]
	v_pk_fma_f32 v[26:27], v[74:75], v[170:171], v[26:27] op_sel:[0,1,0] op_sel_hi:[1,1,1]
	v_pk_fma_f32 v[12:13], v[70:71], v[164:165], v[12:13] op_sel:[0,1,0] op_sel_hi:[1,1,1]
	v_pk_fma_f32 v[28:29], v[66:67], v[170:171], v[28:29] op_sel:[0,1,0] op_sel_hi:[1,1,1]
	v_pk_fma_f32 v[62:63], v[78:79], v[168:169], v[62:63] op_sel_hi:[1,0,1]
	v_pk_fma_f32 v[46:47], v[74:75], v[172:173], v[46:47] op_sel_hi:[1,0,1]
	v_pk_fma_f32 v[64:65], v[70:71], v[168:169], v[64:65] op_sel_hi:[1,0,1]
	v_pk_fma_f32 v[48:49], v[66:67], v[172:173], v[48:49] op_sel_hi:[1,0,1]
	v_pk_fma_f32 v[14:15], v[80:81], v[168:169], v[14:15] op_sel_hi:[1,0,1]
	v_pk_fma_f32 v[30:31], v[76:77], v[172:173], v[30:31] op_sel_hi:[1,0,1]
	v_pk_fma_f32 v[16:17], v[72:73], v[168:169], v[16:17] op_sel_hi:[1,0,1]
	v_pk_fma_f32 v[32:33], v[68:69], v[172:173], v[32:33] op_sel_hi:[1,0,1]
	v_pk_fma_f32 v[62:63], v[80:81], v[168:169], v[62:63] op_sel:[0,1,0] op_sel_hi:[1,1,1] neg_lo:[0,1,0] neg_hi:[0,1,0]
	v_pk_fma_f32 v[46:47], v[76:77], v[172:173], v[46:47] op_sel:[0,1,0] op_sel_hi:[1,1,1] neg_lo:[0,1,0] neg_hi:[0,1,0]
	v_pk_fma_f32 v[64:65], v[72:73], v[168:169], v[64:65] op_sel:[0,1,0] op_sel_hi:[1,1,1] neg_lo:[0,1,0] neg_hi:[0,1,0]
	v_pk_fma_f32 v[48:49], v[68:69], v[172:173], v[48:49] op_sel:[0,1,0] op_sel_hi:[1,1,1] neg_lo:[0,1,0] neg_hi:[0,1,0]
	v_pk_fma_f32 v[14:15], v[78:79], v[168:169], v[14:15] op_sel:[0,1,0] op_sel_hi:[1,1,1]
	v_pk_fma_f32 v[30:31], v[74:75], v[172:173], v[30:31] op_sel:[0,1,0] op_sel_hi:[1,1,1]
	v_pk_fma_f32 v[16:17], v[70:71], v[168:169], v[16:17] op_sel:[0,1,0] op_sel_hi:[1,1,1]
	v_pk_fma_f32 v[32:33], v[66:67], v[172:173], v[32:33] op_sel:[0,1,0] op_sel_hi:[1,1,1]
	v_mov_b32_e32 v156, v65
	v_mov_b32_e32 v157, v17
	v_mov_b32_e32 v166, v65
	v_mov_b32_e32 v167, v17
	s_nop 1
	v_permlane32_swap_b32_e32 v156, v166
	v_permlane32_swap_b32_e32 v157, v167
	v_mov_b32_e32 v156, v49
	v_mov_b32_e32 v157, v33
	v_mov_b32_e32 v150, v49
	v_mov_b32_e32 v151, v33
	s_nop 1
	v_permlane32_swap_b32_e32 v156, v150
	v_permlane32_swap_b32_e32 v157, v151
	v_cvt_pk_bf16_f32 v1, v50, v2
	ds_write_b32 v174, v1
	v_cvt_pk_bf16_f32 v146, v34, v18
	ds_write_b32 v174, v146 offset:128
	v_cvt_pk_bf16_f32 v178, v51, v3
	ds_write_b32 v174, v178 offset:272
	v_cvt_pk_bf16_f32 v1, v35, v19
	ds_write_b32 v174, v1 offset:400
	v_cvt_pk_bf16_f32 v146, v52, v4
	ds_write_b32 v174, v146 offset:544
	v_cvt_pk_bf16_f32 v178, v36, v20
	ds_write_b32 v174, v178 offset:672
	v_cvt_pk_bf16_f32 v1, v53, v5
	ds_write_b32 v174, v1 offset:816
	v_cvt_pk_bf16_f32 v146, v37, v21
	ds_write_b32 v174, v146 offset:944
	v_cvt_pk_bf16_f32 v178, v54, v6
	ds_write_b32 v174, v178 offset:1088
	v_cvt_pk_bf16_f32 v1, v38, v22
	ds_write_b32 v174, v1 offset:1216
	v_cvt_pk_bf16_f32 v146, v55, v7
	ds_write_b32 v174, v146 offset:1360
	v_cvt_pk_bf16_f32 v178, v39, v23
	ds_write_b32 v174, v178 offset:1488
	v_cvt_pk_bf16_f32 v1, v56, v8
	ds_write_b32 v174, v1 offset:1632
	v_cvt_pk_bf16_f32 v146, v40, v24
	ds_write_b32 v174, v146 offset:1760
	v_cvt_pk_bf16_f32 v178, v57, v9
	ds_write_b32 v174, v178 offset:1904
	v_cvt_pk_bf16_f32 v1, v41, v25
	ds_write_b32 v174, v1 offset:2032
	v_cvt_pk_bf16_f32 v146, v58, v10
	ds_write_b32 v174, v146 offset:2176
	v_cvt_pk_bf16_f32 v178, v42, v26
	ds_write_b32 v174, v178 offset:2304
	v_cvt_pk_bf16_f32 v1, v59, v11
	ds_write_b32 v174, v1 offset:2448
	v_cvt_pk_bf16_f32 v146, v43, v27
	ds_write_b32 v174, v146 offset:2576
	v_cvt_pk_bf16_f32 v178, v60, v12
	ds_write_b32 v174, v178 offset:2720
	v_cvt_pk_bf16_f32 v1, v44, v28
	ds_write_b32 v174, v1 offset:2848
	v_cvt_pk_bf16_f32 v146, v61, v13
	ds_write_b32 v174, v146 offset:2992
	v_cvt_pk_bf16_f32 v178, v45, v29
	ds_write_b32 v174, v178 offset:3120
	v_cvt_pk_bf16_f32 v1, v62, v14
	ds_write_b32 v174, v1 offset:3264
	v_cvt_pk_bf16_f32 v146, v46, v30
	ds_write_b32 v174, v146 offset:3392
	v_cvt_pk_bf16_f32 v178, v63, v15
	ds_write_b32 v174, v178 offset:3536
	v_cvt_pk_bf16_f32 v1, v47, v31
	ds_write_b32 v174, v1 offset:3664
	v_cvt_pk_bf16_f32 v146, v64, v16
	ds_write_b32 v174, v146 offset:3808
	v_cvt_pk_bf16_f32 v178, v48, v32
	ds_write_b32 v174, v178 offset:3936
	v_cvt_pk_bf16_f32 v1, v65, v17
	ds_write_b32 v174, v1 offset:4080
	v_cvt_pk_bf16_f32 v146, v49, v33
	ds_write_b32 v174, v146 offset:4208
	s_waitcnt lgkmcnt(0)
	ds_read_b128 v[2:5], v175
	ds_read_b128 v[6:9], v175 offset:64
	ds_read_b128 v[10:13], v175 offset:128
	ds_read_b128 v[14:17], v175 offset:192
	ds_read_b128 v[18:21], v175 offset:4352
	ds_read_b128 v[22:25], v175 offset:4416
	ds_read_b128 v[26:29], v175 offset:4480
	ds_read_b128 v[30:33], v175 offset:4544
	s_waitcnt vmcnt(0)
	s_waitcnt lgkmcnt(7)
	v_mfma_f32_16x16x32_bf16 v[34:37], v[94:97], v[2:5], 0
	s_waitcnt lgkmcnt(6)
	v_mfma_f32_16x16x32_bf16 v[34:37], v[90:93], v[6:9], v[34:37]
	s_waitcnt lgkmcnt(5)
	v_mfma_f32_16x16x32_bf16 v[34:37], v[86:89], v[10:13], v[34:37]
	s_waitcnt lgkmcnt(4)
	v_mfma_f32_16x16x32_bf16 v[34:37], v[82:85], v[14:17], v[34:37]
	s_waitcnt lgkmcnt(3)
	v_mfma_f32_16x16x32_bf16 v[38:41], v[94:97], v[18:21], 0
	s_waitcnt lgkmcnt(2)
	v_mfma_f32_16x16x32_bf16 v[38:41], v[90:93], v[22:25], v[38:41]
	s_waitcnt lgkmcnt(1)
	v_mfma_f32_16x16x32_bf16 v[38:41], v[86:89], v[26:29], v[38:41]
	s_waitcnt lgkmcnt(0)
	v_mfma_f32_16x16x32_bf16 v[38:41], v[82:85], v[30:33], v[38:41]
	s_add_u32 s6, s6, 0x8000
	s_addc_u32 s7, s7, 0
	v_lshlrev_b32_e32 v42, 16, v160
	v_and_b32_e32 v43, 0xffff0000, v160
	v_lshlrev_b32_e32 v44, 16, v161
	v_and_b32_e32 v45, 0xffff0000, v161
	v_lshlrev_b32_e32 v46, 16, v162
	v_and_b32_e32 v47, 0xffff0000, v162
	v_lshlrev_b32_e32 v48, 16, v163
	v_and_b32_e32 v49, 0xffff0000, v163
	s_nop 1
	v_mov_b32_e32 v156, 0x3d372713
	v_mov_b32_e32 v158, 0xbfcc422a
	v_mov_b32_e32 v164, 0x3fb8aa3b
	v_mov_b32_e32 v168, 1.0
	v_pk_fma_f32 v[50:51], v[98:99], v[42:43], v[34:35]
	v_pk_fma_f32 v[52:53], v[100:101], v[44:45], v[36:37]
	v_pk_fma_f32 v[54:55], v[98:99], v[46:47], v[38:39]
	v_pk_fma_f32 v[56:57], v[100:101], v[48:49], v[40:41]
	v_pk_mul_f32 v[2:3], v[50:51], v[156:157] op_sel_hi:[1,0]
	v_pk_mul_f32 v[4:5], v[52:53], v[156:157] op_sel_hi:[1,0]
	v_pk_mul_f32 v[6:7], v[54:55], v[156:157] op_sel_hi:[1,0]
	v_pk_mul_f32 v[8:9], v[56:57], v[156:157] op_sel_hi:[1,0]
	v_pk_mul_f32 v[2:3], v[50:51], v[2:3]
	v_pk_mul_f32 v[4:5], v[52:53], v[4:5]
	v_pk_mul_f32 v[6:7], v[54:55], v[6:7]
	v_pk_mul_f32 v[8:9], v[56:57], v[8:9]
	v_pk_fma_f32 v[2:3], v[50:51], v[2:3], v[50:51]
	v_pk_fma_f32 v[4:5], v[52:53], v[4:5], v[52:53]
	v_pk_fma_f32 v[6:7], v[54:55], v[6:7], v[54:55]
	v_pk_fma_f32 v[8:9], v[56:57], v[8:9], v[56:57]
	v_pk_mul_f32 v[2:3], v[2:3], v[158:159] op_sel_hi:[1,0]
	v_pk_mul_f32 v[4:5], v[4:5], v[158:159] op_sel_hi:[1,0]
	v_pk_mul_f32 v[6:7], v[6:7], v[158:159] op_sel_hi:[1,0]
	v_pk_mul_f32 v[8:9], v[8:9], v[158:159] op_sel_hi:[1,0]
	v_pk_mul_f32 v[2:3], v[2:3], v[164:165] op_sel_hi:[1,0]
	v_pk_mul_f32 v[4:5], v[4:5], v[164:165] op_sel_hi:[1,0]
	v_pk_mul_f32 v[6:7], v[6:7], v[164:165] op_sel_hi:[1,0]
	v_pk_mul_f32 v[8:9], v[8:9], v[164:165] op_sel_hi:[1,0]
	v_exp_f32_e32 v2, v2
	v_exp_f32_e32 v3, v3
	v_exp_f32_e32 v4, v4
	v_exp_f32_e32 v5, v5
	v_exp_f32_e32 v6, v6
	v_exp_f32_e32 v7, v7
	v_exp_f32_e32 v8, v8
	v_exp_f32_e32 v9, v9
	v_pk_add_f32 v[2:3], v[2:3], v[168:169] op_sel_hi:[1,0]
	v_pk_add_f32 v[4:5], v[4:5], v[168:169] op_sel_hi:[1,0]
	v_pk_add_f32 v[6:7], v[6:7], v[168:169] op_sel_hi:[1,0]
	v_pk_add_f32 v[8:9], v[8:9], v[168:169] op_sel_hi:[1,0]
	v_rcp_f32_e32 v2, v2
	v_rcp_f32_e32 v3, v3
	v_rcp_f32_e32 v4, v4
	v_rcp_f32_e32 v5, v5
	v_rcp_f32_e32 v6, v6
	v_rcp_f32_e32 v7, v7
	v_rcp_f32_e32 v8, v8
	v_rcp_f32_e32 v9, v9
	v_pk_mul_f32 v[50:51], v[50:51], v[2:3]
	v_pk_mul_f32 v[52:53], v[52:53], v[4:5]
	v_pk_mul_f32 v[54:55], v[54:55], v[6:7]
	v_pk_mul_f32 v[56:57], v[56:57], v[8:9]
	v_cvt_pk_bf16_f32 v10, v50, v51
	v_cvt_pk_bf16_f32 v11, v52, v53
	v_cvt_pk_bf16_f32 v12, v54, v55
	v_cvt_pk_bf16_f32 v13, v56, v57
	global_store_dwordx2 v176, v[10:11], s[10:11]
	global_store_dwordx2 v177, v[12:13], s[10:11]
	s_add_u32 s10, s10, 0x8000
	s_addc_u32 s11, s11, 0
	s_nop 0
	v_mfma_f32_32x32x16_bf16 v[50:65], v[138:141], v[114:117], 0
	v_mfma_f32_32x32x16_bf16 v[2:17], v[138:141], v[110:113], 0
	v_mfma_f32_32x32x16_bf16 v[34:49], v[138:141], v[106:109], 0
	v_mfma_f32_32x32x16_bf16 v[18:33], v[138:141], v[102:105], 0
	global_load_dwordx2 v[160:161], v176, s[6:7]
	global_load_dwordx2 v[162:163], v177, s[6:7]
	s_nop 9
	v_fmac_f32_e32 v51, v78, v50
	v_fmac_f32_e32 v35, v74, v34
	v_fmac_f32_e32 v3, v80, v50
	v_fmac_f32_e32 v19, v76, v34
	v_fma_f32 v51, -v80, v2, v51
	v_fma_f32 v35, -v76, v18, v35
	v_fmac_f32_e32 v3, v78, v2
	v_fmac_f32_e32 v19, v74, v18
	v_fmac_f32_e32 v52, v78, v51
	v_fmac_f32_e32 v36, v74, v35
	v_fmac_f32_e32 v4, v80, v51
	v_fmac_f32_e32 v20, v76, v35
	v_fma_f32 v52, -v80, v3, v52
	v_fma_f32 v36, -v76, v19, v36
	v_fmac_f32_e32 v4, v78, v3
	v_fmac_f32_e32 v20, v74, v19
	v_fmac_f32_e32 v53, v78, v52
	v_fmac_f32_e32 v37, v74, v36
	v_fmac_f32_e32 v5, v80, v52
	v_fmac_f32_e32 v21, v76, v36
	v_fma_f32 v53, -v80, v4, v53
	v_fma_f32 v37, -v76, v20, v37
	v_fmac_f32_e32 v5, v78, v4
	v_fmac_f32_e32 v21, v74, v20
	v_fmac_f32_e32 v54, v78, v53
	v_fmac_f32_e32 v38, v74, v37
	v_fmac_f32_e32 v6, v80, v53
	v_fmac_f32_e32 v22, v76, v37
	v_fma_f32 v54, -v80, v5, v54
	v_fma_f32 v38, -v76, v21, v38
	v_fmac_f32_e32 v6, v78, v5
	v_fmac_f32_e32 v22, v74, v21
	v_fmac_f32_e32 v55, v78, v54
	v_fmac_f32_e32 v39, v74, v38
	v_fmac_f32_e32 v7, v80, v54
	v_fmac_f32_e32 v23, v76, v38
	v_fma_f32 v55, -v80, v6, v55
	v_fma_f32 v39, -v76, v22, v39
	v_fmac_f32_e32 v7, v78, v6
	v_fmac_f32_e32 v23, v74, v22
	v_fmac_f32_e32 v56, v78, v55
	v_fmac_f32_e32 v40, v74, v39
	v_fmac_f32_e32 v8, v80, v55
	v_fmac_f32_e32 v24, v76, v39
	v_fma_f32 v56, -v80, v7, v56
	v_fma_f32 v40, -v76, v23, v40
	v_fmac_f32_e32 v8, v78, v7
	v_fmac_f32_e32 v24, v74, v23
	v_fmac_f32_e32 v57, v78, v56
	v_fmac_f32_e32 v41, v74, v40
	v_fmac_f32_e32 v9, v80, v56
	v_fmac_f32_e32 v25, v76, v40
	v_fma_f32 v57, -v80, v8, v57
	v_fma_f32 v41, -v76, v24, v41
	v_fmac_f32_e32 v9, v78, v8
	v_fmac_f32_e32 v25, v74, v24
	v_fmac_f32_e32 v58, v78, v57
	v_fmac_f32_e32 v42, v74, v41
	v_fmac_f32_e32 v10, v80, v57
	v_fmac_f32_e32 v26, v76, v41
	v_fma_f32 v58, -v80, v9, v58
	v_fma_f32 v42, -v76, v25, v42
	v_fmac_f32_e32 v10, v78, v9
	v_fmac_f32_e32 v26, v74, v25
	v_fmac_f32_e32 v59, v78, v58
	v_fmac_f32_e32 v43, v74, v42
	v_fmac_f32_e32 v11, v80, v58
	v_fmac_f32_e32 v27, v76, v42
	v_fma_f32 v59, -v80, v10, v59
	v_fma_f32 v43, -v76, v26, v43
	v_fmac_f32_e32 v11, v78, v10
	v_fmac_f32_e32 v27, v74, v26
	v_fmac_f32_e32 v60, v78, v59
	v_fmac_f32_e32 v44, v74, v43
	v_fmac_f32_e32 v12, v80, v59
	v_fmac_f32_e32 v28, v76, v43
	v_fma_f32 v60, -v80, v11, v60
	v_fma_f32 v44, -v76, v27, v44
	v_fmac_f32_e32 v12, v78, v11
	v_fmac_f32_e32 v28, v74, v27
	v_fmac_f32_e32 v61, v78, v60
	v_fmac_f32_e32 v45, v74, v44
	v_fmac_f32_e32 v13, v80, v60
	v_fmac_f32_e32 v29, v76, v44
	v_fma_f32 v61, -v80, v12, v61
	v_fma_f32 v45, -v76, v28, v45
	v_fmac_f32_e32 v13, v78, v12
	v_fmac_f32_e32 v29, v74, v28
	v_fmac_f32_e32 v62, v78, v61
	v_fmac_f32_e32 v46, v74, v45
	v_fmac_f32_e32 v14, v80, v61
	v_fmac_f32_e32 v30, v76, v45
	v_fma_f32 v62, -v80, v13, v62
	v_fma_f32 v46, -v76, v29, v46
	v_fmac_f32_e32 v14, v78, v13
	v_fmac_f32_e32 v30, v74, v29
	v_fmac_f32_e32 v63, v78, v62
	v_fmac_f32_e32 v47, v74, v46
	v_fmac_f32_e32 v15, v80, v62
	v_fmac_f32_e32 v31, v76, v46
	v_fma_f32 v63, -v80, v14, v63
	v_fma_f32 v47, -v76, v30, v47
	v_fmac_f32_e32 v15, v78, v14
	v_fmac_f32_e32 v31, v74, v30
	v_fmac_f32_e32 v64, v78, v63
	v_fmac_f32_e32 v48, v74, v47
	v_fmac_f32_e32 v16, v80, v63
	v_fmac_f32_e32 v32, v76, v47
	v_fma_f32 v64, -v80, v15, v64
	v_fma_f32 v48, -v76, v31, v48
	v_fmac_f32_e32 v16, v78, v15
	v_fmac_f32_e32 v32, v74, v31
	v_fmac_f32_e32 v65, v78, v64
	v_fmac_f32_e32 v49, v74, v48
	v_fmac_f32_e32 v17, v80, v64
	v_fmac_f32_e32 v33, v76, v48
	v_fma_f32 v65, -v80, v16, v65
	v_fma_f32 v49, -v76, v32, v49
	v_fmac_f32_e32 v17, v78, v16
	v_fmac_f32_e32 v33, v74, v32
	v_mov_b32_e32 v156, v65
	v_mov_b32_e32 v157, v17
	v_mov_b32_e32 v158, v65
	v_mov_b32_e32 v159, v17
	s_nop 1
	v_permlane32_swap_b32_e32 v156, v158
	v_permlane32_swap_b32_e32 v157, v159
	v_pk_fma_f32 v[164:165], v[166:167], v[152:153], v[156:157] op_sel_hi:[1,0,1]
	v_pk_fma_f32 v[164:165], v[166:167], v[152:153], v[164:165] op_sel:[1,1,0] op_sel_hi:[0,1,1] neg_lo:[0,1,0]
	v_cndmask_b32_e32 v164, v166, v164, vcc
	v_cndmask_b32_e32 v165, v167, v165, vcc
	v_mov_b32_e32 v156, v49
	v_mov_b32_e32 v157, v33
	v_mov_b32_e32 v158, v49
	v_mov_b32_e32 v159, v33
	s_nop 1
	v_permlane32_swap_b32_e32 v156, v158
	v_permlane32_swap_b32_e32 v157, v159
	v_pk_fma_f32 v[170:171], v[150:151], v[154:155], v[156:157] op_sel_hi:[1,0,1]
	v_pk_fma_f32 v[170:171], v[150:151], v[154:155], v[170:171] op_sel:[1,1,0] op_sel_hi:[0,1,1] neg_lo:[0,1,0]
	v_cndmask_b32_e32 v170, v150, v170, vcc
	v_cndmask_b32_e32 v171, v151, v171, vcc
	v_pk_mul_f32 v[168:169], v[164:165], v[70:71] op_sel:[0,1] op_sel_hi:[1,1]
	v_pk_mul_f32 v[172:173], v[170:171], v[66:67] op_sel:[0,1] op_sel_hi:[1,1]
	v_pk_fma_f32 v[168:169], v[164:165], v[72:73], v[168:169] op_sel:[1,1,0] op_sel_hi:[0,1,1] neg_lo:[0,1,0]
	v_pk_fma_f32 v[172:173], v[170:171], v[68:69], v[172:173] op_sel:[1,1,0] op_sel_hi:[0,1,1] neg_lo:[0,1,0]
	v_pk_fma_f32 v[50:51], v[78:79], v[164:165], v[50:51] op_sel_hi:[1,0,1]
	v_pk_fma_f32 v[34:35], v[74:75], v[170:171], v[34:35] op_sel_hi:[1,0,1]
	v_pk_fma_f32 v[52:53], v[70:71], v[164:165], v[52:53] op_sel_hi:[1,0,1]
	v_pk_fma_f32 v[36:37], v[66:67], v[170:171], v[36:37] op_sel_hi:[1,0,1]
	v_pk_fma_f32 v[2:3], v[80:81], v[164:165], v[2:3] op_sel_hi:[1,0,1]
	v_pk_fma_f32 v[18:19], v[76:77], v[170:171], v[18:19] op_sel_hi:[1,0,1]
	v_pk_fma_f32 v[4:5], v[72:73], v[164:165], v[4:5] op_sel_hi:[1,0,1]
	v_pk_fma_f32 v[20:21], v[68:69], v[170:171], v[20:21] op_sel_hi:[1,0,1]
	v_pk_fma_f32 v[50:51], v[80:81], v[164:165], v[50:51] op_sel:[0,1,0] op_sel_hi:[1,1,1] neg_lo:[0,1,0] neg_hi:[0,1,0]
	v_pk_fma_f32 v[34:35], v[76:77], v[170:171], v[34:35] op_sel:[0,1,0] op_sel_hi:[1,1,1] neg_lo:[0,1,0] neg_hi:[0,1,0]
	v_pk_fma_f32 v[52:53], v[72:73], v[164:165], v[52:53] op_sel:[0,1,0] op_sel_hi:[1,1,1] neg_lo:[0,1,0] neg_hi:[0,1,0]
	v_pk_fma_f32 v[36:37], v[68:69], v[170:171], v[36:37] op_sel:[0,1,0] op_sel_hi:[1,1,1] neg_lo:[0,1,0] neg_hi:[0,1,0]
	v_pk_fma_f32 v[2:3], v[78:79], v[164:165], v[2:3] op_sel:[0,1,0] op_sel_hi:[1,1,1]
	v_pk_fma_f32 v[18:19], v[74:75], v[170:171], v[18:19] op_sel:[0,1,0] op_sel_hi:[1,1,1]
	v_pk_fma_f32 v[4:5], v[70:71], v[164:165], v[4:5] op_sel:[0,1,0] op_sel_hi:[1,1,1]
	v_pk_fma_f32 v[20:21], v[66:67], v[170:171], v[20:21] op_sel:[0,1,0] op_sel_hi:[1,1,1]
	v_pk_mul_f32 v[164:165], v[168:169], v[70:71] op_sel:[0,1] op_sel_hi:[1,1]
	v_pk_mul_f32 v[170:171], v[172:173], v[66:67] op_sel:[0,1] op_sel_hi:[1,1]
	v_pk_fma_f32 v[164:165], v[168:169], v[72:73], v[164:165] op_sel:[1,1,0] op_sel_hi:[0,1,1] neg_lo:[0,1,0]
	v_pk_fma_f32 v[170:171], v[172:173], v[68:69], v[170:171] op_sel:[1,1,0] op_sel_hi:[0,1,1] neg_lo:[0,1,0]
	v_pk_fma_f32 v[54:55], v[78:79], v[168:169], v[54:55] op_sel_hi:[1,0,1]
	v_pk_fma_f32 v[38:39], v[74:75], v[172:173], v[38:39] op_sel_hi:[1,0,1]
	v_pk_fma_f32 v[56:57], v[70:71], v[168:169], v[56:57] op_sel_hi:[1,0,1]
	v_pk_fma_f32 v[40:41], v[66:67], v[172:173], v[40:41] op_sel_hi:[1,0,1]
	v_pk_fma_f32 v[6:7], v[80:81], v[168:169], v[6:7] op_sel_hi:[1,0,1]
	v_pk_fma_f32 v[22:23], v[76:77], v[172:173], v[22:23] op_sel_hi:[1,0,1]
	v_pk_fma_f32 v[8:9], v[72:73], v[168:169], v[8:9] op_sel_hi:[1,0,1]
	v_pk_fma_f32 v[24:25], v[68:69], v[172:173], v[24:25] op_sel_hi:[1,0,1]
	v_pk_fma_f32 v[54:55], v[80:81], v[168:169], v[54:55] op_sel:[0,1,0] op_sel_hi:[1,1,1] neg_lo:[0,1,0] neg_hi:[0,1,0]
	v_pk_fma_f32 v[38:39], v[76:77], v[172:173], v[38:39] op_sel:[0,1,0] op_sel_hi:[1,1,1] neg_lo:[0,1,0] neg_hi:[0,1,0]
	v_pk_fma_f32 v[56:57], v[72:73], v[168:169], v[56:57] op_sel:[0,1,0] op_sel_hi:[1,1,1] neg_lo:[0,1,0] neg_hi:[0,1,0]
	v_pk_fma_f32 v[40:41], v[68:69], v[172:173], v[40:41] op_sel:[0,1,0] op_sel_hi:[1,1,1] neg_lo:[0,1,0] neg_hi:[0,1,0]
	v_pk_fma_f32 v[6:7], v[78:79], v[168:169], v[6:7] op_sel:[0,1,0] op_sel_hi:[1,1,1]
	v_pk_fma_f32 v[22:23], v[74:75], v[172:173], v[22:23] op_sel:[0,1,0] op_sel_hi:[1,1,1]
	v_pk_fma_f32 v[8:9], v[70:71], v[168:169], v[8:9] op_sel:[0,1,0] op_sel_hi:[1,1,1]
	v_pk_fma_f32 v[24:25], v[66:67], v[172:173], v[24:25] op_sel:[0,1,0] op_sel_hi:[1,1,1]
	v_pk_mul_f32 v[168:169], v[164:165], v[70:71] op_sel:[0,1] op_sel_hi:[1,1]
	v_pk_mul_f32 v[172:173], v[170:171], v[66:67] op_sel:[0,1] op_sel_hi:[1,1]
	v_pk_fma_f32 v[168:169], v[164:165], v[72:73], v[168:169] op_sel:[1,1,0] op_sel_hi:[0,1,1] neg_lo:[0,1,0]
	v_pk_fma_f32 v[172:173], v[170:171], v[68:69], v[172:173] op_sel:[1,1,0] op_sel_hi:[0,1,1] neg_lo:[0,1,0]
	v_pk_fma_f32 v[58:59], v[78:79], v[164:165], v[58:59] op_sel_hi:[1,0,1]
	v_pk_fma_f32 v[42:43], v[74:75], v[170:171], v[42:43] op_sel_hi:[1,0,1]
	v_pk_fma_f32 v[60:61], v[70:71], v[164:165], v[60:61] op_sel_hi:[1,0,1]
	v_pk_fma_f32 v[44:45], v[66:67], v[170:171], v[44:45] op_sel_hi:[1,0,1]
	v_pk_fma_f32 v[10:11], v[80:81], v[164:165], v[10:11] op_sel_hi:[1,0,1]
	v_pk_fma_f32 v[26:27], v[76:77], v[170:171], v[26:27] op_sel_hi:[1,0,1]
	v_pk_fma_f32 v[12:13], v[72:73], v[164:165], v[12:13] op_sel_hi:[1,0,1]
	v_pk_fma_f32 v[28:29], v[68:69], v[170:171], v[28:29] op_sel_hi:[1,0,1]
	v_pk_fma_f32 v[58:59], v[80:81], v[164:165], v[58:59] op_sel:[0,1,0] op_sel_hi:[1,1,1] neg_lo:[0,1,0] neg_hi:[0,1,0]
	v_pk_fma_f32 v[42:43], v[76:77], v[170:171], v[42:43] op_sel:[0,1,0] op_sel_hi:[1,1,1] neg_lo:[0,1,0] neg_hi:[0,1,0]
	v_pk_fma_f32 v[60:61], v[72:73], v[164:165], v[60:61] op_sel:[0,1,0] op_sel_hi:[1,1,1] neg_lo:[0,1,0] neg_hi:[0,1,0]
	v_pk_fma_f32 v[44:45], v[68:69], v[170:171], v[44:45] op_sel:[0,1,0] op_sel_hi:[1,1,1] neg_lo:[0,1,0] neg_hi:[0,1,0]
	v_pk_fma_f32 v[10:11], v[78:79], v[164:165], v[10:11] op_sel:[0,1,0] op_sel_hi:[1,1,1]
	v_pk_fma_f32 v[26:27], v[74:75], v[170:171], v[26:27] op_sel:[0,1,0] op_sel_hi:[1,1,1]
	v_pk_fma_f32 v[12:13], v[70:71], v[164:165], v[12:13] op_sel:[0,1,0] op_sel_hi:[1,1,1]
	v_pk_fma_f32 v[28:29], v[66:67], v[170:171], v[28:29] op_sel:[0,1,0] op_sel_hi:[1,1,1]
	v_pk_fma_f32 v[62:63], v[78:79], v[168:169], v[62:63] op_sel_hi:[1,0,1]
	v_pk_fma_f32 v[46:47], v[74:75], v[172:173], v[46:47] op_sel_hi:[1,0,1]
	v_pk_fma_f32 v[64:65], v[70:71], v[168:169], v[64:65] op_sel_hi:[1,0,1]
	v_pk_fma_f32 v[48:49], v[66:67], v[172:173], v[48:49] op_sel_hi:[1,0,1]
	v_pk_fma_f32 v[14:15], v[80:81], v[168:169], v[14:15] op_sel_hi:[1,0,1]
	v_pk_fma_f32 v[30:31], v[76:77], v[172:173], v[30:31] op_sel_hi:[1,0,1]
	v_pk_fma_f32 v[16:17], v[72:73], v[168:169], v[16:17] op_sel_hi:[1,0,1]
	v_pk_fma_f32 v[32:33], v[68:69], v[172:173], v[32:33] op_sel_hi:[1,0,1]
	v_pk_fma_f32 v[62:63], v[80:81], v[168:169], v[62:63] op_sel:[0,1,0] op_sel_hi:[1,1,1] neg_lo:[0,1,0] neg_hi:[0,1,0]
	v_pk_fma_f32 v[46:47], v[76:77], v[172:173], v[46:47] op_sel:[0,1,0] op_sel_hi:[1,1,1] neg_lo:[0,1,0] neg_hi:[0,1,0]
	v_pk_fma_f32 v[64:65], v[72:73], v[168:169], v[64:65] op_sel:[0,1,0] op_sel_hi:[1,1,1] neg_lo:[0,1,0] neg_hi:[0,1,0]
	v_pk_fma_f32 v[48:49], v[68:69], v[172:173], v[48:49] op_sel:[0,1,0] op_sel_hi:[1,1,1] neg_lo:[0,1,0] neg_hi:[0,1,0]
	v_pk_fma_f32 v[14:15], v[78:79], v[168:169], v[14:15] op_sel:[0,1,0] op_sel_hi:[1,1,1]
	v_pk_fma_f32 v[30:31], v[74:75], v[172:173], v[30:31] op_sel:[0,1,0] op_sel_hi:[1,1,1]
	v_pk_fma_f32 v[16:17], v[70:71], v[168:169], v[16:17] op_sel:[0,1,0] op_sel_hi:[1,1,1]
	v_pk_fma_f32 v[32:33], v[66:67], v[172:173], v[32:33] op_sel:[0,1,0] op_sel_hi:[1,1,1]
	v_mov_b32_e32 v156, v65
	v_mov_b32_e32 v157, v17
	v_mov_b32_e32 v166, v65
	v_mov_b32_e32 v167, v17
	s_nop 1
	v_permlane32_swap_b32_e32 v156, v166
	v_permlane32_swap_b32_e32 v157, v167
	v_mov_b32_e32 v156, v49
	v_mov_b32_e32 v157, v33
	v_mov_b32_e32 v150, v49
	v_mov_b32_e32 v151, v33
	s_nop 1
	v_permlane32_swap_b32_e32 v156, v150
	v_permlane32_swap_b32_e32 v157, v151
	v_cvt_pk_bf16_f32 v1, v50, v2
	ds_write_b32 v174, v1
	v_cvt_pk_bf16_f32 v146, v34, v18
	ds_write_b32 v174, v146 offset:128
	v_cvt_pk_bf16_f32 v178, v51, v3
	ds_write_b32 v174, v178 offset:272
	v_cvt_pk_bf16_f32 v1, v35, v19
	ds_write_b32 v174, v1 offset:400
	v_cvt_pk_bf16_f32 v146, v52, v4
	ds_write_b32 v174, v146 offset:544
	v_cvt_pk_bf16_f32 v178, v36, v20
	ds_write_b32 v174, v178 offset:672
	v_cvt_pk_bf16_f32 v1, v53, v5
	ds_write_b32 v174, v1 offset:816
	v_cvt_pk_bf16_f32 v146, v37, v21
	ds_write_b32 v174, v146 offset:944
	v_cvt_pk_bf16_f32 v178, v54, v6
	ds_write_b32 v174, v178 offset:1088
	v_cvt_pk_bf16_f32 v1, v38, v22
	ds_write_b32 v174, v1 offset:1216
	v_cvt_pk_bf16_f32 v146, v55, v7
	ds_write_b32 v174, v146 offset:1360
	v_cvt_pk_bf16_f32 v178, v39, v23
	ds_write_b32 v174, v178 offset:1488
	v_cvt_pk_bf16_f32 v1, v56, v8
	ds_write_b32 v174, v1 offset:1632
	v_cvt_pk_bf16_f32 v146, v40, v24
	ds_write_b32 v174, v146 offset:1760
	v_cvt_pk_bf16_f32 v178, v57, v9
	ds_write_b32 v174, v178 offset:1904
	v_cvt_pk_bf16_f32 v1, v41, v25
	ds_write_b32 v174, v1 offset:2032
	v_cvt_pk_bf16_f32 v146, v58, v10
	ds_write_b32 v174, v146 offset:2176
	v_cvt_pk_bf16_f32 v178, v42, v26
	ds_write_b32 v174, v178 offset:2304
	v_cvt_pk_bf16_f32 v1, v59, v11
	ds_write_b32 v174, v1 offset:2448
	v_cvt_pk_bf16_f32 v146, v43, v27
	ds_write_b32 v174, v146 offset:2576
	v_cvt_pk_bf16_f32 v178, v60, v12
	ds_write_b32 v174, v178 offset:2720
	v_cvt_pk_bf16_f32 v1, v44, v28
	ds_write_b32 v174, v1 offset:2848
	v_cvt_pk_bf16_f32 v146, v61, v13
	ds_write_b32 v174, v146 offset:2992
	v_cvt_pk_bf16_f32 v178, v45, v29
	ds_write_b32 v174, v178 offset:3120
	v_cvt_pk_bf16_f32 v1, v62, v14
	ds_write_b32 v174, v1 offset:3264
	v_cvt_pk_bf16_f32 v146, v46, v30
	ds_write_b32 v174, v146 offset:3392
	v_cvt_pk_bf16_f32 v178, v63, v15
	ds_write_b32 v174, v178 offset:3536
	v_cvt_pk_bf16_f32 v1, v47, v31
	ds_write_b32 v174, v1 offset:3664
	v_cvt_pk_bf16_f32 v146, v64, v16
	ds_write_b32 v174, v146 offset:3808
	v_cvt_pk_bf16_f32 v178, v48, v32
	ds_write_b32 v174, v178 offset:3936
	v_cvt_pk_bf16_f32 v1, v65, v17
	ds_write_b32 v174, v1 offset:4080
	v_cvt_pk_bf16_f32 v146, v49, v33
	ds_write_b32 v174, v146 offset:4208
	s_waitcnt lgkmcnt(0)
	ds_read_b128 v[2:5], v175
	ds_read_b128 v[6:9], v175 offset:64
	ds_read_b128 v[10:13], v175 offset:128
	ds_read_b128 v[14:17], v175 offset:192
	ds_read_b128 v[18:21], v175 offset:4352
	ds_read_b128 v[22:25], v175 offset:4416
	ds_read_b128 v[26:29], v175 offset:4480
	ds_read_b128 v[30:33], v175 offset:4544
	s_waitcnt vmcnt(0)
	s_waitcnt lgkmcnt(7)
	v_mfma_f32_16x16x32_bf16 v[34:37], v[94:97], v[2:5], 0
	s_waitcnt lgkmcnt(6)
	v_mfma_f32_16x16x32_bf16 v[34:37], v[90:93], v[6:9], v[34:37]
	s_waitcnt lgkmcnt(5)
	v_mfma_f32_16x16x32_bf16 v[34:37], v[86:89], v[10:13], v[34:37]
	s_waitcnt lgkmcnt(4)
	v_mfma_f32_16x16x32_bf16 v[34:37], v[82:85], v[14:17], v[34:37]
	s_waitcnt lgkmcnt(3)
	v_mfma_f32_16x16x32_bf16 v[38:41], v[94:97], v[18:21], 0
	s_waitcnt lgkmcnt(2)
	v_mfma_f32_16x16x32_bf16 v[38:41], v[90:93], v[22:25], v[38:41]
	s_waitcnt lgkmcnt(1)
	v_mfma_f32_16x16x32_bf16 v[38:41], v[86:89], v[26:29], v[38:41]
	s_waitcnt lgkmcnt(0)
	v_mfma_f32_16x16x32_bf16 v[38:41], v[82:85], v[30:33], v[38:41]
	s_add_u32 s6, s6, 0x8000
	s_addc_u32 s7, s7, 0
	v_lshlrev_b32_e32 v42, 16, v160
	v_and_b32_e32 v43, 0xffff0000, v160
	v_lshlrev_b32_e32 v44, 16, v161
	v_and_b32_e32 v45, 0xffff0000, v161
	v_lshlrev_b32_e32 v46, 16, v162
	v_and_b32_e32 v47, 0xffff0000, v162
	v_lshlrev_b32_e32 v48, 16, v163
	v_and_b32_e32 v49, 0xffff0000, v163
	s_nop 1
	v_mov_b32_e32 v156, 0x3d372713
	v_mov_b32_e32 v158, 0xbfcc422a
	v_mov_b32_e32 v164, 0x3fb8aa3b
	v_mov_b32_e32 v168, 1.0
	v_pk_fma_f32 v[50:51], v[98:99], v[42:43], v[34:35]
	v_pk_fma_f32 v[52:53], v[100:101], v[44:45], v[36:37]
	v_pk_fma_f32 v[54:55], v[98:99], v[46:47], v[38:39]
	v_pk_fma_f32 v[56:57], v[100:101], v[48:49], v[40:41]
	v_pk_mul_f32 v[2:3], v[50:51], v[156:157] op_sel_hi:[1,0]
	v_pk_mul_f32 v[4:5], v[52:53], v[156:157] op_sel_hi:[1,0]
	v_pk_mul_f32 v[6:7], v[54:55], v[156:157] op_sel_hi:[1,0]
	v_pk_mul_f32 v[8:9], v[56:57], v[156:157] op_sel_hi:[1,0]
	v_pk_mul_f32 v[2:3], v[50:51], v[2:3]
	v_pk_mul_f32 v[4:5], v[52:53], v[4:5]
	v_pk_mul_f32 v[6:7], v[54:55], v[6:7]
	v_pk_mul_f32 v[8:9], v[56:57], v[8:9]
	v_pk_fma_f32 v[2:3], v[50:51], v[2:3], v[50:51]
	v_pk_fma_f32 v[4:5], v[52:53], v[4:5], v[52:53]
	v_pk_fma_f32 v[6:7], v[54:55], v[6:7], v[54:55]
	v_pk_fma_f32 v[8:9], v[56:57], v[8:9], v[56:57]
	v_pk_mul_f32 v[2:3], v[2:3], v[158:159] op_sel_hi:[1,0]
	v_pk_mul_f32 v[4:5], v[4:5], v[158:159] op_sel_hi:[1,0]
	v_pk_mul_f32 v[6:7], v[6:7], v[158:159] op_sel_hi:[1,0]
	v_pk_mul_f32 v[8:9], v[8:9], v[158:159] op_sel_hi:[1,0]
	v_pk_mul_f32 v[2:3], v[2:3], v[164:165] op_sel_hi:[1,0]
	v_pk_mul_f32 v[4:5], v[4:5], v[164:165] op_sel_hi:[1,0]
	v_pk_mul_f32 v[6:7], v[6:7], v[164:165] op_sel_hi:[1,0]
	v_pk_mul_f32 v[8:9], v[8:9], v[164:165] op_sel_hi:[1,0]
	v_exp_f32_e32 v2, v2
	v_exp_f32_e32 v3, v3
	v_exp_f32_e32 v4, v4
	v_exp_f32_e32 v5, v5
	v_exp_f32_e32 v6, v6
	v_exp_f32_e32 v7, v7
	v_exp_f32_e32 v8, v8
	v_exp_f32_e32 v9, v9
	v_pk_add_f32 v[2:3], v[2:3], v[168:169] op_sel_hi:[1,0]
	v_pk_add_f32 v[4:5], v[4:5], v[168:169] op_sel_hi:[1,0]
	v_pk_add_f32 v[6:7], v[6:7], v[168:169] op_sel_hi:[1,0]
	v_pk_add_f32 v[8:9], v[8:9], v[168:169] op_sel_hi:[1,0]
	v_rcp_f32_e32 v2, v2
	v_rcp_f32_e32 v3, v3
	v_rcp_f32_e32 v4, v4
	v_rcp_f32_e32 v5, v5
	v_rcp_f32_e32 v6, v6
	v_rcp_f32_e32 v7, v7
	v_rcp_f32_e32 v8, v8
	v_rcp_f32_e32 v9, v9
	v_pk_mul_f32 v[50:51], v[50:51], v[2:3]
	v_pk_mul_f32 v[52:53], v[52:53], v[4:5]
	v_pk_mul_f32 v[54:55], v[54:55], v[6:7]
	v_pk_mul_f32 v[56:57], v[56:57], v[8:9]
	v_cvt_pk_bf16_f32 v10, v50, v51
	v_cvt_pk_bf16_f32 v11, v52, v53
	v_cvt_pk_bf16_f32 v12, v54, v55
	v_cvt_pk_bf16_f32 v13, v56, v57
	global_store_dwordx2 v176, v[10:11], s[10:11]
	global_store_dwordx2 v177, v[12:13], s[10:11]
	s_add_u32 s10, s10, 0x8000
	s_addc_u32 s11, s11, 0
	s_nop 0
	v_mfma_f32_32x32x16_bf16 v[50:65], v[134:137], v[114:117], 0
	v_mfma_f32_32x32x16_bf16 v[2:17], v[134:137], v[110:113], 0
	v_mfma_f32_32x32x16_bf16 v[34:49], v[134:137], v[106:109], 0
	v_mfma_f32_32x32x16_bf16 v[18:33], v[134:137], v[102:105], 0
	global_load_dwordx2 v[160:161], v176, s[6:7]
	global_load_dwordx2 v[162:163], v177, s[6:7]
	s_nop 9
	v_fmac_f32_e32 v51, v78, v50
	v_fmac_f32_e32 v35, v74, v34
	v_fmac_f32_e32 v3, v80, v50
	v_fmac_f32_e32 v19, v76, v34
	v_fma_f32 v51, -v80, v2, v51
	v_fma_f32 v35, -v76, v18, v35
	v_fmac_f32_e32 v3, v78, v2
	v_fmac_f32_e32 v19, v74, v18
	v_fmac_f32_e32 v52, v78, v51
	v_fmac_f32_e32 v36, v74, v35
	v_fmac_f32_e32 v4, v80, v51
	v_fmac_f32_e32 v20, v76, v35
	v_fma_f32 v52, -v80, v3, v52
	v_fma_f32 v36, -v76, v19, v36
	v_fmac_f32_e32 v4, v78, v3
	v_fmac_f32_e32 v20, v74, v19
	v_fmac_f32_e32 v53, v78, v52
	v_fmac_f32_e32 v37, v74, v36
	v_fmac_f32_e32 v5, v80, v52
	v_fmac_f32_e32 v21, v76, v36
	v_fma_f32 v53, -v80, v4, v53
	v_fma_f32 v37, -v76, v20, v37
	v_fmac_f32_e32 v5, v78, v4
	v_fmac_f32_e32 v21, v74, v20
	v_fmac_f32_e32 v54, v78, v53
	v_fmac_f32_e32 v38, v74, v37
	v_fmac_f32_e32 v6, v80, v53
	v_fmac_f32_e32 v22, v76, v37
	v_fma_f32 v54, -v80, v5, v54
	v_fma_f32 v38, -v76, v21, v38
	v_fmac_f32_e32 v6, v78, v5
	v_fmac_f32_e32 v22, v74, v21
	v_fmac_f32_e32 v55, v78, v54
	v_fmac_f32_e32 v39, v74, v38
	v_fmac_f32_e32 v7, v80, v54
	v_fmac_f32_e32 v23, v76, v38
	v_fma_f32 v55, -v80, v6, v55
	v_fma_f32 v39, -v76, v22, v39
	v_fmac_f32_e32 v7, v78, v6
	v_fmac_f32_e32 v23, v74, v22
	v_fmac_f32_e32 v56, v78, v55
	v_fmac_f32_e32 v40, v74, v39
	v_fmac_f32_e32 v8, v80, v55
	v_fmac_f32_e32 v24, v76, v39
	v_fma_f32 v56, -v80, v7, v56
	v_fma_f32 v40, -v76, v23, v40
	v_fmac_f32_e32 v8, v78, v7
	v_fmac_f32_e32 v24, v74, v23
	v_fmac_f32_e32 v57, v78, v56
	v_fmac_f32_e32 v41, v74, v40
	v_fmac_f32_e32 v9, v80, v56
	v_fmac_f32_e32 v25, v76, v40
	v_fma_f32 v57, -v80, v8, v57
	v_fma_f32 v41, -v76, v24, v41
	v_fmac_f32_e32 v9, v78, v8
	v_fmac_f32_e32 v25, v74, v24
	v_fmac_f32_e32 v58, v78, v57
	v_fmac_f32_e32 v42, v74, v41
	v_fmac_f32_e32 v10, v80, v57
	v_fmac_f32_e32 v26, v76, v41
	v_fma_f32 v58, -v80, v9, v58
	v_fma_f32 v42, -v76, v25, v42
	v_fmac_f32_e32 v10, v78, v9
	v_fmac_f32_e32 v26, v74, v25
	v_fmac_f32_e32 v59, v78, v58
	v_fmac_f32_e32 v43, v74, v42
	v_fmac_f32_e32 v11, v80, v58
	v_fmac_f32_e32 v27, v76, v42
	v_fma_f32 v59, -v80, v10, v59
	v_fma_f32 v43, -v76, v26, v43
	v_fmac_f32_e32 v11, v78, v10
	v_fmac_f32_e32 v27, v74, v26
	v_fmac_f32_e32 v60, v78, v59
	v_fmac_f32_e32 v44, v74, v43
	v_fmac_f32_e32 v12, v80, v59
	v_fmac_f32_e32 v28, v76, v43
	v_fma_f32 v60, -v80, v11, v60
	v_fma_f32 v44, -v76, v27, v44
	v_fmac_f32_e32 v12, v78, v11
	v_fmac_f32_e32 v28, v74, v27
	v_fmac_f32_e32 v61, v78, v60
	v_fmac_f32_e32 v45, v74, v44
	v_fmac_f32_e32 v13, v80, v60
	v_fmac_f32_e32 v29, v76, v44
	v_fma_f32 v61, -v80, v12, v61
	v_fma_f32 v45, -v76, v28, v45
	v_fmac_f32_e32 v13, v78, v12
	v_fmac_f32_e32 v29, v74, v28
	v_fmac_f32_e32 v62, v78, v61
	v_fmac_f32_e32 v46, v74, v45
	v_fmac_f32_e32 v14, v80, v61
	v_fmac_f32_e32 v30, v76, v45
	v_fma_f32 v62, -v80, v13, v62
	v_fma_f32 v46, -v76, v29, v46
	v_fmac_f32_e32 v14, v78, v13
	v_fmac_f32_e32 v30, v74, v29
	v_fmac_f32_e32 v63, v78, v62
	v_fmac_f32_e32 v47, v74, v46
	v_fmac_f32_e32 v15, v80, v62
	v_fmac_f32_e32 v31, v76, v46
	v_fma_f32 v63, -v80, v14, v63
	v_fma_f32 v47, -v76, v30, v47
	v_fmac_f32_e32 v15, v78, v14
	v_fmac_f32_e32 v31, v74, v30
	v_fmac_f32_e32 v64, v78, v63
	v_fmac_f32_e32 v48, v74, v47
	v_fmac_f32_e32 v16, v80, v63
	v_fmac_f32_e32 v32, v76, v47
	v_fma_f32 v64, -v80, v15, v64
	v_fma_f32 v48, -v76, v31, v48
	v_fmac_f32_e32 v16, v78, v15
	v_fmac_f32_e32 v32, v74, v31
	v_fmac_f32_e32 v65, v78, v64
	v_fmac_f32_e32 v49, v74, v48
	v_fmac_f32_e32 v17, v80, v64
	v_fmac_f32_e32 v33, v76, v48
	v_fma_f32 v65, -v80, v16, v65
	v_fma_f32 v49, -v76, v32, v49
	v_fmac_f32_e32 v17, v78, v16
	v_fmac_f32_e32 v33, v74, v32
	v_mov_b32_e32 v156, v65
	v_mov_b32_e32 v157, v17
	v_mov_b32_e32 v158, v65
	v_mov_b32_e32 v159, v17
	s_nop 1
	v_permlane32_swap_b32_e32 v156, v158
	v_permlane32_swap_b32_e32 v157, v159
	v_pk_fma_f32 v[164:165], v[166:167], v[152:153], v[156:157] op_sel_hi:[1,0,1]
	v_pk_fma_f32 v[164:165], v[166:167], v[152:153], v[164:165] op_sel:[1,1,0] op_sel_hi:[0,1,1] neg_lo:[0,1,0]
	v_cndmask_b32_e32 v164, v166, v164, vcc
	v_cndmask_b32_e32 v165, v167, v165, vcc
	v_mov_b32_e32 v156, v49
	v_mov_b32_e32 v157, v33
	v_mov_b32_e32 v158, v49
	v_mov_b32_e32 v159, v33
	s_nop 1
	v_permlane32_swap_b32_e32 v156, v158
	v_permlane32_swap_b32_e32 v157, v159
	v_pk_fma_f32 v[170:171], v[150:151], v[154:155], v[156:157] op_sel_hi:[1,0,1]
	v_pk_fma_f32 v[170:171], v[150:151], v[154:155], v[170:171] op_sel:[1,1,0] op_sel_hi:[0,1,1] neg_lo:[0,1,0]
	v_cndmask_b32_e32 v170, v150, v170, vcc
	v_cndmask_b32_e32 v171, v151, v171, vcc
	v_pk_mul_f32 v[168:169], v[164:165], v[70:71] op_sel:[0,1] op_sel_hi:[1,1]
	v_pk_mul_f32 v[172:173], v[170:171], v[66:67] op_sel:[0,1] op_sel_hi:[1,1]
	v_pk_fma_f32 v[168:169], v[164:165], v[72:73], v[168:169] op_sel:[1,1,0] op_sel_hi:[0,1,1] neg_lo:[0,1,0]
	v_pk_fma_f32 v[172:173], v[170:171], v[68:69], v[172:173] op_sel:[1,1,0] op_sel_hi:[0,1,1] neg_lo:[0,1,0]
	v_pk_fma_f32 v[50:51], v[78:79], v[164:165], v[50:51] op_sel_hi:[1,0,1]
	v_pk_fma_f32 v[34:35], v[74:75], v[170:171], v[34:35] op_sel_hi:[1,0,1]
	v_pk_fma_f32 v[52:53], v[70:71], v[164:165], v[52:53] op_sel_hi:[1,0,1]
	v_pk_fma_f32 v[36:37], v[66:67], v[170:171], v[36:37] op_sel_hi:[1,0,1]
	v_pk_fma_f32 v[2:3], v[80:81], v[164:165], v[2:3] op_sel_hi:[1,0,1]
	v_pk_fma_f32 v[18:19], v[76:77], v[170:171], v[18:19] op_sel_hi:[1,0,1]
	v_pk_fma_f32 v[4:5], v[72:73], v[164:165], v[4:5] op_sel_hi:[1,0,1]
	v_pk_fma_f32 v[20:21], v[68:69], v[170:171], v[20:21] op_sel_hi:[1,0,1]
	v_pk_fma_f32 v[50:51], v[80:81], v[164:165], v[50:51] op_sel:[0,1,0] op_sel_hi:[1,1,1] neg_lo:[0,1,0] neg_hi:[0,1,0]
	v_pk_fma_f32 v[34:35], v[76:77], v[170:171], v[34:35] op_sel:[0,1,0] op_sel_hi:[1,1,1] neg_lo:[0,1,0] neg_hi:[0,1,0]
	v_pk_fma_f32 v[52:53], v[72:73], v[164:165], v[52:53] op_sel:[0,1,0] op_sel_hi:[1,1,1] neg_lo:[0,1,0] neg_hi:[0,1,0]
	v_pk_fma_f32 v[36:37], v[68:69], v[170:171], v[36:37] op_sel:[0,1,0] op_sel_hi:[1,1,1] neg_lo:[0,1,0] neg_hi:[0,1,0]
	v_pk_fma_f32 v[2:3], v[78:79], v[164:165], v[2:3] op_sel:[0,1,0] op_sel_hi:[1,1,1]
	v_pk_fma_f32 v[18:19], v[74:75], v[170:171], v[18:19] op_sel:[0,1,0] op_sel_hi:[1,1,1]
	v_pk_fma_f32 v[4:5], v[70:71], v[164:165], v[4:5] op_sel:[0,1,0] op_sel_hi:[1,1,1]
	v_pk_fma_f32 v[20:21], v[66:67], v[170:171], v[20:21] op_sel:[0,1,0] op_sel_hi:[1,1,1]
	v_pk_mul_f32 v[164:165], v[168:169], v[70:71] op_sel:[0,1] op_sel_hi:[1,1]
	v_pk_mul_f32 v[170:171], v[172:173], v[66:67] op_sel:[0,1] op_sel_hi:[1,1]
	v_pk_fma_f32 v[164:165], v[168:169], v[72:73], v[164:165] op_sel:[1,1,0] op_sel_hi:[0,1,1] neg_lo:[0,1,0]
	v_pk_fma_f32 v[170:171], v[172:173], v[68:69], v[170:171] op_sel:[1,1,0] op_sel_hi:[0,1,1] neg_lo:[0,1,0]
	v_pk_fma_f32 v[54:55], v[78:79], v[168:169], v[54:55] op_sel_hi:[1,0,1]
	v_pk_fma_f32 v[38:39], v[74:75], v[172:173], v[38:39] op_sel_hi:[1,0,1]
	v_pk_fma_f32 v[56:57], v[70:71], v[168:169], v[56:57] op_sel_hi:[1,0,1]
	v_pk_fma_f32 v[40:41], v[66:67], v[172:173], v[40:41] op_sel_hi:[1,0,1]
	v_pk_fma_f32 v[6:7], v[80:81], v[168:169], v[6:7] op_sel_hi:[1,0,1]
	v_pk_fma_f32 v[22:23], v[76:77], v[172:173], v[22:23] op_sel_hi:[1,0,1]
	v_pk_fma_f32 v[8:9], v[72:73], v[168:169], v[8:9] op_sel_hi:[1,0,1]
	v_pk_fma_f32 v[24:25], v[68:69], v[172:173], v[24:25] op_sel_hi:[1,0,1]
	v_pk_fma_f32 v[54:55], v[80:81], v[168:169], v[54:55] op_sel:[0,1,0] op_sel_hi:[1,1,1] neg_lo:[0,1,0] neg_hi:[0,1,0]
	v_pk_fma_f32 v[38:39], v[76:77], v[172:173], v[38:39] op_sel:[0,1,0] op_sel_hi:[1,1,1] neg_lo:[0,1,0] neg_hi:[0,1,0]
	v_pk_fma_f32 v[56:57], v[72:73], v[168:169], v[56:57] op_sel:[0,1,0] op_sel_hi:[1,1,1] neg_lo:[0,1,0] neg_hi:[0,1,0]
	v_pk_fma_f32 v[40:41], v[68:69], v[172:173], v[40:41] op_sel:[0,1,0] op_sel_hi:[1,1,1] neg_lo:[0,1,0] neg_hi:[0,1,0]
	v_pk_fma_f32 v[6:7], v[78:79], v[168:169], v[6:7] op_sel:[0,1,0] op_sel_hi:[1,1,1]
	v_pk_fma_f32 v[22:23], v[74:75], v[172:173], v[22:23] op_sel:[0,1,0] op_sel_hi:[1,1,1]
	v_pk_fma_f32 v[8:9], v[70:71], v[168:169], v[8:9] op_sel:[0,1,0] op_sel_hi:[1,1,1]
	v_pk_fma_f32 v[24:25], v[66:67], v[172:173], v[24:25] op_sel:[0,1,0] op_sel_hi:[1,1,1]
	v_pk_mul_f32 v[168:169], v[164:165], v[70:71] op_sel:[0,1] op_sel_hi:[1,1]
	v_pk_mul_f32 v[172:173], v[170:171], v[66:67] op_sel:[0,1] op_sel_hi:[1,1]
	v_pk_fma_f32 v[168:169], v[164:165], v[72:73], v[168:169] op_sel:[1,1,0] op_sel_hi:[0,1,1] neg_lo:[0,1,0]
	v_pk_fma_f32 v[172:173], v[170:171], v[68:69], v[172:173] op_sel:[1,1,0] op_sel_hi:[0,1,1] neg_lo:[0,1,0]
	v_pk_fma_f32 v[58:59], v[78:79], v[164:165], v[58:59] op_sel_hi:[1,0,1]
	v_pk_fma_f32 v[42:43], v[74:75], v[170:171], v[42:43] op_sel_hi:[1,0,1]
	v_pk_fma_f32 v[60:61], v[70:71], v[164:165], v[60:61] op_sel_hi:[1,0,1]
	v_pk_fma_f32 v[44:45], v[66:67], v[170:171], v[44:45] op_sel_hi:[1,0,1]
	v_pk_fma_f32 v[10:11], v[80:81], v[164:165], v[10:11] op_sel_hi:[1,0,1]
	v_pk_fma_f32 v[26:27], v[76:77], v[170:171], v[26:27] op_sel_hi:[1,0,1]
	v_pk_fma_f32 v[12:13], v[72:73], v[164:165], v[12:13] op_sel_hi:[1,0,1]
	v_pk_fma_f32 v[28:29], v[68:69], v[170:171], v[28:29] op_sel_hi:[1,0,1]
	v_pk_fma_f32 v[58:59], v[80:81], v[164:165], v[58:59] op_sel:[0,1,0] op_sel_hi:[1,1,1] neg_lo:[0,1,0] neg_hi:[0,1,0]
	v_pk_fma_f32 v[42:43], v[76:77], v[170:171], v[42:43] op_sel:[0,1,0] op_sel_hi:[1,1,1] neg_lo:[0,1,0] neg_hi:[0,1,0]
	v_pk_fma_f32 v[60:61], v[72:73], v[164:165], v[60:61] op_sel:[0,1,0] op_sel_hi:[1,1,1] neg_lo:[0,1,0] neg_hi:[0,1,0]
	v_pk_fma_f32 v[44:45], v[68:69], v[170:171], v[44:45] op_sel:[0,1,0] op_sel_hi:[1,1,1] neg_lo:[0,1,0] neg_hi:[0,1,0]
	v_pk_fma_f32 v[10:11], v[78:79], v[164:165], v[10:11] op_sel:[0,1,0] op_sel_hi:[1,1,1]
	v_pk_fma_f32 v[26:27], v[74:75], v[170:171], v[26:27] op_sel:[0,1,0] op_sel_hi:[1,1,1]
	v_pk_fma_f32 v[12:13], v[70:71], v[164:165], v[12:13] op_sel:[0,1,0] op_sel_hi:[1,1,1]
	v_pk_fma_f32 v[28:29], v[66:67], v[170:171], v[28:29] op_sel:[0,1,0] op_sel_hi:[1,1,1]
	v_pk_fma_f32 v[62:63], v[78:79], v[168:169], v[62:63] op_sel_hi:[1,0,1]
	v_pk_fma_f32 v[46:47], v[74:75], v[172:173], v[46:47] op_sel_hi:[1,0,1]
	v_pk_fma_f32 v[64:65], v[70:71], v[168:169], v[64:65] op_sel_hi:[1,0,1]
	v_pk_fma_f32 v[48:49], v[66:67], v[172:173], v[48:49] op_sel_hi:[1,0,1]
	v_pk_fma_f32 v[14:15], v[80:81], v[168:169], v[14:15] op_sel_hi:[1,0,1]
	v_pk_fma_f32 v[30:31], v[76:77], v[172:173], v[30:31] op_sel_hi:[1,0,1]
	v_pk_fma_f32 v[16:17], v[72:73], v[168:169], v[16:17] op_sel_hi:[1,0,1]
	v_pk_fma_f32 v[32:33], v[68:69], v[172:173], v[32:33] op_sel_hi:[1,0,1]
	v_pk_fma_f32 v[62:63], v[80:81], v[168:169], v[62:63] op_sel:[0,1,0] op_sel_hi:[1,1,1] neg_lo:[0,1,0] neg_hi:[0,1,0]
	v_pk_fma_f32 v[46:47], v[76:77], v[172:173], v[46:47] op_sel:[0,1,0] op_sel_hi:[1,1,1] neg_lo:[0,1,0] neg_hi:[0,1,0]
	v_pk_fma_f32 v[64:65], v[72:73], v[168:169], v[64:65] op_sel:[0,1,0] op_sel_hi:[1,1,1] neg_lo:[0,1,0] neg_hi:[0,1,0]
	v_pk_fma_f32 v[48:49], v[68:69], v[172:173], v[48:49] op_sel:[0,1,0] op_sel_hi:[1,1,1] neg_lo:[0,1,0] neg_hi:[0,1,0]
	v_pk_fma_f32 v[14:15], v[78:79], v[168:169], v[14:15] op_sel:[0,1,0] op_sel_hi:[1,1,1]
	v_pk_fma_f32 v[30:31], v[74:75], v[172:173], v[30:31] op_sel:[0,1,0] op_sel_hi:[1,1,1]
	v_pk_fma_f32 v[16:17], v[70:71], v[168:169], v[16:17] op_sel:[0,1,0] op_sel_hi:[1,1,1]
	v_pk_fma_f32 v[32:33], v[66:67], v[172:173], v[32:33] op_sel:[0,1,0] op_sel_hi:[1,1,1]
	v_mov_b32_e32 v156, v65
	v_mov_b32_e32 v157, v17
	v_mov_b32_e32 v166, v65
	v_mov_b32_e32 v167, v17
	s_nop 1
	v_permlane32_swap_b32_e32 v156, v166
	v_permlane32_swap_b32_e32 v157, v167
	v_mov_b32_e32 v156, v49
	v_mov_b32_e32 v157, v33
	v_mov_b32_e32 v150, v49
	v_mov_b32_e32 v151, v33
	s_nop 1
	v_permlane32_swap_b32_e32 v156, v150
	v_permlane32_swap_b32_e32 v157, v151
	v_cvt_pk_bf16_f32 v1, v50, v2
	ds_write_b32 v174, v1
	v_cvt_pk_bf16_f32 v146, v34, v18
	ds_write_b32 v174, v146 offset:128
	v_cvt_pk_bf16_f32 v178, v51, v3
	ds_write_b32 v174, v178 offset:272
	v_cvt_pk_bf16_f32 v1, v35, v19
	ds_write_b32 v174, v1 offset:400
	v_cvt_pk_bf16_f32 v146, v52, v4
	ds_write_b32 v174, v146 offset:544
	v_cvt_pk_bf16_f32 v178, v36, v20
	ds_write_b32 v174, v178 offset:672
	v_cvt_pk_bf16_f32 v1, v53, v5
	ds_write_b32 v174, v1 offset:816
	v_cvt_pk_bf16_f32 v146, v37, v21
	ds_write_b32 v174, v146 offset:944
	v_cvt_pk_bf16_f32 v178, v54, v6
	ds_write_b32 v174, v178 offset:1088
	v_cvt_pk_bf16_f32 v1, v38, v22
	ds_write_b32 v174, v1 offset:1216
	v_cvt_pk_bf16_f32 v146, v55, v7
	ds_write_b32 v174, v146 offset:1360
	v_cvt_pk_bf16_f32 v178, v39, v23
	ds_write_b32 v174, v178 offset:1488
	v_cvt_pk_bf16_f32 v1, v56, v8
	ds_write_b32 v174, v1 offset:1632
	v_cvt_pk_bf16_f32 v146, v40, v24
	ds_write_b32 v174, v146 offset:1760
	v_cvt_pk_bf16_f32 v178, v57, v9
	ds_write_b32 v174, v178 offset:1904
	v_cvt_pk_bf16_f32 v1, v41, v25
	ds_write_b32 v174, v1 offset:2032
	v_cvt_pk_bf16_f32 v146, v58, v10
	ds_write_b32 v174, v146 offset:2176
	v_cvt_pk_bf16_f32 v178, v42, v26
	ds_write_b32 v174, v178 offset:2304
	v_cvt_pk_bf16_f32 v1, v59, v11
	ds_write_b32 v174, v1 offset:2448
	v_cvt_pk_bf16_f32 v146, v43, v27
	ds_write_b32 v174, v146 offset:2576
	v_cvt_pk_bf16_f32 v178, v60, v12
	ds_write_b32 v174, v178 offset:2720
	v_cvt_pk_bf16_f32 v1, v44, v28
	ds_write_b32 v174, v1 offset:2848
	v_cvt_pk_bf16_f32 v146, v61, v13
	ds_write_b32 v174, v146 offset:2992
	v_cvt_pk_bf16_f32 v178, v45, v29
	ds_write_b32 v174, v178 offset:3120
	v_cvt_pk_bf16_f32 v1, v62, v14
	ds_write_b32 v174, v1 offset:3264
	v_cvt_pk_bf16_f32 v146, v46, v30
	ds_write_b32 v174, v146 offset:3392
	v_cvt_pk_bf16_f32 v178, v63, v15
	ds_write_b32 v174, v178 offset:3536
	v_cvt_pk_bf16_f32 v1, v47, v31
	ds_write_b32 v174, v1 offset:3664
	v_cvt_pk_bf16_f32 v146, v64, v16
	ds_write_b32 v174, v146 offset:3808
	v_cvt_pk_bf16_f32 v178, v48, v32
	ds_write_b32 v174, v178 offset:3936
	v_cvt_pk_bf16_f32 v1, v65, v17
	ds_write_b32 v174, v1 offset:4080
	v_cvt_pk_bf16_f32 v146, v49, v33
	ds_write_b32 v174, v146 offset:4208
	s_waitcnt lgkmcnt(0)
	ds_read_b128 v[2:5], v175
	ds_read_b128 v[6:9], v175 offset:64
	ds_read_b128 v[10:13], v175 offset:128
	ds_read_b128 v[14:17], v175 offset:192
	ds_read_b128 v[18:21], v175 offset:4352
	ds_read_b128 v[22:25], v175 offset:4416
	ds_read_b128 v[26:29], v175 offset:4480
	ds_read_b128 v[30:33], v175 offset:4544
	s_waitcnt vmcnt(0)
	s_waitcnt lgkmcnt(7)
	v_mfma_f32_16x16x32_bf16 v[34:37], v[94:97], v[2:5], 0
	s_waitcnt lgkmcnt(6)
	v_mfma_f32_16x16x32_bf16 v[34:37], v[90:93], v[6:9], v[34:37]
	s_waitcnt lgkmcnt(5)
	v_mfma_f32_16x16x32_bf16 v[34:37], v[86:89], v[10:13], v[34:37]
	s_waitcnt lgkmcnt(4)
	v_mfma_f32_16x16x32_bf16 v[34:37], v[82:85], v[14:17], v[34:37]
	s_waitcnt lgkmcnt(3)
	v_mfma_f32_16x16x32_bf16 v[38:41], v[94:97], v[18:21], 0
	s_waitcnt lgkmcnt(2)
	v_mfma_f32_16x16x32_bf16 v[38:41], v[90:93], v[22:25], v[38:41]
	s_waitcnt lgkmcnt(1)
	v_mfma_f32_16x16x32_bf16 v[38:41], v[86:89], v[26:29], v[38:41]
	s_waitcnt lgkmcnt(0)
	v_mfma_f32_16x16x32_bf16 v[38:41], v[82:85], v[30:33], v[38:41]
	s_add_u32 s6, s6, 0x8000
	s_addc_u32 s7, s7, 0
	v_lshlrev_b32_e32 v42, 16, v160
	v_and_b32_e32 v43, 0xffff0000, v160
	v_lshlrev_b32_e32 v44, 16, v161
	v_and_b32_e32 v45, 0xffff0000, v161
	v_lshlrev_b32_e32 v46, 16, v162
	v_and_b32_e32 v47, 0xffff0000, v162
	v_lshlrev_b32_e32 v48, 16, v163
	v_and_b32_e32 v49, 0xffff0000, v163
	s_nop 1
	v_mov_b32_e32 v156, 0x3d372713
	v_mov_b32_e32 v158, 0xbfcc422a
	v_mov_b32_e32 v164, 0x3fb8aa3b
	v_mov_b32_e32 v168, 1.0
	v_pk_fma_f32 v[50:51], v[98:99], v[42:43], v[34:35]
	v_pk_fma_f32 v[52:53], v[100:101], v[44:45], v[36:37]
	v_pk_fma_f32 v[54:55], v[98:99], v[46:47], v[38:39]
	v_pk_fma_f32 v[56:57], v[100:101], v[48:49], v[40:41]
	v_pk_mul_f32 v[2:3], v[50:51], v[156:157] op_sel_hi:[1,0]
	v_pk_mul_f32 v[4:5], v[52:53], v[156:157] op_sel_hi:[1,0]
	v_pk_mul_f32 v[6:7], v[54:55], v[156:157] op_sel_hi:[1,0]
	v_pk_mul_f32 v[8:9], v[56:57], v[156:157] op_sel_hi:[1,0]
	v_pk_mul_f32 v[2:3], v[50:51], v[2:3]
	v_pk_mul_f32 v[4:5], v[52:53], v[4:5]
	v_pk_mul_f32 v[6:7], v[54:55], v[6:7]
	v_pk_mul_f32 v[8:9], v[56:57], v[8:9]
	v_pk_fma_f32 v[2:3], v[50:51], v[2:3], v[50:51]
	v_pk_fma_f32 v[4:5], v[52:53], v[4:5], v[52:53]
	v_pk_fma_f32 v[6:7], v[54:55], v[6:7], v[54:55]
	v_pk_fma_f32 v[8:9], v[56:57], v[8:9], v[56:57]
	v_pk_mul_f32 v[2:3], v[2:3], v[158:159] op_sel_hi:[1,0]
	v_pk_mul_f32 v[4:5], v[4:5], v[158:159] op_sel_hi:[1,0]
	v_pk_mul_f32 v[6:7], v[6:7], v[158:159] op_sel_hi:[1,0]
	v_pk_mul_f32 v[8:9], v[8:9], v[158:159] op_sel_hi:[1,0]
	v_pk_mul_f32 v[2:3], v[2:3], v[164:165] op_sel_hi:[1,0]
	v_pk_mul_f32 v[4:5], v[4:5], v[164:165] op_sel_hi:[1,0]
	v_pk_mul_f32 v[6:7], v[6:7], v[164:165] op_sel_hi:[1,0]
	v_pk_mul_f32 v[8:9], v[8:9], v[164:165] op_sel_hi:[1,0]
	v_exp_f32_e32 v2, v2
	v_exp_f32_e32 v3, v3
	v_exp_f32_e32 v4, v4
	v_exp_f32_e32 v5, v5
	v_exp_f32_e32 v6, v6
	v_exp_f32_e32 v7, v7
	v_exp_f32_e32 v8, v8
	v_exp_f32_e32 v9, v9
	v_pk_add_f32 v[2:3], v[2:3], v[168:169] op_sel_hi:[1,0]
	v_pk_add_f32 v[4:5], v[4:5], v[168:169] op_sel_hi:[1,0]
	v_pk_add_f32 v[6:7], v[6:7], v[168:169] op_sel_hi:[1,0]
	v_pk_add_f32 v[8:9], v[8:9], v[168:169] op_sel_hi:[1,0]
	v_rcp_f32_e32 v2, v2
	v_rcp_f32_e32 v3, v3
	v_rcp_f32_e32 v4, v4
	v_rcp_f32_e32 v5, v5
	v_rcp_f32_e32 v6, v6
	v_rcp_f32_e32 v7, v7
	v_rcp_f32_e32 v8, v8
	v_rcp_f32_e32 v9, v9
	v_pk_mul_f32 v[50:51], v[50:51], v[2:3]
	v_pk_mul_f32 v[52:53], v[52:53], v[4:5]
	v_pk_mul_f32 v[54:55], v[54:55], v[6:7]
	v_pk_mul_f32 v[56:57], v[56:57], v[8:9]
	v_cvt_pk_bf16_f32 v10, v50, v51
	v_cvt_pk_bf16_f32 v11, v52, v53
	v_cvt_pk_bf16_f32 v12, v54, v55
	v_cvt_pk_bf16_f32 v13, v56, v57
	global_store_dwordx2 v176, v[10:11], s[10:11]
	global_store_dwordx2 v177, v[12:13], s[10:11]
	s_add_u32 s10, s10, 0x8000
	s_addc_u32 s11, s11, 0
	s_nop 0
	v_mfma_f32_32x32x16_bf16 v[50:65], v[130:133], v[114:117], 0
	v_mfma_f32_32x32x16_bf16 v[2:17], v[130:133], v[110:113], 0
	v_mfma_f32_32x32x16_bf16 v[34:49], v[130:133], v[106:109], 0
	v_mfma_f32_32x32x16_bf16 v[18:33], v[130:133], v[102:105], 0
	global_load_dwordx2 v[160:161], v176, s[6:7]
	global_load_dwordx2 v[162:163], v177, s[6:7]
	s_nop 9
	v_fmac_f32_e32 v51, v78, v50
	v_fmac_f32_e32 v35, v74, v34
	v_fmac_f32_e32 v3, v80, v50
	v_fmac_f32_e32 v19, v76, v34
	v_fma_f32 v51, -v80, v2, v51
	v_fma_f32 v35, -v76, v18, v35
	v_fmac_f32_e32 v3, v78, v2
	v_fmac_f32_e32 v19, v74, v18
	v_fmac_f32_e32 v52, v78, v51
	v_fmac_f32_e32 v36, v74, v35
	v_fmac_f32_e32 v4, v80, v51
	v_fmac_f32_e32 v20, v76, v35
	v_fma_f32 v52, -v80, v3, v52
	v_fma_f32 v36, -v76, v19, v36
	v_fmac_f32_e32 v4, v78, v3
	v_fmac_f32_e32 v20, v74, v19
	v_fmac_f32_e32 v53, v78, v52
	v_fmac_f32_e32 v37, v74, v36
	v_fmac_f32_e32 v5, v80, v52
	v_fmac_f32_e32 v21, v76, v36
	v_fma_f32 v53, -v80, v4, v53
	v_fma_f32 v37, -v76, v20, v37
	v_fmac_f32_e32 v5, v78, v4
	v_fmac_f32_e32 v21, v74, v20
	v_fmac_f32_e32 v54, v78, v53
	v_fmac_f32_e32 v38, v74, v37
	v_fmac_f32_e32 v6, v80, v53
	v_fmac_f32_e32 v22, v76, v37
	v_fma_f32 v54, -v80, v5, v54
	v_fma_f32 v38, -v76, v21, v38
	v_fmac_f32_e32 v6, v78, v5
	v_fmac_f32_e32 v22, v74, v21
	v_fmac_f32_e32 v55, v78, v54
	v_fmac_f32_e32 v39, v74, v38
	v_fmac_f32_e32 v7, v80, v54
	v_fmac_f32_e32 v23, v76, v38
	v_fma_f32 v55, -v80, v6, v55
	v_fma_f32 v39, -v76, v22, v39
	v_fmac_f32_e32 v7, v78, v6
	v_fmac_f32_e32 v23, v74, v22
	v_fmac_f32_e32 v56, v78, v55
	v_fmac_f32_e32 v40, v74, v39
	v_fmac_f32_e32 v8, v80, v55
	v_fmac_f32_e32 v24, v76, v39
	v_fma_f32 v56, -v80, v7, v56
	v_fma_f32 v40, -v76, v23, v40
	v_fmac_f32_e32 v8, v78, v7
	v_fmac_f32_e32 v24, v74, v23
	v_fmac_f32_e32 v57, v78, v56
	v_fmac_f32_e32 v41, v74, v40
	v_fmac_f32_e32 v9, v80, v56
	v_fmac_f32_e32 v25, v76, v40
	v_fma_f32 v57, -v80, v8, v57
	v_fma_f32 v41, -v76, v24, v41
	v_fmac_f32_e32 v9, v78, v8
	v_fmac_f32_e32 v25, v74, v24
	v_fmac_f32_e32 v58, v78, v57
	v_fmac_f32_e32 v42, v74, v41
	v_fmac_f32_e32 v10, v80, v57
	v_fmac_f32_e32 v26, v76, v41
	v_fma_f32 v58, -v80, v9, v58
	v_fma_f32 v42, -v76, v25, v42
	v_fmac_f32_e32 v10, v78, v9
	v_fmac_f32_e32 v26, v74, v25
	v_fmac_f32_e32 v59, v78, v58
	v_fmac_f32_e32 v43, v74, v42
	v_fmac_f32_e32 v11, v80, v58
	v_fmac_f32_e32 v27, v76, v42
	v_fma_f32 v59, -v80, v10, v59
	v_fma_f32 v43, -v76, v26, v43
	v_fmac_f32_e32 v11, v78, v10
	v_fmac_f32_e32 v27, v74, v26
	v_fmac_f32_e32 v60, v78, v59
	v_fmac_f32_e32 v44, v74, v43
	v_fmac_f32_e32 v12, v80, v59
	v_fmac_f32_e32 v28, v76, v43
	v_fma_f32 v60, -v80, v11, v60
	v_fma_f32 v44, -v76, v27, v44
	v_fmac_f32_e32 v12, v78, v11
	v_fmac_f32_e32 v28, v74, v27
	v_fmac_f32_e32 v61, v78, v60
	v_fmac_f32_e32 v45, v74, v44
	v_fmac_f32_e32 v13, v80, v60
	v_fmac_f32_e32 v29, v76, v44
	v_fma_f32 v61, -v80, v12, v61
	v_fma_f32 v45, -v76, v28, v45
	v_fmac_f32_e32 v13, v78, v12
	v_fmac_f32_e32 v29, v74, v28
	v_fmac_f32_e32 v62, v78, v61
	v_fmac_f32_e32 v46, v74, v45
	v_fmac_f32_e32 v14, v80, v61
	v_fmac_f32_e32 v30, v76, v45
	v_fma_f32 v62, -v80, v13, v62
	v_fma_f32 v46, -v76, v29, v46
	v_fmac_f32_e32 v14, v78, v13
	v_fmac_f32_e32 v30, v74, v29
	v_fmac_f32_e32 v63, v78, v62
	v_fmac_f32_e32 v47, v74, v46
	v_fmac_f32_e32 v15, v80, v62
	v_fmac_f32_e32 v31, v76, v46
	v_fma_f32 v63, -v80, v14, v63
	v_fma_f32 v47, -v76, v30, v47
	v_fmac_f32_e32 v15, v78, v14
	v_fmac_f32_e32 v31, v74, v30
	v_fmac_f32_e32 v64, v78, v63
	v_fmac_f32_e32 v48, v74, v47
	v_fmac_f32_e32 v16, v80, v63
	v_fmac_f32_e32 v32, v76, v47
	v_fma_f32 v64, -v80, v15, v64
	v_fma_f32 v48, -v76, v31, v48
	v_fmac_f32_e32 v16, v78, v15
	v_fmac_f32_e32 v32, v74, v31
	v_fmac_f32_e32 v65, v78, v64
	v_fmac_f32_e32 v49, v74, v48
	v_fmac_f32_e32 v17, v80, v64
	v_fmac_f32_e32 v33, v76, v48
	v_fma_f32 v65, -v80, v16, v65
	v_fma_f32 v49, -v76, v32, v49
	v_fmac_f32_e32 v17, v78, v16
	v_fmac_f32_e32 v33, v74, v32
	v_mov_b32_e32 v156, v65
	v_mov_b32_e32 v157, v17
	v_mov_b32_e32 v158, v65
	v_mov_b32_e32 v159, v17
	s_nop 1
	v_permlane32_swap_b32_e32 v156, v158
	v_permlane32_swap_b32_e32 v157, v159
	v_pk_fma_f32 v[164:165], v[166:167], v[152:153], v[156:157] op_sel_hi:[1,0,1]
	v_pk_fma_f32 v[164:165], v[166:167], v[152:153], v[164:165] op_sel:[1,1,0] op_sel_hi:[0,1,1] neg_lo:[0,1,0]
	v_cndmask_b32_e32 v164, v166, v164, vcc
	v_cndmask_b32_e32 v165, v167, v165, vcc
	v_mov_b32_e32 v156, v49
	v_mov_b32_e32 v157, v33
	v_mov_b32_e32 v158, v49
	v_mov_b32_e32 v159, v33
	s_nop 1
	v_permlane32_swap_b32_e32 v156, v158
	v_permlane32_swap_b32_e32 v157, v159
	v_pk_fma_f32 v[170:171], v[150:151], v[154:155], v[156:157] op_sel_hi:[1,0,1]
	v_pk_fma_f32 v[170:171], v[150:151], v[154:155], v[170:171] op_sel:[1,1,0] op_sel_hi:[0,1,1] neg_lo:[0,1,0]
	v_cndmask_b32_e32 v170, v150, v170, vcc
	v_cndmask_b32_e32 v171, v151, v171, vcc
	v_pk_mul_f32 v[168:169], v[164:165], v[70:71] op_sel:[0,1] op_sel_hi:[1,1]
	v_pk_mul_f32 v[172:173], v[170:171], v[66:67] op_sel:[0,1] op_sel_hi:[1,1]
	v_pk_fma_f32 v[168:169], v[164:165], v[72:73], v[168:169] op_sel:[1,1,0] op_sel_hi:[0,1,1] neg_lo:[0,1,0]
	v_pk_fma_f32 v[172:173], v[170:171], v[68:69], v[172:173] op_sel:[1,1,0] op_sel_hi:[0,1,1] neg_lo:[0,1,0]
	v_pk_fma_f32 v[50:51], v[78:79], v[164:165], v[50:51] op_sel_hi:[1,0,1]
	v_pk_fma_f32 v[34:35], v[74:75], v[170:171], v[34:35] op_sel_hi:[1,0,1]
	v_pk_fma_f32 v[52:53], v[70:71], v[164:165], v[52:53] op_sel_hi:[1,0,1]
	v_pk_fma_f32 v[36:37], v[66:67], v[170:171], v[36:37] op_sel_hi:[1,0,1]
	v_pk_fma_f32 v[2:3], v[80:81], v[164:165], v[2:3] op_sel_hi:[1,0,1]
	v_pk_fma_f32 v[18:19], v[76:77], v[170:171], v[18:19] op_sel_hi:[1,0,1]
	v_pk_fma_f32 v[4:5], v[72:73], v[164:165], v[4:5] op_sel_hi:[1,0,1]
	v_pk_fma_f32 v[20:21], v[68:69], v[170:171], v[20:21] op_sel_hi:[1,0,1]
	v_pk_fma_f32 v[50:51], v[80:81], v[164:165], v[50:51] op_sel:[0,1,0] op_sel_hi:[1,1,1] neg_lo:[0,1,0] neg_hi:[0,1,0]
	v_pk_fma_f32 v[34:35], v[76:77], v[170:171], v[34:35] op_sel:[0,1,0] op_sel_hi:[1,1,1] neg_lo:[0,1,0] neg_hi:[0,1,0]
	v_pk_fma_f32 v[52:53], v[72:73], v[164:165], v[52:53] op_sel:[0,1,0] op_sel_hi:[1,1,1] neg_lo:[0,1,0] neg_hi:[0,1,0]
	v_pk_fma_f32 v[36:37], v[68:69], v[170:171], v[36:37] op_sel:[0,1,0] op_sel_hi:[1,1,1] neg_lo:[0,1,0] neg_hi:[0,1,0]
	v_pk_fma_f32 v[2:3], v[78:79], v[164:165], v[2:3] op_sel:[0,1,0] op_sel_hi:[1,1,1]
	v_pk_fma_f32 v[18:19], v[74:75], v[170:171], v[18:19] op_sel:[0,1,0] op_sel_hi:[1,1,1]
	v_pk_fma_f32 v[4:5], v[70:71], v[164:165], v[4:5] op_sel:[0,1,0] op_sel_hi:[1,1,1]
	v_pk_fma_f32 v[20:21], v[66:67], v[170:171], v[20:21] op_sel:[0,1,0] op_sel_hi:[1,1,1]
	v_pk_mul_f32 v[164:165], v[168:169], v[70:71] op_sel:[0,1] op_sel_hi:[1,1]
	v_pk_mul_f32 v[170:171], v[172:173], v[66:67] op_sel:[0,1] op_sel_hi:[1,1]
	v_pk_fma_f32 v[164:165], v[168:169], v[72:73], v[164:165] op_sel:[1,1,0] op_sel_hi:[0,1,1] neg_lo:[0,1,0]
	v_pk_fma_f32 v[170:171], v[172:173], v[68:69], v[170:171] op_sel:[1,1,0] op_sel_hi:[0,1,1] neg_lo:[0,1,0]
	v_pk_fma_f32 v[54:55], v[78:79], v[168:169], v[54:55] op_sel_hi:[1,0,1]
	v_pk_fma_f32 v[38:39], v[74:75], v[172:173], v[38:39] op_sel_hi:[1,0,1]
	v_pk_fma_f32 v[56:57], v[70:71], v[168:169], v[56:57] op_sel_hi:[1,0,1]
	v_pk_fma_f32 v[40:41], v[66:67], v[172:173], v[40:41] op_sel_hi:[1,0,1]
	v_pk_fma_f32 v[6:7], v[80:81], v[168:169], v[6:7] op_sel_hi:[1,0,1]
	v_pk_fma_f32 v[22:23], v[76:77], v[172:173], v[22:23] op_sel_hi:[1,0,1]
	v_pk_fma_f32 v[8:9], v[72:73], v[168:169], v[8:9] op_sel_hi:[1,0,1]
	v_pk_fma_f32 v[24:25], v[68:69], v[172:173], v[24:25] op_sel_hi:[1,0,1]
	v_pk_fma_f32 v[54:55], v[80:81], v[168:169], v[54:55] op_sel:[0,1,0] op_sel_hi:[1,1,1] neg_lo:[0,1,0] neg_hi:[0,1,0]
	v_pk_fma_f32 v[38:39], v[76:77], v[172:173], v[38:39] op_sel:[0,1,0] op_sel_hi:[1,1,1] neg_lo:[0,1,0] neg_hi:[0,1,0]
	v_pk_fma_f32 v[56:57], v[72:73], v[168:169], v[56:57] op_sel:[0,1,0] op_sel_hi:[1,1,1] neg_lo:[0,1,0] neg_hi:[0,1,0]
	v_pk_fma_f32 v[40:41], v[68:69], v[172:173], v[40:41] op_sel:[0,1,0] op_sel_hi:[1,1,1] neg_lo:[0,1,0] neg_hi:[0,1,0]
	v_pk_fma_f32 v[6:7], v[78:79], v[168:169], v[6:7] op_sel:[0,1,0] op_sel_hi:[1,1,1]
	v_pk_fma_f32 v[22:23], v[74:75], v[172:173], v[22:23] op_sel:[0,1,0] op_sel_hi:[1,1,1]
	v_pk_fma_f32 v[8:9], v[70:71], v[168:169], v[8:9] op_sel:[0,1,0] op_sel_hi:[1,1,1]
	v_pk_fma_f32 v[24:25], v[66:67], v[172:173], v[24:25] op_sel:[0,1,0] op_sel_hi:[1,1,1]
	v_pk_mul_f32 v[168:169], v[164:165], v[70:71] op_sel:[0,1] op_sel_hi:[1,1]
	v_pk_mul_f32 v[172:173], v[170:171], v[66:67] op_sel:[0,1] op_sel_hi:[1,1]
	v_pk_fma_f32 v[168:169], v[164:165], v[72:73], v[168:169] op_sel:[1,1,0] op_sel_hi:[0,1,1] neg_lo:[0,1,0]
	v_pk_fma_f32 v[172:173], v[170:171], v[68:69], v[172:173] op_sel:[1,1,0] op_sel_hi:[0,1,1] neg_lo:[0,1,0]
	v_pk_fma_f32 v[58:59], v[78:79], v[164:165], v[58:59] op_sel_hi:[1,0,1]
	v_pk_fma_f32 v[42:43], v[74:75], v[170:171], v[42:43] op_sel_hi:[1,0,1]
	v_pk_fma_f32 v[60:61], v[70:71], v[164:165], v[60:61] op_sel_hi:[1,0,1]
	v_pk_fma_f32 v[44:45], v[66:67], v[170:171], v[44:45] op_sel_hi:[1,0,1]
	v_pk_fma_f32 v[10:11], v[80:81], v[164:165], v[10:11] op_sel_hi:[1,0,1]
	v_pk_fma_f32 v[26:27], v[76:77], v[170:171], v[26:27] op_sel_hi:[1,0,1]
	v_pk_fma_f32 v[12:13], v[72:73], v[164:165], v[12:13] op_sel_hi:[1,0,1]
	v_pk_fma_f32 v[28:29], v[68:69], v[170:171], v[28:29] op_sel_hi:[1,0,1]
	v_pk_fma_f32 v[58:59], v[80:81], v[164:165], v[58:59] op_sel:[0,1,0] op_sel_hi:[1,1,1] neg_lo:[0,1,0] neg_hi:[0,1,0]
	v_pk_fma_f32 v[42:43], v[76:77], v[170:171], v[42:43] op_sel:[0,1,0] op_sel_hi:[1,1,1] neg_lo:[0,1,0] neg_hi:[0,1,0]
	v_pk_fma_f32 v[60:61], v[72:73], v[164:165], v[60:61] op_sel:[0,1,0] op_sel_hi:[1,1,1] neg_lo:[0,1,0] neg_hi:[0,1,0]
	v_pk_fma_f32 v[44:45], v[68:69], v[170:171], v[44:45] op_sel:[0,1,0] op_sel_hi:[1,1,1] neg_lo:[0,1,0] neg_hi:[0,1,0]
	v_pk_fma_f32 v[10:11], v[78:79], v[164:165], v[10:11] op_sel:[0,1,0] op_sel_hi:[1,1,1]
	v_pk_fma_f32 v[26:27], v[74:75], v[170:171], v[26:27] op_sel:[0,1,0] op_sel_hi:[1,1,1]
	v_pk_fma_f32 v[12:13], v[70:71], v[164:165], v[12:13] op_sel:[0,1,0] op_sel_hi:[1,1,1]
	v_pk_fma_f32 v[28:29], v[66:67], v[170:171], v[28:29] op_sel:[0,1,0] op_sel_hi:[1,1,1]
	v_pk_fma_f32 v[62:63], v[78:79], v[168:169], v[62:63] op_sel_hi:[1,0,1]
	v_pk_fma_f32 v[46:47], v[74:75], v[172:173], v[46:47] op_sel_hi:[1,0,1]
	v_pk_fma_f32 v[64:65], v[70:71], v[168:169], v[64:65] op_sel_hi:[1,0,1]
	v_pk_fma_f32 v[48:49], v[66:67], v[172:173], v[48:49] op_sel_hi:[1,0,1]
	v_pk_fma_f32 v[14:15], v[80:81], v[168:169], v[14:15] op_sel_hi:[1,0,1]
	v_pk_fma_f32 v[30:31], v[76:77], v[172:173], v[30:31] op_sel_hi:[1,0,1]
	v_pk_fma_f32 v[16:17], v[72:73], v[168:169], v[16:17] op_sel_hi:[1,0,1]
	v_pk_fma_f32 v[32:33], v[68:69], v[172:173], v[32:33] op_sel_hi:[1,0,1]
	v_pk_fma_f32 v[62:63], v[80:81], v[168:169], v[62:63] op_sel:[0,1,0] op_sel_hi:[1,1,1] neg_lo:[0,1,0] neg_hi:[0,1,0]
	v_pk_fma_f32 v[46:47], v[76:77], v[172:173], v[46:47] op_sel:[0,1,0] op_sel_hi:[1,1,1] neg_lo:[0,1,0] neg_hi:[0,1,0]
	v_pk_fma_f32 v[64:65], v[72:73], v[168:169], v[64:65] op_sel:[0,1,0] op_sel_hi:[1,1,1] neg_lo:[0,1,0] neg_hi:[0,1,0]
	v_pk_fma_f32 v[48:49], v[68:69], v[172:173], v[48:49] op_sel:[0,1,0] op_sel_hi:[1,1,1] neg_lo:[0,1,0] neg_hi:[0,1,0]
	v_pk_fma_f32 v[14:15], v[78:79], v[168:169], v[14:15] op_sel:[0,1,0] op_sel_hi:[1,1,1]
	v_pk_fma_f32 v[30:31], v[74:75], v[172:173], v[30:31] op_sel:[0,1,0] op_sel_hi:[1,1,1]
	v_pk_fma_f32 v[16:17], v[70:71], v[168:169], v[16:17] op_sel:[0,1,0] op_sel_hi:[1,1,1]
	v_pk_fma_f32 v[32:33], v[66:67], v[172:173], v[32:33] op_sel:[0,1,0] op_sel_hi:[1,1,1]
	v_mov_b32_e32 v156, v65
	v_mov_b32_e32 v157, v17
	v_mov_b32_e32 v166, v65
	v_mov_b32_e32 v167, v17
	s_nop 1
	v_permlane32_swap_b32_e32 v156, v166
	v_permlane32_swap_b32_e32 v157, v167
	v_mov_b32_e32 v156, v49
	v_mov_b32_e32 v157, v33
	v_mov_b32_e32 v150, v49
	v_mov_b32_e32 v151, v33
	s_nop 1
	v_permlane32_swap_b32_e32 v156, v150
	v_permlane32_swap_b32_e32 v157, v151
	v_cvt_pk_bf16_f32 v1, v50, v2
	ds_write_b32 v174, v1
	v_cvt_pk_bf16_f32 v146, v34, v18
	ds_write_b32 v174, v146 offset:128
	v_cvt_pk_bf16_f32 v178, v51, v3
	ds_write_b32 v174, v178 offset:272
	v_cvt_pk_bf16_f32 v1, v35, v19
	ds_write_b32 v174, v1 offset:400
	v_cvt_pk_bf16_f32 v146, v52, v4
	ds_write_b32 v174, v146 offset:544
	v_cvt_pk_bf16_f32 v178, v36, v20
	ds_write_b32 v174, v178 offset:672
	v_cvt_pk_bf16_f32 v1, v53, v5
	ds_write_b32 v174, v1 offset:816
	v_cvt_pk_bf16_f32 v146, v37, v21
	ds_write_b32 v174, v146 offset:944
	v_cvt_pk_bf16_f32 v178, v54, v6
	ds_write_b32 v174, v178 offset:1088
	v_cvt_pk_bf16_f32 v1, v38, v22
	ds_write_b32 v174, v1 offset:1216
	v_cvt_pk_bf16_f32 v146, v55, v7
	ds_write_b32 v174, v146 offset:1360
	v_cvt_pk_bf16_f32 v178, v39, v23
	ds_write_b32 v174, v178 offset:1488
	v_cvt_pk_bf16_f32 v1, v56, v8
	ds_write_b32 v174, v1 offset:1632
	v_cvt_pk_bf16_f32 v146, v40, v24
	ds_write_b32 v174, v146 offset:1760
	v_cvt_pk_bf16_f32 v178, v57, v9
	ds_write_b32 v174, v178 offset:1904
	v_cvt_pk_bf16_f32 v1, v41, v25
	ds_write_b32 v174, v1 offset:2032
	v_cvt_pk_bf16_f32 v146, v58, v10
	ds_write_b32 v174, v146 offset:2176
	v_cvt_pk_bf16_f32 v178, v42, v26
	ds_write_b32 v174, v178 offset:2304
	v_cvt_pk_bf16_f32 v1, v59, v11
	ds_write_b32 v174, v1 offset:2448
	v_cvt_pk_bf16_f32 v146, v43, v27
	ds_write_b32 v174, v146 offset:2576
	v_cvt_pk_bf16_f32 v178, v60, v12
	ds_write_b32 v174, v178 offset:2720
	v_cvt_pk_bf16_f32 v1, v44, v28
	ds_write_b32 v174, v1 offset:2848
	v_cvt_pk_bf16_f32 v146, v61, v13
	ds_write_b32 v174, v146 offset:2992
	v_cvt_pk_bf16_f32 v178, v45, v29
	ds_write_b32 v174, v178 offset:3120
	v_cvt_pk_bf16_f32 v1, v62, v14
	ds_write_b32 v174, v1 offset:3264
	v_cvt_pk_bf16_f32 v146, v46, v30
	ds_write_b32 v174, v146 offset:3392
	v_cvt_pk_bf16_f32 v178, v63, v15
	ds_write_b32 v174, v178 offset:3536
	v_cvt_pk_bf16_f32 v1, v47, v31
	ds_write_b32 v174, v1 offset:3664
	v_cvt_pk_bf16_f32 v146, v64, v16
	ds_write_b32 v174, v146 offset:3808
	v_cvt_pk_bf16_f32 v178, v48, v32
	ds_write_b32 v174, v178 offset:3936
	v_cvt_pk_bf16_f32 v1, v65, v17
	ds_write_b32 v174, v1 offset:4080
	v_cvt_pk_bf16_f32 v146, v49, v33
	ds_write_b32 v174, v146 offset:4208
	s_waitcnt lgkmcnt(0)
	ds_read_b128 v[2:5], v175
	ds_read_b128 v[6:9], v175 offset:64
	ds_read_b128 v[10:13], v175 offset:128
	ds_read_b128 v[14:17], v175 offset:192
	ds_read_b128 v[18:21], v175 offset:4352
	ds_read_b128 v[22:25], v175 offset:4416
	ds_read_b128 v[26:29], v175 offset:4480
	ds_read_b128 v[30:33], v175 offset:4544
	s_waitcnt vmcnt(0)
	s_waitcnt lgkmcnt(7)
	v_mfma_f32_16x16x32_bf16 v[34:37], v[94:97], v[2:5], 0
	s_waitcnt lgkmcnt(6)
	v_mfma_f32_16x16x32_bf16 v[34:37], v[90:93], v[6:9], v[34:37]
	s_waitcnt lgkmcnt(5)
	v_mfma_f32_16x16x32_bf16 v[34:37], v[86:89], v[10:13], v[34:37]
	s_waitcnt lgkmcnt(4)
	v_mfma_f32_16x16x32_bf16 v[34:37], v[82:85], v[14:17], v[34:37]
	s_waitcnt lgkmcnt(3)
	v_mfma_f32_16x16x32_bf16 v[38:41], v[94:97], v[18:21], 0
	s_waitcnt lgkmcnt(2)
	v_mfma_f32_16x16x32_bf16 v[38:41], v[90:93], v[22:25], v[38:41]
	s_waitcnt lgkmcnt(1)
	v_mfma_f32_16x16x32_bf16 v[38:41], v[86:89], v[26:29], v[38:41]
	s_waitcnt lgkmcnt(0)
	v_mfma_f32_16x16x32_bf16 v[38:41], v[82:85], v[30:33], v[38:41]
	s_add_u32 s6, s6, 0x8000
	s_addc_u32 s7, s7, 0
	v_lshlrev_b32_e32 v42, 16, v160
	v_and_b32_e32 v43, 0xffff0000, v160
	v_lshlrev_b32_e32 v44, 16, v161
	v_and_b32_e32 v45, 0xffff0000, v161
	v_lshlrev_b32_e32 v46, 16, v162
	v_and_b32_e32 v47, 0xffff0000, v162
	v_lshlrev_b32_e32 v48, 16, v163
	v_and_b32_e32 v49, 0xffff0000, v163
	s_nop 1
	v_mov_b32_e32 v156, 0x3d372713
	v_mov_b32_e32 v158, 0xbfcc422a
	v_mov_b32_e32 v164, 0x3fb8aa3b
	v_mov_b32_e32 v168, 1.0
	v_pk_fma_f32 v[50:51], v[98:99], v[42:43], v[34:35]
	v_pk_fma_f32 v[52:53], v[100:101], v[44:45], v[36:37]
	v_pk_fma_f32 v[54:55], v[98:99], v[46:47], v[38:39]
	v_pk_fma_f32 v[56:57], v[100:101], v[48:49], v[40:41]
	v_pk_mul_f32 v[2:3], v[50:51], v[156:157] op_sel_hi:[1,0]
	v_pk_mul_f32 v[4:5], v[52:53], v[156:157] op_sel_hi:[1,0]
	v_pk_mul_f32 v[6:7], v[54:55], v[156:157] op_sel_hi:[1,0]
	v_pk_mul_f32 v[8:9], v[56:57], v[156:157] op_sel_hi:[1,0]
	v_pk_mul_f32 v[2:3], v[50:51], v[2:3]
	v_pk_mul_f32 v[4:5], v[52:53], v[4:5]
	v_pk_mul_f32 v[6:7], v[54:55], v[6:7]
	v_pk_mul_f32 v[8:9], v[56:57], v[8:9]
	v_pk_fma_f32 v[2:3], v[50:51], v[2:3], v[50:51]
	v_pk_fma_f32 v[4:5], v[52:53], v[4:5], v[52:53]
	v_pk_fma_f32 v[6:7], v[54:55], v[6:7], v[54:55]
	v_pk_fma_f32 v[8:9], v[56:57], v[8:9], v[56:57]
	v_pk_mul_f32 v[2:3], v[2:3], v[158:159] op_sel_hi:[1,0]
	v_pk_mul_f32 v[4:5], v[4:5], v[158:159] op_sel_hi:[1,0]
	v_pk_mul_f32 v[6:7], v[6:7], v[158:159] op_sel_hi:[1,0]
	v_pk_mul_f32 v[8:9], v[8:9], v[158:159] op_sel_hi:[1,0]
	v_pk_mul_f32 v[2:3], v[2:3], v[164:165] op_sel_hi:[1,0]
	v_pk_mul_f32 v[4:5], v[4:5], v[164:165] op_sel_hi:[1,0]
	v_pk_mul_f32 v[6:7], v[6:7], v[164:165] op_sel_hi:[1,0]
	v_pk_mul_f32 v[8:9], v[8:9], v[164:165] op_sel_hi:[1,0]
	v_exp_f32_e32 v2, v2
	v_exp_f32_e32 v3, v3
	v_exp_f32_e32 v4, v4
	v_exp_f32_e32 v5, v5
	v_exp_f32_e32 v6, v6
	v_exp_f32_e32 v7, v7
	v_exp_f32_e32 v8, v8
	v_exp_f32_e32 v9, v9
	v_pk_add_f32 v[2:3], v[2:3], v[168:169] op_sel_hi:[1,0]
	v_pk_add_f32 v[4:5], v[4:5], v[168:169] op_sel_hi:[1,0]
	v_pk_add_f32 v[6:7], v[6:7], v[168:169] op_sel_hi:[1,0]
	v_pk_add_f32 v[8:9], v[8:9], v[168:169] op_sel_hi:[1,0]
	v_rcp_f32_e32 v2, v2
	v_rcp_f32_e32 v3, v3
	v_rcp_f32_e32 v4, v4
	v_rcp_f32_e32 v5, v5
	v_rcp_f32_e32 v6, v6
	v_rcp_f32_e32 v7, v7
	v_rcp_f32_e32 v8, v8
	v_rcp_f32_e32 v9, v9
	v_pk_mul_f32 v[50:51], v[50:51], v[2:3]
	v_pk_mul_f32 v[52:53], v[52:53], v[4:5]
	v_pk_mul_f32 v[54:55], v[54:55], v[6:7]
	v_pk_mul_f32 v[56:57], v[56:57], v[8:9]
	v_cvt_pk_bf16_f32 v10, v50, v51
	v_cvt_pk_bf16_f32 v11, v52, v53
	v_cvt_pk_bf16_f32 v12, v54, v55
	v_cvt_pk_bf16_f32 v13, v56, v57
	global_store_dwordx2 v176, v[10:11], s[10:11]
	global_store_dwordx2 v177, v[12:13], s[10:11]
	s_add_u32 s10, s10, 0x8000
	s_addc_u32 s11, s11, 0
	s_nop 0
	v_mfma_f32_32x32x16_bf16 v[50:65], v[126:129], v[114:117], 0
	v_mfma_f32_32x32x16_bf16 v[2:17], v[126:129], v[110:113], 0
	v_mfma_f32_32x32x16_bf16 v[34:49], v[126:129], v[106:109], 0
	v_mfma_f32_32x32x16_bf16 v[18:33], v[126:129], v[102:105], 0
	global_load_dwordx2 v[160:161], v176, s[6:7]
	global_load_dwordx2 v[162:163], v177, s[6:7]
	s_nop 9
	v_fmac_f32_e32 v51, v78, v50
	v_fmac_f32_e32 v35, v74, v34
	v_fmac_f32_e32 v3, v80, v50
	v_fmac_f32_e32 v19, v76, v34
	v_fma_f32 v51, -v80, v2, v51
	v_fma_f32 v35, -v76, v18, v35
	v_fmac_f32_e32 v3, v78, v2
	v_fmac_f32_e32 v19, v74, v18
	v_fmac_f32_e32 v52, v78, v51
	v_fmac_f32_e32 v36, v74, v35
	v_fmac_f32_e32 v4, v80, v51
	v_fmac_f32_e32 v20, v76, v35
	v_fma_f32 v52, -v80, v3, v52
	v_fma_f32 v36, -v76, v19, v36
	v_fmac_f32_e32 v4, v78, v3
	v_fmac_f32_e32 v20, v74, v19
	v_fmac_f32_e32 v53, v78, v52
	v_fmac_f32_e32 v37, v74, v36
	v_fmac_f32_e32 v5, v80, v52
	v_fmac_f32_e32 v21, v76, v36
	v_fma_f32 v53, -v80, v4, v53
	v_fma_f32 v37, -v76, v20, v37
	v_fmac_f32_e32 v5, v78, v4
	v_fmac_f32_e32 v21, v74, v20
	v_fmac_f32_e32 v54, v78, v53
	v_fmac_f32_e32 v38, v74, v37
	v_fmac_f32_e32 v6, v80, v53
	v_fmac_f32_e32 v22, v76, v37
	v_fma_f32 v54, -v80, v5, v54
	v_fma_f32 v38, -v76, v21, v38
	v_fmac_f32_e32 v6, v78, v5
	v_fmac_f32_e32 v22, v74, v21
	v_fmac_f32_e32 v55, v78, v54
	v_fmac_f32_e32 v39, v74, v38
	v_fmac_f32_e32 v7, v80, v54
	v_fmac_f32_e32 v23, v76, v38
	v_fma_f32 v55, -v80, v6, v55
	v_fma_f32 v39, -v76, v22, v39
	v_fmac_f32_e32 v7, v78, v6
	v_fmac_f32_e32 v23, v74, v22
	v_fmac_f32_e32 v56, v78, v55
	v_fmac_f32_e32 v40, v74, v39
	v_fmac_f32_e32 v8, v80, v55
	v_fmac_f32_e32 v24, v76, v39
	v_fma_f32 v56, -v80, v7, v56
	v_fma_f32 v40, -v76, v23, v40
	v_fmac_f32_e32 v8, v78, v7
	v_fmac_f32_e32 v24, v74, v23
	v_fmac_f32_e32 v57, v78, v56
	v_fmac_f32_e32 v41, v74, v40
	v_fmac_f32_e32 v9, v80, v56
	v_fmac_f32_e32 v25, v76, v40
	v_fma_f32 v57, -v80, v8, v57
	v_fma_f32 v41, -v76, v24, v41
	v_fmac_f32_e32 v9, v78, v8
	v_fmac_f32_e32 v25, v74, v24
	v_fmac_f32_e32 v58, v78, v57
	v_fmac_f32_e32 v42, v74, v41
	v_fmac_f32_e32 v10, v80, v57
	v_fmac_f32_e32 v26, v76, v41
	v_fma_f32 v58, -v80, v9, v58
	v_fma_f32 v42, -v76, v25, v42
	v_fmac_f32_e32 v10, v78, v9
	v_fmac_f32_e32 v26, v74, v25
	v_fmac_f32_e32 v59, v78, v58
	v_fmac_f32_e32 v43, v74, v42
	v_fmac_f32_e32 v11, v80, v58
	v_fmac_f32_e32 v27, v76, v42
	v_fma_f32 v59, -v80, v10, v59
	v_fma_f32 v43, -v76, v26, v43
	v_fmac_f32_e32 v11, v78, v10
	v_fmac_f32_e32 v27, v74, v26
	v_fmac_f32_e32 v60, v78, v59
	v_fmac_f32_e32 v44, v74, v43
	v_fmac_f32_e32 v12, v80, v59
	v_fmac_f32_e32 v28, v76, v43
	v_fma_f32 v60, -v80, v11, v60
	v_fma_f32 v44, -v76, v27, v44
	v_fmac_f32_e32 v12, v78, v11
	v_fmac_f32_e32 v28, v74, v27
	v_fmac_f32_e32 v61, v78, v60
	v_fmac_f32_e32 v45, v74, v44
	v_fmac_f32_e32 v13, v80, v60
	v_fmac_f32_e32 v29, v76, v44
	v_fma_f32 v61, -v80, v12, v61
	v_fma_f32 v45, -v76, v28, v45
	v_fmac_f32_e32 v13, v78, v12
	v_fmac_f32_e32 v29, v74, v28
	v_fmac_f32_e32 v62, v78, v61
	v_fmac_f32_e32 v46, v74, v45
	v_fmac_f32_e32 v14, v80, v61
	v_fmac_f32_e32 v30, v76, v45
	v_fma_f32 v62, -v80, v13, v62
	v_fma_f32 v46, -v76, v29, v46
	v_fmac_f32_e32 v14, v78, v13
	v_fmac_f32_e32 v30, v74, v29
	v_fmac_f32_e32 v63, v78, v62
	v_fmac_f32_e32 v47, v74, v46
	v_fmac_f32_e32 v15, v80, v62
	v_fmac_f32_e32 v31, v76, v46
	v_fma_f32 v63, -v80, v14, v63
	v_fma_f32 v47, -v76, v30, v47
	v_fmac_f32_e32 v15, v78, v14
	v_fmac_f32_e32 v31, v74, v30
	v_fmac_f32_e32 v64, v78, v63
	v_fmac_f32_e32 v48, v74, v47
	v_fmac_f32_e32 v16, v80, v63
	v_fmac_f32_e32 v32, v76, v47
	v_fma_f32 v64, -v80, v15, v64
	v_fma_f32 v48, -v76, v31, v48
	v_fmac_f32_e32 v16, v78, v15
	v_fmac_f32_e32 v32, v74, v31
	v_fmac_f32_e32 v65, v78, v64
	v_fmac_f32_e32 v49, v74, v48
	v_fmac_f32_e32 v17, v80, v64
	v_fmac_f32_e32 v33, v76, v48
	v_fma_f32 v65, -v80, v16, v65
	v_fma_f32 v49, -v76, v32, v49
	v_fmac_f32_e32 v17, v78, v16
	v_fmac_f32_e32 v33, v74, v32
	v_mov_b32_e32 v156, v65
	v_mov_b32_e32 v157, v17
	v_mov_b32_e32 v158, v65
	v_mov_b32_e32 v159, v17
	s_nop 1
	v_permlane32_swap_b32_e32 v156, v158
	v_permlane32_swap_b32_e32 v157, v159
	v_pk_fma_f32 v[164:165], v[166:167], v[152:153], v[156:157] op_sel_hi:[1,0,1]
	v_pk_fma_f32 v[164:165], v[166:167], v[152:153], v[164:165] op_sel:[1,1,0] op_sel_hi:[0,1,1] neg_lo:[0,1,0]
	v_cndmask_b32_e32 v164, v166, v164, vcc
	v_cndmask_b32_e32 v165, v167, v165, vcc
	v_mov_b32_e32 v156, v49
	v_mov_b32_e32 v157, v33
	v_mov_b32_e32 v158, v49
	v_mov_b32_e32 v159, v33
	s_nop 1
	v_permlane32_swap_b32_e32 v156, v158
	v_permlane32_swap_b32_e32 v157, v159
	v_pk_fma_f32 v[170:171], v[150:151], v[154:155], v[156:157] op_sel_hi:[1,0,1]
	v_pk_fma_f32 v[170:171], v[150:151], v[154:155], v[170:171] op_sel:[1,1,0] op_sel_hi:[0,1,1] neg_lo:[0,1,0]
	v_cndmask_b32_e32 v170, v150, v170, vcc
	v_cndmask_b32_e32 v171, v151, v171, vcc
	v_pk_mul_f32 v[168:169], v[164:165], v[70:71] op_sel:[0,1] op_sel_hi:[1,1]
	v_pk_mul_f32 v[172:173], v[170:171], v[66:67] op_sel:[0,1] op_sel_hi:[1,1]
	v_pk_fma_f32 v[168:169], v[164:165], v[72:73], v[168:169] op_sel:[1,1,0] op_sel_hi:[0,1,1] neg_lo:[0,1,0]
	v_pk_fma_f32 v[172:173], v[170:171], v[68:69], v[172:173] op_sel:[1,1,0] op_sel_hi:[0,1,1] neg_lo:[0,1,0]
	v_pk_fma_f32 v[50:51], v[78:79], v[164:165], v[50:51] op_sel_hi:[1,0,1]
	v_pk_fma_f32 v[34:35], v[74:75], v[170:171], v[34:35] op_sel_hi:[1,0,1]
	v_pk_fma_f32 v[52:53], v[70:71], v[164:165], v[52:53] op_sel_hi:[1,0,1]
	v_pk_fma_f32 v[36:37], v[66:67], v[170:171], v[36:37] op_sel_hi:[1,0,1]
	v_pk_fma_f32 v[2:3], v[80:81], v[164:165], v[2:3] op_sel_hi:[1,0,1]
	v_pk_fma_f32 v[18:19], v[76:77], v[170:171], v[18:19] op_sel_hi:[1,0,1]
	v_pk_fma_f32 v[4:5], v[72:73], v[164:165], v[4:5] op_sel_hi:[1,0,1]
	v_pk_fma_f32 v[20:21], v[68:69], v[170:171], v[20:21] op_sel_hi:[1,0,1]
	v_pk_fma_f32 v[50:51], v[80:81], v[164:165], v[50:51] op_sel:[0,1,0] op_sel_hi:[1,1,1] neg_lo:[0,1,0] neg_hi:[0,1,0]
	v_pk_fma_f32 v[34:35], v[76:77], v[170:171], v[34:35] op_sel:[0,1,0] op_sel_hi:[1,1,1] neg_lo:[0,1,0] neg_hi:[0,1,0]
	v_pk_fma_f32 v[52:53], v[72:73], v[164:165], v[52:53] op_sel:[0,1,0] op_sel_hi:[1,1,1] neg_lo:[0,1,0] neg_hi:[0,1,0]
	v_pk_fma_f32 v[36:37], v[68:69], v[170:171], v[36:37] op_sel:[0,1,0] op_sel_hi:[1,1,1] neg_lo:[0,1,0] neg_hi:[0,1,0]
	v_pk_fma_f32 v[2:3], v[78:79], v[164:165], v[2:3] op_sel:[0,1,0] op_sel_hi:[1,1,1]
	v_pk_fma_f32 v[18:19], v[74:75], v[170:171], v[18:19] op_sel:[0,1,0] op_sel_hi:[1,1,1]
	v_pk_fma_f32 v[4:5], v[70:71], v[164:165], v[4:5] op_sel:[0,1,0] op_sel_hi:[1,1,1]
	v_pk_fma_f32 v[20:21], v[66:67], v[170:171], v[20:21] op_sel:[0,1,0] op_sel_hi:[1,1,1]
	v_pk_mul_f32 v[164:165], v[168:169], v[70:71] op_sel:[0,1] op_sel_hi:[1,1]
	v_pk_mul_f32 v[170:171], v[172:173], v[66:67] op_sel:[0,1] op_sel_hi:[1,1]
	v_pk_fma_f32 v[164:165], v[168:169], v[72:73], v[164:165] op_sel:[1,1,0] op_sel_hi:[0,1,1] neg_lo:[0,1,0]
	v_pk_fma_f32 v[170:171], v[172:173], v[68:69], v[170:171] op_sel:[1,1,0] op_sel_hi:[0,1,1] neg_lo:[0,1,0]
	v_pk_fma_f32 v[54:55], v[78:79], v[168:169], v[54:55] op_sel_hi:[1,0,1]
	v_pk_fma_f32 v[38:39], v[74:75], v[172:173], v[38:39] op_sel_hi:[1,0,1]
	v_pk_fma_f32 v[56:57], v[70:71], v[168:169], v[56:57] op_sel_hi:[1,0,1]
	v_pk_fma_f32 v[40:41], v[66:67], v[172:173], v[40:41] op_sel_hi:[1,0,1]
	v_pk_fma_f32 v[6:7], v[80:81], v[168:169], v[6:7] op_sel_hi:[1,0,1]
	v_pk_fma_f32 v[22:23], v[76:77], v[172:173], v[22:23] op_sel_hi:[1,0,1]
	v_pk_fma_f32 v[8:9], v[72:73], v[168:169], v[8:9] op_sel_hi:[1,0,1]
	v_pk_fma_f32 v[24:25], v[68:69], v[172:173], v[24:25] op_sel_hi:[1,0,1]
	v_pk_fma_f32 v[54:55], v[80:81], v[168:169], v[54:55] op_sel:[0,1,0] op_sel_hi:[1,1,1] neg_lo:[0,1,0] neg_hi:[0,1,0]
	v_pk_fma_f32 v[38:39], v[76:77], v[172:173], v[38:39] op_sel:[0,1,0] op_sel_hi:[1,1,1] neg_lo:[0,1,0] neg_hi:[0,1,0]
	v_pk_fma_f32 v[56:57], v[72:73], v[168:169], v[56:57] op_sel:[0,1,0] op_sel_hi:[1,1,1] neg_lo:[0,1,0] neg_hi:[0,1,0]
	v_pk_fma_f32 v[40:41], v[68:69], v[172:173], v[40:41] op_sel:[0,1,0] op_sel_hi:[1,1,1] neg_lo:[0,1,0] neg_hi:[0,1,0]
	v_pk_fma_f32 v[6:7], v[78:79], v[168:169], v[6:7] op_sel:[0,1,0] op_sel_hi:[1,1,1]
	v_pk_fma_f32 v[22:23], v[74:75], v[172:173], v[22:23] op_sel:[0,1,0] op_sel_hi:[1,1,1]
	v_pk_fma_f32 v[8:9], v[70:71], v[168:169], v[8:9] op_sel:[0,1,0] op_sel_hi:[1,1,1]
	v_pk_fma_f32 v[24:25], v[66:67], v[172:173], v[24:25] op_sel:[0,1,0] op_sel_hi:[1,1,1]
	v_pk_mul_f32 v[168:169], v[164:165], v[70:71] op_sel:[0,1] op_sel_hi:[1,1]
	v_pk_mul_f32 v[172:173], v[170:171], v[66:67] op_sel:[0,1] op_sel_hi:[1,1]
	v_pk_fma_f32 v[168:169], v[164:165], v[72:73], v[168:169] op_sel:[1,1,0] op_sel_hi:[0,1,1] neg_lo:[0,1,0]
	v_pk_fma_f32 v[172:173], v[170:171], v[68:69], v[172:173] op_sel:[1,1,0] op_sel_hi:[0,1,1] neg_lo:[0,1,0]
	v_pk_fma_f32 v[58:59], v[78:79], v[164:165], v[58:59] op_sel_hi:[1,0,1]
	v_pk_fma_f32 v[42:43], v[74:75], v[170:171], v[42:43] op_sel_hi:[1,0,1]
	v_pk_fma_f32 v[60:61], v[70:71], v[164:165], v[60:61] op_sel_hi:[1,0,1]
	v_pk_fma_f32 v[44:45], v[66:67], v[170:171], v[44:45] op_sel_hi:[1,0,1]
	v_pk_fma_f32 v[10:11], v[80:81], v[164:165], v[10:11] op_sel_hi:[1,0,1]
	v_pk_fma_f32 v[26:27], v[76:77], v[170:171], v[26:27] op_sel_hi:[1,0,1]
	v_pk_fma_f32 v[12:13], v[72:73], v[164:165], v[12:13] op_sel_hi:[1,0,1]
	v_pk_fma_f32 v[28:29], v[68:69], v[170:171], v[28:29] op_sel_hi:[1,0,1]
	v_pk_fma_f32 v[58:59], v[80:81], v[164:165], v[58:59] op_sel:[0,1,0] op_sel_hi:[1,1,1] neg_lo:[0,1,0] neg_hi:[0,1,0]
	v_pk_fma_f32 v[42:43], v[76:77], v[170:171], v[42:43] op_sel:[0,1,0] op_sel_hi:[1,1,1] neg_lo:[0,1,0] neg_hi:[0,1,0]
	v_pk_fma_f32 v[60:61], v[72:73], v[164:165], v[60:61] op_sel:[0,1,0] op_sel_hi:[1,1,1] neg_lo:[0,1,0] neg_hi:[0,1,0]
	v_pk_fma_f32 v[44:45], v[68:69], v[170:171], v[44:45] op_sel:[0,1,0] op_sel_hi:[1,1,1] neg_lo:[0,1,0] neg_hi:[0,1,0]
	v_pk_fma_f32 v[10:11], v[78:79], v[164:165], v[10:11] op_sel:[0,1,0] op_sel_hi:[1,1,1]
	v_pk_fma_f32 v[26:27], v[74:75], v[170:171], v[26:27] op_sel:[0,1,0] op_sel_hi:[1,1,1]
	v_pk_fma_f32 v[12:13], v[70:71], v[164:165], v[12:13] op_sel:[0,1,0] op_sel_hi:[1,1,1]
	v_pk_fma_f32 v[28:29], v[66:67], v[170:171], v[28:29] op_sel:[0,1,0] op_sel_hi:[1,1,1]
	v_pk_fma_f32 v[62:63], v[78:79], v[168:169], v[62:63] op_sel_hi:[1,0,1]
	v_pk_fma_f32 v[46:47], v[74:75], v[172:173], v[46:47] op_sel_hi:[1,0,1]
	v_pk_fma_f32 v[64:65], v[70:71], v[168:169], v[64:65] op_sel_hi:[1,0,1]
	v_pk_fma_f32 v[48:49], v[66:67], v[172:173], v[48:49] op_sel_hi:[1,0,1]
	v_pk_fma_f32 v[14:15], v[80:81], v[168:169], v[14:15] op_sel_hi:[1,0,1]
	v_pk_fma_f32 v[30:31], v[76:77], v[172:173], v[30:31] op_sel_hi:[1,0,1]
	v_pk_fma_f32 v[16:17], v[72:73], v[168:169], v[16:17] op_sel_hi:[1,0,1]
	v_pk_fma_f32 v[32:33], v[68:69], v[172:173], v[32:33] op_sel_hi:[1,0,1]
	v_pk_fma_f32 v[62:63], v[80:81], v[168:169], v[62:63] op_sel:[0,1,0] op_sel_hi:[1,1,1] neg_lo:[0,1,0] neg_hi:[0,1,0]
	v_pk_fma_f32 v[46:47], v[76:77], v[172:173], v[46:47] op_sel:[0,1,0] op_sel_hi:[1,1,1] neg_lo:[0,1,0] neg_hi:[0,1,0]
	v_pk_fma_f32 v[64:65], v[72:73], v[168:169], v[64:65] op_sel:[0,1,0] op_sel_hi:[1,1,1] neg_lo:[0,1,0] neg_hi:[0,1,0]
	v_pk_fma_f32 v[48:49], v[68:69], v[172:173], v[48:49] op_sel:[0,1,0] op_sel_hi:[1,1,1] neg_lo:[0,1,0] neg_hi:[0,1,0]
	v_pk_fma_f32 v[14:15], v[78:79], v[168:169], v[14:15] op_sel:[0,1,0] op_sel_hi:[1,1,1]
	v_pk_fma_f32 v[30:31], v[74:75], v[172:173], v[30:31] op_sel:[0,1,0] op_sel_hi:[1,1,1]
	v_pk_fma_f32 v[16:17], v[70:71], v[168:169], v[16:17] op_sel:[0,1,0] op_sel_hi:[1,1,1]
	v_pk_fma_f32 v[32:33], v[66:67], v[172:173], v[32:33] op_sel:[0,1,0] op_sel_hi:[1,1,1]
	v_mov_b32_e32 v156, v65
	v_mov_b32_e32 v157, v17
	v_mov_b32_e32 v166, v65
	v_mov_b32_e32 v167, v17
	s_nop 1
	v_permlane32_swap_b32_e32 v156, v166
	v_permlane32_swap_b32_e32 v157, v167
	v_mov_b32_e32 v156, v49
	v_mov_b32_e32 v157, v33
	v_mov_b32_e32 v150, v49
	v_mov_b32_e32 v151, v33
	s_nop 1
	v_permlane32_swap_b32_e32 v156, v150
	v_permlane32_swap_b32_e32 v157, v151
	v_cvt_pk_bf16_f32 v1, v50, v2
	ds_write_b32 v174, v1
	v_cvt_pk_bf16_f32 v146, v34, v18
	ds_write_b32 v174, v146 offset:128
	v_cvt_pk_bf16_f32 v178, v51, v3
	ds_write_b32 v174, v178 offset:272
	v_cvt_pk_bf16_f32 v1, v35, v19
	ds_write_b32 v174, v1 offset:400
	v_cvt_pk_bf16_f32 v146, v52, v4
	ds_write_b32 v174, v146 offset:544
	v_cvt_pk_bf16_f32 v178, v36, v20
	ds_write_b32 v174, v178 offset:672
	v_cvt_pk_bf16_f32 v1, v53, v5
	ds_write_b32 v174, v1 offset:816
	v_cvt_pk_bf16_f32 v146, v37, v21
	ds_write_b32 v174, v146 offset:944
	v_cvt_pk_bf16_f32 v178, v54, v6
	ds_write_b32 v174, v178 offset:1088
	v_cvt_pk_bf16_f32 v1, v38, v22
	ds_write_b32 v174, v1 offset:1216
	v_cvt_pk_bf16_f32 v146, v55, v7
	ds_write_b32 v174, v146 offset:1360
	v_cvt_pk_bf16_f32 v178, v39, v23
	ds_write_b32 v174, v178 offset:1488
	v_cvt_pk_bf16_f32 v1, v56, v8
	ds_write_b32 v174, v1 offset:1632
	v_cvt_pk_bf16_f32 v146, v40, v24
	ds_write_b32 v174, v146 offset:1760
	v_cvt_pk_bf16_f32 v178, v57, v9
	ds_write_b32 v174, v178 offset:1904
	v_cvt_pk_bf16_f32 v1, v41, v25
	ds_write_b32 v174, v1 offset:2032
	v_cvt_pk_bf16_f32 v146, v58, v10
	ds_write_b32 v174, v146 offset:2176
	v_cvt_pk_bf16_f32 v178, v42, v26
	ds_write_b32 v174, v178 offset:2304
	v_cvt_pk_bf16_f32 v1, v59, v11
	ds_write_b32 v174, v1 offset:2448
	v_cvt_pk_bf16_f32 v146, v43, v27
	ds_write_b32 v174, v146 offset:2576
	v_cvt_pk_bf16_f32 v178, v60, v12
	ds_write_b32 v174, v178 offset:2720
	v_cvt_pk_bf16_f32 v1, v44, v28
	ds_write_b32 v174, v1 offset:2848
	v_cvt_pk_bf16_f32 v146, v61, v13
	ds_write_b32 v174, v146 offset:2992
	v_cvt_pk_bf16_f32 v178, v45, v29
	ds_write_b32 v174, v178 offset:3120
	v_cvt_pk_bf16_f32 v1, v62, v14
	ds_write_b32 v174, v1 offset:3264
	v_cvt_pk_bf16_f32 v146, v46, v30
	ds_write_b32 v174, v146 offset:3392
	v_cvt_pk_bf16_f32 v178, v63, v15
	ds_write_b32 v174, v178 offset:3536
	v_cvt_pk_bf16_f32 v1, v47, v31
	ds_write_b32 v174, v1 offset:3664
	v_cvt_pk_bf16_f32 v146, v64, v16
	ds_write_b32 v174, v146 offset:3808
	v_cvt_pk_bf16_f32 v178, v48, v32
	ds_write_b32 v174, v178 offset:3936
	v_cvt_pk_bf16_f32 v1, v65, v17
	ds_write_b32 v174, v1 offset:4080
	v_cvt_pk_bf16_f32 v146, v49, v33
	ds_write_b32 v174, v146 offset:4208
	s_waitcnt lgkmcnt(0)
	ds_read_b128 v[2:5], v175
	ds_read_b128 v[6:9], v175 offset:64
	ds_read_b128 v[10:13], v175 offset:128
	ds_read_b128 v[14:17], v175 offset:192
	ds_read_b128 v[18:21], v175 offset:4352
	ds_read_b128 v[22:25], v175 offset:4416
	ds_read_b128 v[26:29], v175 offset:4480
	ds_read_b128 v[30:33], v175 offset:4544
	s_waitcnt vmcnt(0)
	s_waitcnt lgkmcnt(7)
	v_mfma_f32_16x16x32_bf16 v[34:37], v[94:97], v[2:5], 0
	s_waitcnt lgkmcnt(6)
	v_mfma_f32_16x16x32_bf16 v[34:37], v[90:93], v[6:9], v[34:37]
	s_waitcnt lgkmcnt(5)
	v_mfma_f32_16x16x32_bf16 v[34:37], v[86:89], v[10:13], v[34:37]
	s_waitcnt lgkmcnt(4)
	v_mfma_f32_16x16x32_bf16 v[34:37], v[82:85], v[14:17], v[34:37]
	s_waitcnt lgkmcnt(3)
	v_mfma_f32_16x16x32_bf16 v[38:41], v[94:97], v[18:21], 0
	s_waitcnt lgkmcnt(2)
	v_mfma_f32_16x16x32_bf16 v[38:41], v[90:93], v[22:25], v[38:41]
	s_waitcnt lgkmcnt(1)
	v_mfma_f32_16x16x32_bf16 v[38:41], v[86:89], v[26:29], v[38:41]
	s_waitcnt lgkmcnt(0)
	v_mfma_f32_16x16x32_bf16 v[38:41], v[82:85], v[30:33], v[38:41]
	s_add_u32 s6, s6, 0x8000
	s_addc_u32 s7, s7, 0
	v_lshlrev_b32_e32 v42, 16, v160
	v_and_b32_e32 v43, 0xffff0000, v160
	v_lshlrev_b32_e32 v44, 16, v161
	v_and_b32_e32 v45, 0xffff0000, v161
	v_lshlrev_b32_e32 v46, 16, v162
	v_and_b32_e32 v47, 0xffff0000, v162
	v_lshlrev_b32_e32 v48, 16, v163
	v_and_b32_e32 v49, 0xffff0000, v163
	s_nop 1
	v_mov_b32_e32 v156, 0x3d372713
	v_mov_b32_e32 v158, 0xbfcc422a
	v_mov_b32_e32 v164, 0x3fb8aa3b
	v_mov_b32_e32 v168, 1.0
	v_pk_fma_f32 v[50:51], v[98:99], v[42:43], v[34:35]
	v_pk_fma_f32 v[52:53], v[100:101], v[44:45], v[36:37]
	v_pk_fma_f32 v[54:55], v[98:99], v[46:47], v[38:39]
	v_pk_fma_f32 v[56:57], v[100:101], v[48:49], v[40:41]
	v_pk_mul_f32 v[2:3], v[50:51], v[156:157] op_sel_hi:[1,0]
	v_pk_mul_f32 v[4:5], v[52:53], v[156:157] op_sel_hi:[1,0]
	v_pk_mul_f32 v[6:7], v[54:55], v[156:157] op_sel_hi:[1,0]
	v_pk_mul_f32 v[8:9], v[56:57], v[156:157] op_sel_hi:[1,0]
	v_pk_mul_f32 v[2:3], v[50:51], v[2:3]
	v_pk_mul_f32 v[4:5], v[52:53], v[4:5]
	v_pk_mul_f32 v[6:7], v[54:55], v[6:7]
	v_pk_mul_f32 v[8:9], v[56:57], v[8:9]
	v_pk_fma_f32 v[2:3], v[50:51], v[2:3], v[50:51]
	v_pk_fma_f32 v[4:5], v[52:53], v[4:5], v[52:53]
	v_pk_fma_f32 v[6:7], v[54:55], v[6:7], v[54:55]
	v_pk_fma_f32 v[8:9], v[56:57], v[8:9], v[56:57]
	v_pk_mul_f32 v[2:3], v[2:3], v[158:159] op_sel_hi:[1,0]
	v_pk_mul_f32 v[4:5], v[4:5], v[158:159] op_sel_hi:[1,0]
	v_pk_mul_f32 v[6:7], v[6:7], v[158:159] op_sel_hi:[1,0]
	v_pk_mul_f32 v[8:9], v[8:9], v[158:159] op_sel_hi:[1,0]
	v_pk_mul_f32 v[2:3], v[2:3], v[164:165] op_sel_hi:[1,0]
	v_pk_mul_f32 v[4:5], v[4:5], v[164:165] op_sel_hi:[1,0]
	v_pk_mul_f32 v[6:7], v[6:7], v[164:165] op_sel_hi:[1,0]
	v_pk_mul_f32 v[8:9], v[8:9], v[164:165] op_sel_hi:[1,0]
	v_exp_f32_e32 v2, v2
	v_exp_f32_e32 v3, v3
	v_exp_f32_e32 v4, v4
	v_exp_f32_e32 v5, v5
	v_exp_f32_e32 v6, v6
	v_exp_f32_e32 v7, v7
	v_exp_f32_e32 v8, v8
	v_exp_f32_e32 v9, v9
	v_pk_add_f32 v[2:3], v[2:3], v[168:169] op_sel_hi:[1,0]
	v_pk_add_f32 v[4:5], v[4:5], v[168:169] op_sel_hi:[1,0]
	v_pk_add_f32 v[6:7], v[6:7], v[168:169] op_sel_hi:[1,0]
	v_pk_add_f32 v[8:9], v[8:9], v[168:169] op_sel_hi:[1,0]
	v_rcp_f32_e32 v2, v2
	v_rcp_f32_e32 v3, v3
	v_rcp_f32_e32 v4, v4
	v_rcp_f32_e32 v5, v5
	v_rcp_f32_e32 v6, v6
	v_rcp_f32_e32 v7, v7
	v_rcp_f32_e32 v8, v8
	v_rcp_f32_e32 v9, v9
	v_pk_mul_f32 v[50:51], v[50:51], v[2:3]
	v_pk_mul_f32 v[52:53], v[52:53], v[4:5]
	v_pk_mul_f32 v[54:55], v[54:55], v[6:7]
	v_pk_mul_f32 v[56:57], v[56:57], v[8:9]
	v_cvt_pk_bf16_f32 v10, v50, v51
	v_cvt_pk_bf16_f32 v11, v52, v53
	v_cvt_pk_bf16_f32 v12, v54, v55
	v_cvt_pk_bf16_f32 v13, v56, v57
	global_store_dwordx2 v176, v[10:11], s[10:11]
	global_store_dwordx2 v177, v[12:13], s[10:11]
	s_add_u32 s10, s10, 0x8000
	s_addc_u32 s11, s11, 0
	s_nop 0
	v_mfma_f32_32x32x16_bf16 v[50:65], v[122:125], v[114:117], 0
	v_mfma_f32_32x32x16_bf16 v[2:17], v[122:125], v[110:113], 0
	v_mfma_f32_32x32x16_bf16 v[34:49], v[122:125], v[106:109], 0
	v_mfma_f32_32x32x16_bf16 v[18:33], v[122:125], v[102:105], 0
	global_load_dwordx2 v[160:161], v176, s[6:7]
	global_load_dwordx2 v[162:163], v177, s[6:7]
	s_nop 9
	v_fmac_f32_e32 v51, v78, v50
	v_fmac_f32_e32 v35, v74, v34
	v_fmac_f32_e32 v3, v80, v50
	v_fmac_f32_e32 v19, v76, v34
	v_fma_f32 v51, -v80, v2, v51
	v_fma_f32 v35, -v76, v18, v35
	v_fmac_f32_e32 v3, v78, v2
	v_fmac_f32_e32 v19, v74, v18
	v_fmac_f32_e32 v52, v78, v51
	v_fmac_f32_e32 v36, v74, v35
	v_fmac_f32_e32 v4, v80, v51
	v_fmac_f32_e32 v20, v76, v35
	v_fma_f32 v52, -v80, v3, v52
	v_fma_f32 v36, -v76, v19, v36
	v_fmac_f32_e32 v4, v78, v3
	v_fmac_f32_e32 v20, v74, v19
	v_fmac_f32_e32 v53, v78, v52
	v_fmac_f32_e32 v37, v74, v36
	v_fmac_f32_e32 v5, v80, v52
	v_fmac_f32_e32 v21, v76, v36
	v_fma_f32 v53, -v80, v4, v53
	v_fma_f32 v37, -v76, v20, v37
	v_fmac_f32_e32 v5, v78, v4
	v_fmac_f32_e32 v21, v74, v20
	v_fmac_f32_e32 v54, v78, v53
	v_fmac_f32_e32 v38, v74, v37
	v_fmac_f32_e32 v6, v80, v53
	v_fmac_f32_e32 v22, v76, v37
	v_fma_f32 v54, -v80, v5, v54
	v_fma_f32 v38, -v76, v21, v38
	v_fmac_f32_e32 v6, v78, v5
	v_fmac_f32_e32 v22, v74, v21
	v_fmac_f32_e32 v55, v78, v54
	v_fmac_f32_e32 v39, v74, v38
	v_fmac_f32_e32 v7, v80, v54
	v_fmac_f32_e32 v23, v76, v38
	v_fma_f32 v55, -v80, v6, v55
	v_fma_f32 v39, -v76, v22, v39
	v_fmac_f32_e32 v7, v78, v6
	v_fmac_f32_e32 v23, v74, v22
	v_fmac_f32_e32 v56, v78, v55
	v_fmac_f32_e32 v40, v74, v39
	v_fmac_f32_e32 v8, v80, v55
	v_fmac_f32_e32 v24, v76, v39
	v_fma_f32 v56, -v80, v7, v56
	v_fma_f32 v40, -v76, v23, v40
	v_fmac_f32_e32 v8, v78, v7
	v_fmac_f32_e32 v24, v74, v23
	v_fmac_f32_e32 v57, v78, v56
	v_fmac_f32_e32 v41, v74, v40
	v_fmac_f32_e32 v9, v80, v56
	v_fmac_f32_e32 v25, v76, v40
	v_fma_f32 v57, -v80, v8, v57
	v_fma_f32 v41, -v76, v24, v41
	v_fmac_f32_e32 v9, v78, v8
	v_fmac_f32_e32 v25, v74, v24
	v_fmac_f32_e32 v58, v78, v57
	v_fmac_f32_e32 v42, v74, v41
	v_fmac_f32_e32 v10, v80, v57
	v_fmac_f32_e32 v26, v76, v41
	v_fma_f32 v58, -v80, v9, v58
	v_fma_f32 v42, -v76, v25, v42
	v_fmac_f32_e32 v10, v78, v9
	v_fmac_f32_e32 v26, v74, v25
	v_fmac_f32_e32 v59, v78, v58
	v_fmac_f32_e32 v43, v74, v42
	v_fmac_f32_e32 v11, v80, v58
	v_fmac_f32_e32 v27, v76, v42
	v_fma_f32 v59, -v80, v10, v59
	v_fma_f32 v43, -v76, v26, v43
	v_fmac_f32_e32 v11, v78, v10
	v_fmac_f32_e32 v27, v74, v26
	v_fmac_f32_e32 v60, v78, v59
	v_fmac_f32_e32 v44, v74, v43
	v_fmac_f32_e32 v12, v80, v59
	v_fmac_f32_e32 v28, v76, v43
	v_fma_f32 v60, -v80, v11, v60
	v_fma_f32 v44, -v76, v27, v44
	v_fmac_f32_e32 v12, v78, v11
	v_fmac_f32_e32 v28, v74, v27
	v_fmac_f32_e32 v61, v78, v60
	v_fmac_f32_e32 v45, v74, v44
	v_fmac_f32_e32 v13, v80, v60
	v_fmac_f32_e32 v29, v76, v44
	v_fma_f32 v61, -v80, v12, v61
	v_fma_f32 v45, -v76, v28, v45
	v_fmac_f32_e32 v13, v78, v12
	v_fmac_f32_e32 v29, v74, v28
	v_fmac_f32_e32 v62, v78, v61
	v_fmac_f32_e32 v46, v74, v45
	v_fmac_f32_e32 v14, v80, v61
	v_fmac_f32_e32 v30, v76, v45
	v_fma_f32 v62, -v80, v13, v62
	v_fma_f32 v46, -v76, v29, v46
	v_fmac_f32_e32 v14, v78, v13
	v_fmac_f32_e32 v30, v74, v29
	v_fmac_f32_e32 v63, v78, v62
	v_fmac_f32_e32 v47, v74, v46
	v_fmac_f32_e32 v15, v80, v62
	v_fmac_f32_e32 v31, v76, v46
	v_fma_f32 v63, -v80, v14, v63
	v_fma_f32 v47, -v76, v30, v47
	v_fmac_f32_e32 v15, v78, v14
	v_fmac_f32_e32 v31, v74, v30
	v_fmac_f32_e32 v64, v78, v63
	v_fmac_f32_e32 v48, v74, v47
	v_fmac_f32_e32 v16, v80, v63
	v_fmac_f32_e32 v32, v76, v47
	v_fma_f32 v64, -v80, v15, v64
	v_fma_f32 v48, -v76, v31, v48
	v_fmac_f32_e32 v16, v78, v15
	v_fmac_f32_e32 v32, v74, v31
	v_fmac_f32_e32 v65, v78, v64
	v_fmac_f32_e32 v49, v74, v48
	v_fmac_f32_e32 v17, v80, v64
	v_fmac_f32_e32 v33, v76, v48
	v_fma_f32 v65, -v80, v16, v65
	v_fma_f32 v49, -v76, v32, v49
	v_fmac_f32_e32 v17, v78, v16
	v_fmac_f32_e32 v33, v74, v32
	v_mov_b32_e32 v156, v65
	v_mov_b32_e32 v157, v17
	v_mov_b32_e32 v158, v65
	v_mov_b32_e32 v159, v17
	s_nop 1
	v_permlane32_swap_b32_e32 v156, v158
	v_permlane32_swap_b32_e32 v157, v159
	v_pk_fma_f32 v[164:165], v[166:167], v[152:153], v[156:157] op_sel_hi:[1,0,1]
	v_pk_fma_f32 v[164:165], v[166:167], v[152:153], v[164:165] op_sel:[1,1,0] op_sel_hi:[0,1,1] neg_lo:[0,1,0]
	v_cndmask_b32_e32 v164, v166, v164, vcc
	v_cndmask_b32_e32 v165, v167, v165, vcc
	v_mov_b32_e32 v156, v49
	v_mov_b32_e32 v157, v33
	v_mov_b32_e32 v158, v49
	v_mov_b32_e32 v159, v33
	s_nop 1
	v_permlane32_swap_b32_e32 v156, v158
	v_permlane32_swap_b32_e32 v157, v159
	v_pk_fma_f32 v[170:171], v[150:151], v[154:155], v[156:157] op_sel_hi:[1,0,1]
	v_pk_fma_f32 v[170:171], v[150:151], v[154:155], v[170:171] op_sel:[1,1,0] op_sel_hi:[0,1,1] neg_lo:[0,1,0]
	v_cndmask_b32_e32 v170, v150, v170, vcc
	v_cndmask_b32_e32 v171, v151, v171, vcc
	v_pk_mul_f32 v[168:169], v[164:165], v[70:71] op_sel:[0,1] op_sel_hi:[1,1]
	v_pk_mul_f32 v[172:173], v[170:171], v[66:67] op_sel:[0,1] op_sel_hi:[1,1]
	v_pk_fma_f32 v[168:169], v[164:165], v[72:73], v[168:169] op_sel:[1,1,0] op_sel_hi:[0,1,1] neg_lo:[0,1,0]
	v_pk_fma_f32 v[172:173], v[170:171], v[68:69], v[172:173] op_sel:[1,1,0] op_sel_hi:[0,1,1] neg_lo:[0,1,0]
	v_pk_fma_f32 v[50:51], v[78:79], v[164:165], v[50:51] op_sel_hi:[1,0,1]
	v_pk_fma_f32 v[34:35], v[74:75], v[170:171], v[34:35] op_sel_hi:[1,0,1]
	v_pk_fma_f32 v[52:53], v[70:71], v[164:165], v[52:53] op_sel_hi:[1,0,1]
	v_pk_fma_f32 v[36:37], v[66:67], v[170:171], v[36:37] op_sel_hi:[1,0,1]
	v_pk_fma_f32 v[2:3], v[80:81], v[164:165], v[2:3] op_sel_hi:[1,0,1]
	v_pk_fma_f32 v[18:19], v[76:77], v[170:171], v[18:19] op_sel_hi:[1,0,1]
	v_pk_fma_f32 v[4:5], v[72:73], v[164:165], v[4:5] op_sel_hi:[1,0,1]
	v_pk_fma_f32 v[20:21], v[68:69], v[170:171], v[20:21] op_sel_hi:[1,0,1]
	v_pk_fma_f32 v[50:51], v[80:81], v[164:165], v[50:51] op_sel:[0,1,0] op_sel_hi:[1,1,1] neg_lo:[0,1,0] neg_hi:[0,1,0]
	v_pk_fma_f32 v[34:35], v[76:77], v[170:171], v[34:35] op_sel:[0,1,0] op_sel_hi:[1,1,1] neg_lo:[0,1,0] neg_hi:[0,1,0]
	v_pk_fma_f32 v[52:53], v[72:73], v[164:165], v[52:53] op_sel:[0,1,0] op_sel_hi:[1,1,1] neg_lo:[0,1,0] neg_hi:[0,1,0]
	v_pk_fma_f32 v[36:37], v[68:69], v[170:171], v[36:37] op_sel:[0,1,0] op_sel_hi:[1,1,1] neg_lo:[0,1,0] neg_hi:[0,1,0]
	v_pk_fma_f32 v[2:3], v[78:79], v[164:165], v[2:3] op_sel:[0,1,0] op_sel_hi:[1,1,1]
	v_pk_fma_f32 v[18:19], v[74:75], v[170:171], v[18:19] op_sel:[0,1,0] op_sel_hi:[1,1,1]
	v_pk_fma_f32 v[4:5], v[70:71], v[164:165], v[4:5] op_sel:[0,1,0] op_sel_hi:[1,1,1]
	v_pk_fma_f32 v[20:21], v[66:67], v[170:171], v[20:21] op_sel:[0,1,0] op_sel_hi:[1,1,1]
	v_pk_mul_f32 v[164:165], v[168:169], v[70:71] op_sel:[0,1] op_sel_hi:[1,1]
	v_pk_mul_f32 v[170:171], v[172:173], v[66:67] op_sel:[0,1] op_sel_hi:[1,1]
	v_pk_fma_f32 v[164:165], v[168:169], v[72:73], v[164:165] op_sel:[1,1,0] op_sel_hi:[0,1,1] neg_lo:[0,1,0]
	v_pk_fma_f32 v[170:171], v[172:173], v[68:69], v[170:171] op_sel:[1,1,0] op_sel_hi:[0,1,1] neg_lo:[0,1,0]
	v_pk_fma_f32 v[54:55], v[78:79], v[168:169], v[54:55] op_sel_hi:[1,0,1]
	v_pk_fma_f32 v[38:39], v[74:75], v[172:173], v[38:39] op_sel_hi:[1,0,1]
	v_pk_fma_f32 v[56:57], v[70:71], v[168:169], v[56:57] op_sel_hi:[1,0,1]
	v_pk_fma_f32 v[40:41], v[66:67], v[172:173], v[40:41] op_sel_hi:[1,0,1]
	v_pk_fma_f32 v[6:7], v[80:81], v[168:169], v[6:7] op_sel_hi:[1,0,1]
	v_pk_fma_f32 v[22:23], v[76:77], v[172:173], v[22:23] op_sel_hi:[1,0,1]
	v_pk_fma_f32 v[8:9], v[72:73], v[168:169], v[8:9] op_sel_hi:[1,0,1]
	v_pk_fma_f32 v[24:25], v[68:69], v[172:173], v[24:25] op_sel_hi:[1,0,1]
	v_pk_fma_f32 v[54:55], v[80:81], v[168:169], v[54:55] op_sel:[0,1,0] op_sel_hi:[1,1,1] neg_lo:[0,1,0] neg_hi:[0,1,0]
	v_pk_fma_f32 v[38:39], v[76:77], v[172:173], v[38:39] op_sel:[0,1,0] op_sel_hi:[1,1,1] neg_lo:[0,1,0] neg_hi:[0,1,0]
	v_pk_fma_f32 v[56:57], v[72:73], v[168:169], v[56:57] op_sel:[0,1,0] op_sel_hi:[1,1,1] neg_lo:[0,1,0] neg_hi:[0,1,0]
	v_pk_fma_f32 v[40:41], v[68:69], v[172:173], v[40:41] op_sel:[0,1,0] op_sel_hi:[1,1,1] neg_lo:[0,1,0] neg_hi:[0,1,0]
	v_pk_fma_f32 v[6:7], v[78:79], v[168:169], v[6:7] op_sel:[0,1,0] op_sel_hi:[1,1,1]
	v_pk_fma_f32 v[22:23], v[74:75], v[172:173], v[22:23] op_sel:[0,1,0] op_sel_hi:[1,1,1]
	v_pk_fma_f32 v[8:9], v[70:71], v[168:169], v[8:9] op_sel:[0,1,0] op_sel_hi:[1,1,1]
	v_pk_fma_f32 v[24:25], v[66:67], v[172:173], v[24:25] op_sel:[0,1,0] op_sel_hi:[1,1,1]
	v_pk_mul_f32 v[168:169], v[164:165], v[70:71] op_sel:[0,1] op_sel_hi:[1,1]
	v_pk_mul_f32 v[172:173], v[170:171], v[66:67] op_sel:[0,1] op_sel_hi:[1,1]
	v_pk_fma_f32 v[168:169], v[164:165], v[72:73], v[168:169] op_sel:[1,1,0] op_sel_hi:[0,1,1] neg_lo:[0,1,0]
	v_pk_fma_f32 v[172:173], v[170:171], v[68:69], v[172:173] op_sel:[1,1,0] op_sel_hi:[0,1,1] neg_lo:[0,1,0]
	v_pk_fma_f32 v[58:59], v[78:79], v[164:165], v[58:59] op_sel_hi:[1,0,1]
	v_pk_fma_f32 v[42:43], v[74:75], v[170:171], v[42:43] op_sel_hi:[1,0,1]
	v_pk_fma_f32 v[60:61], v[70:71], v[164:165], v[60:61] op_sel_hi:[1,0,1]
	v_pk_fma_f32 v[44:45], v[66:67], v[170:171], v[44:45] op_sel_hi:[1,0,1]
	v_pk_fma_f32 v[10:11], v[80:81], v[164:165], v[10:11] op_sel_hi:[1,0,1]
	v_pk_fma_f32 v[26:27], v[76:77], v[170:171], v[26:27] op_sel_hi:[1,0,1]
	v_pk_fma_f32 v[12:13], v[72:73], v[164:165], v[12:13] op_sel_hi:[1,0,1]
	v_pk_fma_f32 v[28:29], v[68:69], v[170:171], v[28:29] op_sel_hi:[1,0,1]
	v_pk_fma_f32 v[58:59], v[80:81], v[164:165], v[58:59] op_sel:[0,1,0] op_sel_hi:[1,1,1] neg_lo:[0,1,0] neg_hi:[0,1,0]
	v_pk_fma_f32 v[42:43], v[76:77], v[170:171], v[42:43] op_sel:[0,1,0] op_sel_hi:[1,1,1] neg_lo:[0,1,0] neg_hi:[0,1,0]
	v_pk_fma_f32 v[60:61], v[72:73], v[164:165], v[60:61] op_sel:[0,1,0] op_sel_hi:[1,1,1] neg_lo:[0,1,0] neg_hi:[0,1,0]
	v_pk_fma_f32 v[44:45], v[68:69], v[170:171], v[44:45] op_sel:[0,1,0] op_sel_hi:[1,1,1] neg_lo:[0,1,0] neg_hi:[0,1,0]
	v_pk_fma_f32 v[10:11], v[78:79], v[164:165], v[10:11] op_sel:[0,1,0] op_sel_hi:[1,1,1]
	v_pk_fma_f32 v[26:27], v[74:75], v[170:171], v[26:27] op_sel:[0,1,0] op_sel_hi:[1,1,1]
	v_pk_fma_f32 v[12:13], v[70:71], v[164:165], v[12:13] op_sel:[0,1,0] op_sel_hi:[1,1,1]
	v_pk_fma_f32 v[28:29], v[66:67], v[170:171], v[28:29] op_sel:[0,1,0] op_sel_hi:[1,1,1]
	v_pk_fma_f32 v[62:63], v[78:79], v[168:169], v[62:63] op_sel_hi:[1,0,1]
	v_pk_fma_f32 v[46:47], v[74:75], v[172:173], v[46:47] op_sel_hi:[1,0,1]
	v_pk_fma_f32 v[64:65], v[70:71], v[168:169], v[64:65] op_sel_hi:[1,0,1]
	v_pk_fma_f32 v[48:49], v[66:67], v[172:173], v[48:49] op_sel_hi:[1,0,1]
	v_pk_fma_f32 v[14:15], v[80:81], v[168:169], v[14:15] op_sel_hi:[1,0,1]
	v_pk_fma_f32 v[30:31], v[76:77], v[172:173], v[30:31] op_sel_hi:[1,0,1]
	v_pk_fma_f32 v[16:17], v[72:73], v[168:169], v[16:17] op_sel_hi:[1,0,1]
	v_pk_fma_f32 v[32:33], v[68:69], v[172:173], v[32:33] op_sel_hi:[1,0,1]
	v_pk_fma_f32 v[62:63], v[80:81], v[168:169], v[62:63] op_sel:[0,1,0] op_sel_hi:[1,1,1] neg_lo:[0,1,0] neg_hi:[0,1,0]
	v_pk_fma_f32 v[46:47], v[76:77], v[172:173], v[46:47] op_sel:[0,1,0] op_sel_hi:[1,1,1] neg_lo:[0,1,0] neg_hi:[0,1,0]
	v_pk_fma_f32 v[64:65], v[72:73], v[168:169], v[64:65] op_sel:[0,1,0] op_sel_hi:[1,1,1] neg_lo:[0,1,0] neg_hi:[0,1,0]
	v_pk_fma_f32 v[48:49], v[68:69], v[172:173], v[48:49] op_sel:[0,1,0] op_sel_hi:[1,1,1] neg_lo:[0,1,0] neg_hi:[0,1,0]
	v_pk_fma_f32 v[14:15], v[78:79], v[168:169], v[14:15] op_sel:[0,1,0] op_sel_hi:[1,1,1]
	v_pk_fma_f32 v[30:31], v[74:75], v[172:173], v[30:31] op_sel:[0,1,0] op_sel_hi:[1,1,1]
	v_pk_fma_f32 v[16:17], v[70:71], v[168:169], v[16:17] op_sel:[0,1,0] op_sel_hi:[1,1,1]
	v_pk_fma_f32 v[32:33], v[66:67], v[172:173], v[32:33] op_sel:[0,1,0] op_sel_hi:[1,1,1]
	v_mov_b32_e32 v156, v65
	v_mov_b32_e32 v157, v17
	v_mov_b32_e32 v166, v65
	v_mov_b32_e32 v167, v17
	s_nop 1
	v_permlane32_swap_b32_e32 v156, v166
	v_permlane32_swap_b32_e32 v157, v167
	v_mov_b32_e32 v156, v49
	v_mov_b32_e32 v157, v33
	v_mov_b32_e32 v150, v49
	v_mov_b32_e32 v151, v33
	s_nop 1
	v_permlane32_swap_b32_e32 v156, v150
	v_permlane32_swap_b32_e32 v157, v151
	v_cvt_pk_bf16_f32 v1, v50, v2
	ds_write_b32 v174, v1
	v_cvt_pk_bf16_f32 v146, v34, v18
	ds_write_b32 v174, v146 offset:128
	v_cvt_pk_bf16_f32 v178, v51, v3
	ds_write_b32 v174, v178 offset:272
	v_cvt_pk_bf16_f32 v1, v35, v19
	ds_write_b32 v174, v1 offset:400
	v_cvt_pk_bf16_f32 v146, v52, v4
	ds_write_b32 v174, v146 offset:544
	v_cvt_pk_bf16_f32 v178, v36, v20
	ds_write_b32 v174, v178 offset:672
	v_cvt_pk_bf16_f32 v1, v53, v5
	ds_write_b32 v174, v1 offset:816
	v_cvt_pk_bf16_f32 v146, v37, v21
	ds_write_b32 v174, v146 offset:944
	v_cvt_pk_bf16_f32 v178, v54, v6
	ds_write_b32 v174, v178 offset:1088
	v_cvt_pk_bf16_f32 v1, v38, v22
	ds_write_b32 v174, v1 offset:1216
	v_cvt_pk_bf16_f32 v146, v55, v7
	ds_write_b32 v174, v146 offset:1360
	v_cvt_pk_bf16_f32 v178, v39, v23
	ds_write_b32 v174, v178 offset:1488
	v_cvt_pk_bf16_f32 v1, v56, v8
	ds_write_b32 v174, v1 offset:1632
	v_cvt_pk_bf16_f32 v146, v40, v24
	ds_write_b32 v174, v146 offset:1760
	v_cvt_pk_bf16_f32 v178, v57, v9
	ds_write_b32 v174, v178 offset:1904
	v_cvt_pk_bf16_f32 v1, v41, v25
	ds_write_b32 v174, v1 offset:2032
	v_cvt_pk_bf16_f32 v146, v58, v10
	ds_write_b32 v174, v146 offset:2176
	v_cvt_pk_bf16_f32 v178, v42, v26
	ds_write_b32 v174, v178 offset:2304
	v_cvt_pk_bf16_f32 v1, v59, v11
	ds_write_b32 v174, v1 offset:2448
	v_cvt_pk_bf16_f32 v146, v43, v27
	ds_write_b32 v174, v146 offset:2576
	v_cvt_pk_bf16_f32 v178, v60, v12
	ds_write_b32 v174, v178 offset:2720
	v_cvt_pk_bf16_f32 v1, v44, v28
	ds_write_b32 v174, v1 offset:2848
	v_cvt_pk_bf16_f32 v146, v61, v13
	ds_write_b32 v174, v146 offset:2992
	v_cvt_pk_bf16_f32 v178, v45, v29
	ds_write_b32 v174, v178 offset:3120
	v_cvt_pk_bf16_f32 v1, v62, v14
	ds_write_b32 v174, v1 offset:3264
	v_cvt_pk_bf16_f32 v146, v46, v30
	ds_write_b32 v174, v146 offset:3392
	v_cvt_pk_bf16_f32 v178, v63, v15
	ds_write_b32 v174, v178 offset:3536
	v_cvt_pk_bf16_f32 v1, v47, v31
	ds_write_b32 v174, v1 offset:3664
	v_cvt_pk_bf16_f32 v146, v64, v16
	ds_write_b32 v174, v146 offset:3808
	v_cvt_pk_bf16_f32 v178, v48, v32
	ds_write_b32 v174, v178 offset:3936
	v_cvt_pk_bf16_f32 v1, v65, v17
	ds_write_b32 v174, v1 offset:4080
	v_cvt_pk_bf16_f32 v146, v49, v33
	ds_write_b32 v174, v146 offset:4208
	s_waitcnt lgkmcnt(0)
	ds_read_b128 v[2:5], v175
	ds_read_b128 v[6:9], v175 offset:64
	ds_read_b128 v[10:13], v175 offset:128
	ds_read_b128 v[14:17], v175 offset:192
	ds_read_b128 v[18:21], v175 offset:4352
	ds_read_b128 v[22:25], v175 offset:4416
	ds_read_b128 v[26:29], v175 offset:4480
	ds_read_b128 v[30:33], v175 offset:4544
	s_waitcnt vmcnt(0)
	s_waitcnt lgkmcnt(7)
	v_mfma_f32_16x16x32_bf16 v[34:37], v[94:97], v[2:5], 0
	s_waitcnt lgkmcnt(6)
	v_mfma_f32_16x16x32_bf16 v[34:37], v[90:93], v[6:9], v[34:37]
	s_waitcnt lgkmcnt(5)
	v_mfma_f32_16x16x32_bf16 v[34:37], v[86:89], v[10:13], v[34:37]
	s_waitcnt lgkmcnt(4)
	v_mfma_f32_16x16x32_bf16 v[34:37], v[82:85], v[14:17], v[34:37]
	s_waitcnt lgkmcnt(3)
	v_mfma_f32_16x16x32_bf16 v[38:41], v[94:97], v[18:21], 0
	s_waitcnt lgkmcnt(2)
	v_mfma_f32_16x16x32_bf16 v[38:41], v[90:93], v[22:25], v[38:41]
	s_waitcnt lgkmcnt(1)
	v_mfma_f32_16x16x32_bf16 v[38:41], v[86:89], v[26:29], v[38:41]
	s_waitcnt lgkmcnt(0)
	v_mfma_f32_16x16x32_bf16 v[38:41], v[82:85], v[30:33], v[38:41]
	s_add_u32 s6, s6, 0x8000
	s_addc_u32 s7, s7, 0
	v_lshlrev_b32_e32 v42, 16, v160
	v_and_b32_e32 v43, 0xffff0000, v160
	v_lshlrev_b32_e32 v44, 16, v161
	v_and_b32_e32 v45, 0xffff0000, v161
	v_lshlrev_b32_e32 v46, 16, v162
	v_and_b32_e32 v47, 0xffff0000, v162
	v_lshlrev_b32_e32 v48, 16, v163
	v_and_b32_e32 v49, 0xffff0000, v163
	s_nop 1
	v_mov_b32_e32 v156, 0x3d372713
	v_mov_b32_e32 v158, 0xbfcc422a
	v_mov_b32_e32 v164, 0x3fb8aa3b
	v_mov_b32_e32 v168, 1.0
	v_pk_fma_f32 v[50:51], v[98:99], v[42:43], v[34:35]
	v_pk_fma_f32 v[52:53], v[100:101], v[44:45], v[36:37]
	v_pk_fma_f32 v[54:55], v[98:99], v[46:47], v[38:39]
	v_pk_fma_f32 v[56:57], v[100:101], v[48:49], v[40:41]
	v_pk_mul_f32 v[2:3], v[50:51], v[156:157] op_sel_hi:[1,0]
	v_pk_mul_f32 v[4:5], v[52:53], v[156:157] op_sel_hi:[1,0]
	v_pk_mul_f32 v[6:7], v[54:55], v[156:157] op_sel_hi:[1,0]
	v_pk_mul_f32 v[8:9], v[56:57], v[156:157] op_sel_hi:[1,0]
	v_pk_mul_f32 v[2:3], v[50:51], v[2:3]
	v_pk_mul_f32 v[4:5], v[52:53], v[4:5]
	v_pk_mul_f32 v[6:7], v[54:55], v[6:7]
	v_pk_mul_f32 v[8:9], v[56:57], v[8:9]
	v_pk_fma_f32 v[2:3], v[50:51], v[2:3], v[50:51]
	v_pk_fma_f32 v[4:5], v[52:53], v[4:5], v[52:53]
	v_pk_fma_f32 v[6:7], v[54:55], v[6:7], v[54:55]
	v_pk_fma_f32 v[8:9], v[56:57], v[8:9], v[56:57]
	v_pk_mul_f32 v[2:3], v[2:3], v[158:159] op_sel_hi:[1,0]
	v_pk_mul_f32 v[4:5], v[4:5], v[158:159] op_sel_hi:[1,0]
	v_pk_mul_f32 v[6:7], v[6:7], v[158:159] op_sel_hi:[1,0]
	v_pk_mul_f32 v[8:9], v[8:9], v[158:159] op_sel_hi:[1,0]
	v_pk_mul_f32 v[2:3], v[2:3], v[164:165] op_sel_hi:[1,0]
	v_pk_mul_f32 v[4:5], v[4:5], v[164:165] op_sel_hi:[1,0]
	v_pk_mul_f32 v[6:7], v[6:7], v[164:165] op_sel_hi:[1,0]
	v_pk_mul_f32 v[8:9], v[8:9], v[164:165] op_sel_hi:[1,0]
	v_exp_f32_e32 v2, v2
	v_exp_f32_e32 v3, v3
	v_exp_f32_e32 v4, v4
	v_exp_f32_e32 v5, v5
	v_exp_f32_e32 v6, v6
	v_exp_f32_e32 v7, v7
	v_exp_f32_e32 v8, v8
	v_exp_f32_e32 v9, v9
	v_pk_add_f32 v[2:3], v[2:3], v[168:169] op_sel_hi:[1,0]
	v_pk_add_f32 v[4:5], v[4:5], v[168:169] op_sel_hi:[1,0]
	v_pk_add_f32 v[6:7], v[6:7], v[168:169] op_sel_hi:[1,0]
	v_pk_add_f32 v[8:9], v[8:9], v[168:169] op_sel_hi:[1,0]
	v_rcp_f32_e32 v2, v2
	v_rcp_f32_e32 v3, v3
	v_rcp_f32_e32 v4, v4
	v_rcp_f32_e32 v5, v5
	v_rcp_f32_e32 v6, v6
	v_rcp_f32_e32 v7, v7
	v_rcp_f32_e32 v8, v8
	v_rcp_f32_e32 v9, v9
	v_pk_mul_f32 v[50:51], v[50:51], v[2:3]
	v_pk_mul_f32 v[52:53], v[52:53], v[4:5]
	v_pk_mul_f32 v[54:55], v[54:55], v[6:7]
	v_pk_mul_f32 v[56:57], v[56:57], v[8:9]
	v_cvt_pk_bf16_f32 v10, v50, v51
	v_cvt_pk_bf16_f32 v11, v52, v53
	v_cvt_pk_bf16_f32 v12, v54, v55
	v_cvt_pk_bf16_f32 v13, v56, v57
	global_store_dwordx2 v176, v[10:11], s[10:11]
	global_store_dwordx2 v177, v[12:13], s[10:11]
	s_add_u32 s10, s10, 0x8000
	s_addc_u32 s11, s11, 0
	s_nop 0
	v_mfma_f32_32x32x16_bf16 v[50:65], v[118:121], v[114:117], 0
	v_mfma_f32_32x32x16_bf16 v[2:17], v[118:121], v[110:113], 0
	v_mfma_f32_32x32x16_bf16 v[34:49], v[118:121], v[106:109], 0
	v_mfma_f32_32x32x16_bf16 v[18:33], v[118:121], v[102:105], 0
	global_load_dwordx2 v[160:161], v176, s[6:7]
	global_load_dwordx2 v[162:163], v177, s[6:7]
	s_nop 9
	v_fmac_f32_e32 v51, v78, v50
	v_fmac_f32_e32 v35, v74, v34
	v_fmac_f32_e32 v3, v80, v50
	v_fmac_f32_e32 v19, v76, v34
	v_fma_f32 v51, -v80, v2, v51
	v_fma_f32 v35, -v76, v18, v35
	v_fmac_f32_e32 v3, v78, v2
	v_fmac_f32_e32 v19, v74, v18
	v_fmac_f32_e32 v52, v78, v51
	v_fmac_f32_e32 v36, v74, v35
	v_fmac_f32_e32 v4, v80, v51
	v_fmac_f32_e32 v20, v76, v35
	v_fma_f32 v52, -v80, v3, v52
	v_fma_f32 v36, -v76, v19, v36
	v_fmac_f32_e32 v4, v78, v3
	v_fmac_f32_e32 v20, v74, v19
	v_fmac_f32_e32 v53, v78, v52
	v_fmac_f32_e32 v37, v74, v36
	v_fmac_f32_e32 v5, v80, v52
	v_fmac_f32_e32 v21, v76, v36
	v_fma_f32 v53, -v80, v4, v53
	v_fma_f32 v37, -v76, v20, v37
	v_fmac_f32_e32 v5, v78, v4
	v_fmac_f32_e32 v21, v74, v20
	v_fmac_f32_e32 v54, v78, v53
	v_fmac_f32_e32 v38, v74, v37
	v_fmac_f32_e32 v6, v80, v53
	v_fmac_f32_e32 v22, v76, v37
	v_fma_f32 v54, -v80, v5, v54
	v_fma_f32 v38, -v76, v21, v38
	v_fmac_f32_e32 v6, v78, v5
	v_fmac_f32_e32 v22, v74, v21
	v_fmac_f32_e32 v55, v78, v54
	v_fmac_f32_e32 v39, v74, v38
	v_fmac_f32_e32 v7, v80, v54
	v_fmac_f32_e32 v23, v76, v38
	v_fma_f32 v55, -v80, v6, v55
	v_fma_f32 v39, -v76, v22, v39
	v_fmac_f32_e32 v7, v78, v6
	v_fmac_f32_e32 v23, v74, v22
	v_fmac_f32_e32 v56, v78, v55
	v_fmac_f32_e32 v40, v74, v39
	v_fmac_f32_e32 v8, v80, v55
	v_fmac_f32_e32 v24, v76, v39
	v_fma_f32 v56, -v80, v7, v56
	v_fma_f32 v40, -v76, v23, v40
	v_fmac_f32_e32 v8, v78, v7
	v_fmac_f32_e32 v24, v74, v23
	v_fmac_f32_e32 v57, v78, v56
	v_fmac_f32_e32 v41, v74, v40
	v_fmac_f32_e32 v9, v80, v56
	v_fmac_f32_e32 v25, v76, v40
	v_fma_f32 v57, -v80, v8, v57
	v_fma_f32 v41, -v76, v24, v41
	v_fmac_f32_e32 v9, v78, v8
	v_fmac_f32_e32 v25, v74, v24
	v_fmac_f32_e32 v58, v78, v57
	v_fmac_f32_e32 v42, v74, v41
	v_fmac_f32_e32 v10, v80, v57
	v_fmac_f32_e32 v26, v76, v41
	v_fma_f32 v58, -v80, v9, v58
	v_fma_f32 v42, -v76, v25, v42
	v_fmac_f32_e32 v10, v78, v9
	v_fmac_f32_e32 v26, v74, v25
	v_fmac_f32_e32 v59, v78, v58
	v_fmac_f32_e32 v43, v74, v42
	v_fmac_f32_e32 v11, v80, v58
	v_fmac_f32_e32 v27, v76, v42
	v_fma_f32 v59, -v80, v10, v59
	v_fma_f32 v43, -v76, v26, v43
	v_fmac_f32_e32 v11, v78, v10
	v_fmac_f32_e32 v27, v74, v26
	v_fmac_f32_e32 v60, v78, v59
	v_fmac_f32_e32 v44, v74, v43
	v_fmac_f32_e32 v12, v80, v59
	v_fmac_f32_e32 v28, v76, v43
	v_fma_f32 v60, -v80, v11, v60
	v_fma_f32 v44, -v76, v27, v44
	v_fmac_f32_e32 v12, v78, v11
	v_fmac_f32_e32 v28, v74, v27
	v_fmac_f32_e32 v61, v78, v60
	v_fmac_f32_e32 v45, v74, v44
	v_fmac_f32_e32 v13, v80, v60
	v_fmac_f32_e32 v29, v76, v44
	v_fma_f32 v61, -v80, v12, v61
	v_fma_f32 v45, -v76, v28, v45
	v_fmac_f32_e32 v13, v78, v12
	v_fmac_f32_e32 v29, v74, v28
	v_fmac_f32_e32 v62, v78, v61
	v_fmac_f32_e32 v46, v74, v45
	v_fmac_f32_e32 v14, v80, v61
	v_fmac_f32_e32 v30, v76, v45
	v_fma_f32 v62, -v80, v13, v62
	v_fma_f32 v46, -v76, v29, v46
	v_fmac_f32_e32 v14, v78, v13
	v_fmac_f32_e32 v30, v74, v29
	v_fmac_f32_e32 v63, v78, v62
	v_fmac_f32_e32 v47, v74, v46
	v_fmac_f32_e32 v15, v80, v62
	v_fmac_f32_e32 v31, v76, v46
	v_fma_f32 v63, -v80, v14, v63
	v_fma_f32 v47, -v76, v30, v47
	v_fmac_f32_e32 v15, v78, v14
	v_fmac_f32_e32 v31, v74, v30
	v_fmac_f32_e32 v64, v78, v63
	v_fmac_f32_e32 v48, v74, v47
	v_fmac_f32_e32 v16, v80, v63
	v_fmac_f32_e32 v32, v76, v47
	v_fma_f32 v64, -v80, v15, v64
	v_fma_f32 v48, -v76, v31, v48
	v_fmac_f32_e32 v16, v78, v15
	v_fmac_f32_e32 v32, v74, v31
	v_fmac_f32_e32 v65, v78, v64
	v_fmac_f32_e32 v49, v74, v48
	v_fmac_f32_e32 v17, v80, v64
	v_fmac_f32_e32 v33, v76, v48
	v_fma_f32 v65, -v80, v16, v65
	v_fma_f32 v49, -v76, v32, v49
	v_fmac_f32_e32 v17, v78, v16
	v_fmac_f32_e32 v33, v74, v32
	v_mov_b32_e32 v156, v65
	v_mov_b32_e32 v157, v17
	v_mov_b32_e32 v158, v65
	v_mov_b32_e32 v159, v17
	s_nop 1
	v_permlane32_swap_b32_e32 v156, v158
	v_permlane32_swap_b32_e32 v157, v159
	v_pk_fma_f32 v[164:165], v[166:167], v[152:153], v[156:157] op_sel_hi:[1,0,1]
	v_pk_fma_f32 v[164:165], v[166:167], v[152:153], v[164:165] op_sel:[1,1,0] op_sel_hi:[0,1,1] neg_lo:[0,1,0]
	v_cndmask_b32_e32 v164, v166, v164, vcc
	v_cndmask_b32_e32 v165, v167, v165, vcc
	v_mov_b32_e32 v156, v49
	v_mov_b32_e32 v157, v33
	v_mov_b32_e32 v158, v49
	v_mov_b32_e32 v159, v33
	s_nop 1
	v_permlane32_swap_b32_e32 v156, v158
	v_permlane32_swap_b32_e32 v157, v159
	v_pk_fma_f32 v[170:171], v[150:151], v[154:155], v[156:157] op_sel_hi:[1,0,1]
	v_pk_fma_f32 v[170:171], v[150:151], v[154:155], v[170:171] op_sel:[1,1,0] op_sel_hi:[0,1,1] neg_lo:[0,1,0]
	v_cndmask_b32_e32 v170, v150, v170, vcc
	v_cndmask_b32_e32 v171, v151, v171, vcc
	v_pk_mul_f32 v[168:169], v[164:165], v[70:71] op_sel:[0,1] op_sel_hi:[1,1]
	v_pk_mul_f32 v[172:173], v[170:171], v[66:67] op_sel:[0,1] op_sel_hi:[1,1]
	v_pk_fma_f32 v[168:169], v[164:165], v[72:73], v[168:169] op_sel:[1,1,0] op_sel_hi:[0,1,1] neg_lo:[0,1,0]
	v_pk_fma_f32 v[172:173], v[170:171], v[68:69], v[172:173] op_sel:[1,1,0] op_sel_hi:[0,1,1] neg_lo:[0,1,0]
	v_pk_fma_f32 v[50:51], v[78:79], v[164:165], v[50:51] op_sel_hi:[1,0,1]
	v_pk_fma_f32 v[34:35], v[74:75], v[170:171], v[34:35] op_sel_hi:[1,0,1]
	v_pk_fma_f32 v[52:53], v[70:71], v[164:165], v[52:53] op_sel_hi:[1,0,1]
	v_pk_fma_f32 v[36:37], v[66:67], v[170:171], v[36:37] op_sel_hi:[1,0,1]
	v_pk_fma_f32 v[2:3], v[80:81], v[164:165], v[2:3] op_sel_hi:[1,0,1]
	v_pk_fma_f32 v[18:19], v[76:77], v[170:171], v[18:19] op_sel_hi:[1,0,1]
	v_pk_fma_f32 v[4:5], v[72:73], v[164:165], v[4:5] op_sel_hi:[1,0,1]
	v_pk_fma_f32 v[20:21], v[68:69], v[170:171], v[20:21] op_sel_hi:[1,0,1]
	v_pk_fma_f32 v[50:51], v[80:81], v[164:165], v[50:51] op_sel:[0,1,0] op_sel_hi:[1,1,1] neg_lo:[0,1,0] neg_hi:[0,1,0]
	v_pk_fma_f32 v[34:35], v[76:77], v[170:171], v[34:35] op_sel:[0,1,0] op_sel_hi:[1,1,1] neg_lo:[0,1,0] neg_hi:[0,1,0]
	v_pk_fma_f32 v[52:53], v[72:73], v[164:165], v[52:53] op_sel:[0,1,0] op_sel_hi:[1,1,1] neg_lo:[0,1,0] neg_hi:[0,1,0]
	v_pk_fma_f32 v[36:37], v[68:69], v[170:171], v[36:37] op_sel:[0,1,0] op_sel_hi:[1,1,1] neg_lo:[0,1,0] neg_hi:[0,1,0]
	v_pk_fma_f32 v[2:3], v[78:79], v[164:165], v[2:3] op_sel:[0,1,0] op_sel_hi:[1,1,1]
	v_pk_fma_f32 v[18:19], v[74:75], v[170:171], v[18:19] op_sel:[0,1,0] op_sel_hi:[1,1,1]
	v_pk_fma_f32 v[4:5], v[70:71], v[164:165], v[4:5] op_sel:[0,1,0] op_sel_hi:[1,1,1]
	v_pk_fma_f32 v[20:21], v[66:67], v[170:171], v[20:21] op_sel:[0,1,0] op_sel_hi:[1,1,1]
	v_pk_mul_f32 v[164:165], v[168:169], v[70:71] op_sel:[0,1] op_sel_hi:[1,1]
	v_pk_mul_f32 v[170:171], v[172:173], v[66:67] op_sel:[0,1] op_sel_hi:[1,1]
	v_pk_fma_f32 v[164:165], v[168:169], v[72:73], v[164:165] op_sel:[1,1,0] op_sel_hi:[0,1,1] neg_lo:[0,1,0]
	v_pk_fma_f32 v[170:171], v[172:173], v[68:69], v[170:171] op_sel:[1,1,0] op_sel_hi:[0,1,1] neg_lo:[0,1,0]
	v_pk_fma_f32 v[54:55], v[78:79], v[168:169], v[54:55] op_sel_hi:[1,0,1]
	v_pk_fma_f32 v[38:39], v[74:75], v[172:173], v[38:39] op_sel_hi:[1,0,1]
	v_pk_fma_f32 v[56:57], v[70:71], v[168:169], v[56:57] op_sel_hi:[1,0,1]
	v_pk_fma_f32 v[40:41], v[66:67], v[172:173], v[40:41] op_sel_hi:[1,0,1]
	v_pk_fma_f32 v[6:7], v[80:81], v[168:169], v[6:7] op_sel_hi:[1,0,1]
	v_pk_fma_f32 v[22:23], v[76:77], v[172:173], v[22:23] op_sel_hi:[1,0,1]
	v_pk_fma_f32 v[8:9], v[72:73], v[168:169], v[8:9] op_sel_hi:[1,0,1]
	v_pk_fma_f32 v[24:25], v[68:69], v[172:173], v[24:25] op_sel_hi:[1,0,1]
	v_pk_fma_f32 v[54:55], v[80:81], v[168:169], v[54:55] op_sel:[0,1,0] op_sel_hi:[1,1,1] neg_lo:[0,1,0] neg_hi:[0,1,0]
	v_pk_fma_f32 v[38:39], v[76:77], v[172:173], v[38:39] op_sel:[0,1,0] op_sel_hi:[1,1,1] neg_lo:[0,1,0] neg_hi:[0,1,0]
	v_pk_fma_f32 v[56:57], v[72:73], v[168:169], v[56:57] op_sel:[0,1,0] op_sel_hi:[1,1,1] neg_lo:[0,1,0] neg_hi:[0,1,0]
	v_pk_fma_f32 v[40:41], v[68:69], v[172:173], v[40:41] op_sel:[0,1,0] op_sel_hi:[1,1,1] neg_lo:[0,1,0] neg_hi:[0,1,0]
	v_pk_fma_f32 v[6:7], v[78:79], v[168:169], v[6:7] op_sel:[0,1,0] op_sel_hi:[1,1,1]
	v_pk_fma_f32 v[22:23], v[74:75], v[172:173], v[22:23] op_sel:[0,1,0] op_sel_hi:[1,1,1]
	v_pk_fma_f32 v[8:9], v[70:71], v[168:169], v[8:9] op_sel:[0,1,0] op_sel_hi:[1,1,1]
	v_pk_fma_f32 v[24:25], v[66:67], v[172:173], v[24:25] op_sel:[0,1,0] op_sel_hi:[1,1,1]
	v_pk_mul_f32 v[168:169], v[164:165], v[70:71] op_sel:[0,1] op_sel_hi:[1,1]
	v_pk_mul_f32 v[172:173], v[170:171], v[66:67] op_sel:[0,1] op_sel_hi:[1,1]
	v_pk_fma_f32 v[168:169], v[164:165], v[72:73], v[168:169] op_sel:[1,1,0] op_sel_hi:[0,1,1] neg_lo:[0,1,0]
	v_pk_fma_f32 v[172:173], v[170:171], v[68:69], v[172:173] op_sel:[1,1,0] op_sel_hi:[0,1,1] neg_lo:[0,1,0]
	v_pk_fma_f32 v[58:59], v[78:79], v[164:165], v[58:59] op_sel_hi:[1,0,1]
	v_pk_fma_f32 v[42:43], v[74:75], v[170:171], v[42:43] op_sel_hi:[1,0,1]
	v_pk_fma_f32 v[60:61], v[70:71], v[164:165], v[60:61] op_sel_hi:[1,0,1]
	v_pk_fma_f32 v[44:45], v[66:67], v[170:171], v[44:45] op_sel_hi:[1,0,1]
	v_pk_fma_f32 v[10:11], v[80:81], v[164:165], v[10:11] op_sel_hi:[1,0,1]
	v_pk_fma_f32 v[26:27], v[76:77], v[170:171], v[26:27] op_sel_hi:[1,0,1]
	v_pk_fma_f32 v[12:13], v[72:73], v[164:165], v[12:13] op_sel_hi:[1,0,1]
	v_pk_fma_f32 v[28:29], v[68:69], v[170:171], v[28:29] op_sel_hi:[1,0,1]
	v_pk_fma_f32 v[58:59], v[80:81], v[164:165], v[58:59] op_sel:[0,1,0] op_sel_hi:[1,1,1] neg_lo:[0,1,0] neg_hi:[0,1,0]
	v_pk_fma_f32 v[42:43], v[76:77], v[170:171], v[42:43] op_sel:[0,1,0] op_sel_hi:[1,1,1] neg_lo:[0,1,0] neg_hi:[0,1,0]
	v_pk_fma_f32 v[60:61], v[72:73], v[164:165], v[60:61] op_sel:[0,1,0] op_sel_hi:[1,1,1] neg_lo:[0,1,0] neg_hi:[0,1,0]
	v_pk_fma_f32 v[44:45], v[68:69], v[170:171], v[44:45] op_sel:[0,1,0] op_sel_hi:[1,1,1] neg_lo:[0,1,0] neg_hi:[0,1,0]
	v_pk_fma_f32 v[10:11], v[78:79], v[164:165], v[10:11] op_sel:[0,1,0] op_sel_hi:[1,1,1]
	v_pk_fma_f32 v[26:27], v[74:75], v[170:171], v[26:27] op_sel:[0,1,0] op_sel_hi:[1,1,1]
	v_pk_fma_f32 v[12:13], v[70:71], v[164:165], v[12:13] op_sel:[0,1,0] op_sel_hi:[1,1,1]
	v_pk_fma_f32 v[28:29], v[66:67], v[170:171], v[28:29] op_sel:[0,1,0] op_sel_hi:[1,1,1]
	v_pk_fma_f32 v[62:63], v[78:79], v[168:169], v[62:63] op_sel_hi:[1,0,1]
	v_pk_fma_f32 v[46:47], v[74:75], v[172:173], v[46:47] op_sel_hi:[1,0,1]
	v_pk_fma_f32 v[64:65], v[70:71], v[168:169], v[64:65] op_sel_hi:[1,0,1]
	v_pk_fma_f32 v[48:49], v[66:67], v[172:173], v[48:49] op_sel_hi:[1,0,1]
	v_pk_fma_f32 v[14:15], v[80:81], v[168:169], v[14:15] op_sel_hi:[1,0,1]
	v_pk_fma_f32 v[30:31], v[76:77], v[172:173], v[30:31] op_sel_hi:[1,0,1]
	v_pk_fma_f32 v[16:17], v[72:73], v[168:169], v[16:17] op_sel_hi:[1,0,1]
	v_pk_fma_f32 v[32:33], v[68:69], v[172:173], v[32:33] op_sel_hi:[1,0,1]
	v_pk_fma_f32 v[62:63], v[80:81], v[168:169], v[62:63] op_sel:[0,1,0] op_sel_hi:[1,1,1] neg_lo:[0,1,0] neg_hi:[0,1,0]
	v_pk_fma_f32 v[46:47], v[76:77], v[172:173], v[46:47] op_sel:[0,1,0] op_sel_hi:[1,1,1] neg_lo:[0,1,0] neg_hi:[0,1,0]
	v_pk_fma_f32 v[64:65], v[72:73], v[168:169], v[64:65] op_sel:[0,1,0] op_sel_hi:[1,1,1] neg_lo:[0,1,0] neg_hi:[0,1,0]
	v_pk_fma_f32 v[48:49], v[68:69], v[172:173], v[48:49] op_sel:[0,1,0] op_sel_hi:[1,1,1] neg_lo:[0,1,0] neg_hi:[0,1,0]
	v_pk_fma_f32 v[14:15], v[78:79], v[168:169], v[14:15] op_sel:[0,1,0] op_sel_hi:[1,1,1]
	v_pk_fma_f32 v[30:31], v[74:75], v[172:173], v[30:31] op_sel:[0,1,0] op_sel_hi:[1,1,1]
	v_pk_fma_f32 v[16:17], v[70:71], v[168:169], v[16:17] op_sel:[0,1,0] op_sel_hi:[1,1,1]
	v_pk_fma_f32 v[32:33], v[66:67], v[172:173], v[32:33] op_sel:[0,1,0] op_sel_hi:[1,1,1]
	v_mov_b32_e32 v156, v65
	v_mov_b32_e32 v157, v17
	v_mov_b32_e32 v166, v65
	v_mov_b32_e32 v167, v17
	s_nop 1
	v_permlane32_swap_b32_e32 v156, v166
	v_permlane32_swap_b32_e32 v157, v167
	v_mov_b32_e32 v156, v49
	v_mov_b32_e32 v157, v33
	v_mov_b32_e32 v150, v49
	v_mov_b32_e32 v151, v33
	s_nop 1
	v_permlane32_swap_b32_e32 v156, v150
	v_permlane32_swap_b32_e32 v157, v151
	v_cvt_pk_bf16_f32 v1, v50, v2
	ds_write_b32 v174, v1
	v_cvt_pk_bf16_f32 v146, v34, v18
	ds_write_b32 v174, v146 offset:128
	v_cvt_pk_bf16_f32 v178, v51, v3
	ds_write_b32 v174, v178 offset:272
	v_cvt_pk_bf16_f32 v1, v35, v19
	ds_write_b32 v174, v1 offset:400
	v_cvt_pk_bf16_f32 v146, v52, v4
	ds_write_b32 v174, v146 offset:544
	v_cvt_pk_bf16_f32 v178, v36, v20
	ds_write_b32 v174, v178 offset:672
	v_cvt_pk_bf16_f32 v1, v53, v5
	ds_write_b32 v174, v1 offset:816
	v_cvt_pk_bf16_f32 v146, v37, v21
	ds_write_b32 v174, v146 offset:944
	v_cvt_pk_bf16_f32 v178, v54, v6
	ds_write_b32 v174, v178 offset:1088
	v_cvt_pk_bf16_f32 v1, v38, v22
	ds_write_b32 v174, v1 offset:1216
	v_cvt_pk_bf16_f32 v146, v55, v7
	ds_write_b32 v174, v146 offset:1360
	v_cvt_pk_bf16_f32 v178, v39, v23
	ds_write_b32 v174, v178 offset:1488
	v_cvt_pk_bf16_f32 v1, v56, v8
	ds_write_b32 v174, v1 offset:1632
	v_cvt_pk_bf16_f32 v146, v40, v24
	ds_write_b32 v174, v146 offset:1760
	v_cvt_pk_bf16_f32 v178, v57, v9
	ds_write_b32 v174, v178 offset:1904
	v_cvt_pk_bf16_f32 v1, v41, v25
	ds_write_b32 v174, v1 offset:2032
	v_cvt_pk_bf16_f32 v146, v58, v10
	ds_write_b32 v174, v146 offset:2176
	v_cvt_pk_bf16_f32 v178, v42, v26
	ds_write_b32 v174, v178 offset:2304
	v_cvt_pk_bf16_f32 v1, v59, v11
	ds_write_b32 v174, v1 offset:2448
	v_cvt_pk_bf16_f32 v146, v43, v27
	ds_write_b32 v174, v146 offset:2576
	v_cvt_pk_bf16_f32 v178, v60, v12
	ds_write_b32 v174, v178 offset:2720
	v_cvt_pk_bf16_f32 v1, v44, v28
	ds_write_b32 v174, v1 offset:2848
	v_cvt_pk_bf16_f32 v146, v61, v13
	ds_write_b32 v174, v146 offset:2992
	v_cvt_pk_bf16_f32 v178, v45, v29
	ds_write_b32 v174, v178 offset:3120
	v_cvt_pk_bf16_f32 v1, v62, v14
	ds_write_b32 v174, v1 offset:3264
	v_cvt_pk_bf16_f32 v146, v46, v30
	ds_write_b32 v174, v146 offset:3392
	v_cvt_pk_bf16_f32 v178, v63, v15
	ds_write_b32 v174, v178 offset:3536
	v_cvt_pk_bf16_f32 v1, v47, v31
	ds_write_b32 v174, v1 offset:3664
	v_cvt_pk_bf16_f32 v146, v64, v16
	ds_write_b32 v174, v146 offset:3808
	v_cvt_pk_bf16_f32 v178, v48, v32
	ds_write_b32 v174, v178 offset:3936
	v_cvt_pk_bf16_f32 v1, v65, v17
	ds_write_b32 v174, v1 offset:4080
	v_cvt_pk_bf16_f32 v146, v49, v33
	ds_write_b32 v174, v146 offset:4208
	s_waitcnt lgkmcnt(0)
	ds_read_b128 v[2:5], v175
	ds_read_b128 v[6:9], v175 offset:64
	ds_read_b128 v[10:13], v175 offset:128
	ds_read_b128 v[14:17], v175 offset:192
	ds_read_b128 v[18:21], v175 offset:4352
	ds_read_b128 v[22:25], v175 offset:4416
	ds_read_b128 v[26:29], v175 offset:4480
	ds_read_b128 v[30:33], v175 offset:4544
	s_waitcnt vmcnt(0)
	s_waitcnt lgkmcnt(7)
	v_mfma_f32_16x16x32_bf16 v[34:37], v[94:97], v[2:5], 0
	s_waitcnt lgkmcnt(6)
	v_mfma_f32_16x16x32_bf16 v[34:37], v[90:93], v[6:9], v[34:37]
	s_waitcnt lgkmcnt(5)
	v_mfma_f32_16x16x32_bf16 v[34:37], v[86:89], v[10:13], v[34:37]
	s_waitcnt lgkmcnt(4)
	v_mfma_f32_16x16x32_bf16 v[34:37], v[82:85], v[14:17], v[34:37]
	s_waitcnt lgkmcnt(3)
	v_mfma_f32_16x16x32_bf16 v[38:41], v[94:97], v[18:21], 0
	s_waitcnt lgkmcnt(2)
	v_mfma_f32_16x16x32_bf16 v[38:41], v[90:93], v[22:25], v[38:41]
	s_waitcnt lgkmcnt(1)
	v_mfma_f32_16x16x32_bf16 v[38:41], v[86:89], v[26:29], v[38:41]
	s_waitcnt lgkmcnt(0)
	v_mfma_f32_16x16x32_bf16 v[38:41], v[82:85], v[30:33], v[38:41]
	v_lshlrev_b32_e32 v42, 16, v160
	v_and_b32_e32 v43, 0xffff0000, v160
	v_lshlrev_b32_e32 v44, 16, v161
	v_and_b32_e32 v45, 0xffff0000, v161
	v_lshlrev_b32_e32 v46, 16, v162
	v_and_b32_e32 v47, 0xffff0000, v162
	v_lshlrev_b32_e32 v48, 16, v163
	v_and_b32_e32 v49, 0xffff0000, v163
	s_nop 1
	v_mov_b32_e32 v156, 0x3d372713
	v_mov_b32_e32 v158, 0xbfcc422a
	v_mov_b32_e32 v164, 0x3fb8aa3b
	v_mov_b32_e32 v168, 1.0
	v_pk_fma_f32 v[50:51], v[98:99], v[42:43], v[34:35]
	v_pk_fma_f32 v[52:53], v[100:101], v[44:45], v[36:37]
	v_pk_fma_f32 v[54:55], v[98:99], v[46:47], v[38:39]
	v_pk_fma_f32 v[56:57], v[100:101], v[48:49], v[40:41]
	v_pk_mul_f32 v[2:3], v[50:51], v[156:157] op_sel_hi:[1,0]
	v_pk_mul_f32 v[4:5], v[52:53], v[156:157] op_sel_hi:[1,0]
	v_pk_mul_f32 v[6:7], v[54:55], v[156:157] op_sel_hi:[1,0]
	v_pk_mul_f32 v[8:9], v[56:57], v[156:157] op_sel_hi:[1,0]
	v_pk_mul_f32 v[2:3], v[50:51], v[2:3]
	v_pk_mul_f32 v[4:5], v[52:53], v[4:5]
	v_pk_mul_f32 v[6:7], v[54:55], v[6:7]
	v_pk_mul_f32 v[8:9], v[56:57], v[8:9]
	v_pk_fma_f32 v[2:3], v[50:51], v[2:3], v[50:51]
	v_pk_fma_f32 v[4:5], v[52:53], v[4:5], v[52:53]
	v_pk_fma_f32 v[6:7], v[54:55], v[6:7], v[54:55]
	v_pk_fma_f32 v[8:9], v[56:57], v[8:9], v[56:57]
	v_pk_mul_f32 v[2:3], v[2:3], v[158:159] op_sel_hi:[1,0]
	v_pk_mul_f32 v[4:5], v[4:5], v[158:159] op_sel_hi:[1,0]
	v_pk_mul_f32 v[6:7], v[6:7], v[158:159] op_sel_hi:[1,0]
	v_pk_mul_f32 v[8:9], v[8:9], v[158:159] op_sel_hi:[1,0]
	v_pk_mul_f32 v[2:3], v[2:3], v[164:165] op_sel_hi:[1,0]
	v_pk_mul_f32 v[4:5], v[4:5], v[164:165] op_sel_hi:[1,0]
	v_pk_mul_f32 v[6:7], v[6:7], v[164:165] op_sel_hi:[1,0]
	v_pk_mul_f32 v[8:9], v[8:9], v[164:165] op_sel_hi:[1,0]
	v_exp_f32_e32 v2, v2
	v_exp_f32_e32 v3, v3
	v_exp_f32_e32 v4, v4
	v_exp_f32_e32 v5, v5
	v_exp_f32_e32 v6, v6
	v_exp_f32_e32 v7, v7
	v_exp_f32_e32 v8, v8
	v_exp_f32_e32 v9, v9
	v_pk_add_f32 v[2:3], v[2:3], v[168:169] op_sel_hi:[1,0]
	v_pk_add_f32 v[4:5], v[4:5], v[168:169] op_sel_hi:[1,0]
	v_pk_add_f32 v[6:7], v[6:7], v[168:169] op_sel_hi:[1,0]
	v_pk_add_f32 v[8:9], v[8:9], v[168:169] op_sel_hi:[1,0]
	v_rcp_f32_e32 v2, v2
	v_rcp_f32_e32 v3, v3
	v_rcp_f32_e32 v4, v4
	v_rcp_f32_e32 v5, v5
	v_rcp_f32_e32 v6, v6
	v_rcp_f32_e32 v7, v7
	v_rcp_f32_e32 v8, v8
	v_rcp_f32_e32 v9, v9
	v_pk_mul_f32 v[50:51], v[50:51], v[2:3]
	v_pk_mul_f32 v[52:53], v[52:53], v[4:5]
	v_pk_mul_f32 v[54:55], v[54:55], v[6:7]
	v_pk_mul_f32 v[56:57], v[56:57], v[8:9]
	v_cvt_pk_bf16_f32 v10, v50, v51
	v_cvt_pk_bf16_f32 v11, v52, v53
	v_cvt_pk_bf16_f32 v12, v54, v55
	v_cvt_pk_bf16_f32 v13, v56, v57
	global_store_dwordx2 v176, v[10:11], s[10:11]
	global_store_dwordx2 v177, v[12:13], s[10:11]
	v_readlane_b32 s4, v252, 61
	v_readlane_b32 s5, v252, 62
	v_cmp_gt_u32_e32 vcc, 32, v148
	v_and_b32_e32 v146, 31, v148
	v_mov_b32_e32 v3, v166
	v_mov_b32_e32 v2, v167
	v_mov_b32_e32 v4, v150
	v_mov_b32_e32 v5, v151
	v_lshlrev_b32_e32 v146, 2, v146
	s_and_b64 s[4:5], s[4:5], vcc
	s_cmp_eq_u32 s70, 31
	s_cselect_b64 s[0:1], -1, 0
	s_and_b64 s[4:5], s[0:1], s[4:5]
	s_and_saveexec_b64 s[0:1], s[4:5]
	s_cbranch_execz .LBB0_1057
	s_lshl_b32 s2, s64, 11
	s_or_b32 s4, s30, s2
	s_ashr_i32 s5, s4, 31
	s_lshl_b64 s[4:5], s[4:5], 2
	v_readlane_b32 s8, v252, 4
	v_readlane_b32 s9, v252, 5
	s_add_u32 s4, s8, s4
	s_addc_u32 s5, s9, s5
	v_lshl_add_u64 v[6:7], s[4:5], 0, v[146:147]
	v_add_co_u32_e32 v8, vcc, 0x8400000, v6
	v_readlane_b32 s10, v252, 6
	s_nop 0
	v_addc_co_u32_e32 v9, vcc, 0, v7, vcc
	v_add_co_u32_e32 v6, vcc, 0x8404000, v6
	v_readlane_b32 s11, v252, 7
	s_nop 0
	v_addc_co_u32_e32 v7, vcc, 0, v7, vcc
	global_store_dword v[8:9], v3, off
	global_store_dword v[6:7], v2, off
	global_store_dword v[8:9], v4, off offset:128
	global_store_dword v[6:7], v5, off offset:128
	s_branch .LBB0_1057
